# all 16-byte global stores write-through (sc1): less dirty L2 data for the barrier's release write-back
# speedup vs baseline: 1.0026x; 1.0026x over previous
.LBB0_84:
	v_ashrrev_i32_e32 v17, 31, v16
	v_lshlrev_b64 v[18:19], 12, v[16:17]
	v_lshl_add_u64 v[58:59], v[32:33], 0, v[18:19]
	global_load_dwordx4 v[42:45], v[58:59], off offset:1024
	global_load_dwordx4 v[46:49], v[58:59], off
	global_load_dwordx4 v[50:53], v[58:59], off offset:3072
	global_load_dwordx4 v[54:57], v[58:59], off offset:2048
	v_add_u32_e32 v34, s9, v16
	v_cmp_gt_i32_e32 vcc, s73, v34
	s_waitcnt vmcnt(3)
	v_mov_b32_e32 v62, v43
	v_cndmask_b32_e32 v16, v16, v34, vcc
	v_ashrrev_i32_e32 v17, 31, v16
	v_lshlrev_b64 v[16:17], 12, v[16:17]
	v_lshl_add_u64 v[16:17], v[32:33], 0, v[16:17]
	global_load_dwordx4 v[28:31], v[16:17], off
	global_load_dwordx4 v[24:27], v[16:17], off offset:1024
	global_load_dwordx4 v[20:23], v[16:17], off offset:2048
	s_nop 0
	global_load_dwordx4 v[16:19], v[16:17], off offset:3072
	s_waitcnt vmcnt(6)
	v_mov_b32_e32 v63, v47
	v_mov_b32_e32 v60, v42
	v_mov_b32_e32 v61, v46
	s_waitcnt vmcnt(5)
	v_mov_b32_e32 v70, v51
	s_waitcnt vmcnt(4)
	v_mov_b32_e32 v71, v55
	v_pk_mul_f32 v[62:63], v[62:63], v[62:63]
	v_mov_b32_e32 v64, v44
	v_mov_b32_e32 v65, v48
	v_mov_b32_e32 v68, v50
	v_mov_b32_e32 v69, v54
	v_pk_mul_f32 v[70:71], v[70:71], v[70:71]
	v_pk_fma_f32 v[60:61], v[60:61], v[60:61], v[62:63]
	v_mov_b32_e32 v66, v45
	v_mov_b32_e32 v67, v49
	v_mov_b32_e32 v72, v52
	v_mov_b32_e32 v73, v56
	v_pk_fma_f32 v[62:63], v[68:69], v[68:69], v[70:71]
	v_pk_fma_f32 v[60:61], v[64:65], v[64:65], v[60:61]
	v_mov_b32_e32 v74, v53
	v_mov_b32_e32 v75, v57
	v_pk_fma_f32 v[62:63], v[72:73], v[72:73], v[62:63]
	v_pk_fma_f32 v[60:61], v[66:67], v[66:67], v[60:61]
	v_pk_fma_f32 v[62:63], v[74:75], v[74:75], v[62:63]
	v_add_f32_e32 v35, v60, v61
	v_add_f32_e32 v35, v63, v35
	v_add_f32_e32 v35, v62, v35
	s_waitcnt lgkmcnt(0)
	s_nop 1
	v_add_f32_dpp v35, v35, v35 quad_perm:[1,0,3,2] row_mask:0xf bank_mask:0xf
	s_waitcnt lgkmcnt(0)
	s_nop 1
	v_add_f32_dpp v35, v35, v35 quad_perm:[2,3,0,1] row_mask:0xf bank_mask:0xf
	s_waitcnt lgkmcnt(0)
	s_nop 1
	v_add_f32_dpp v35, v35, v35 row_half_mirror row_mask:0xf bank_mask:0xf
	s_waitcnt lgkmcnt(0)
	s_nop 1
	v_add_f32_dpp v35, v35, v35 row_mirror row_mask:0xf bank_mask:0xf
	s_waitcnt lgkmcnt(0)
	v_mov_b32_e32 v60, v35
	s_nop 1
	v_permlane16_swap_b32_e32 v35, v60
	v_add_f32_e32 v35, v35, v60
	s_waitcnt lgkmcnt(0)
	v_mov_b32_e32 v60, v35
	s_nop 1
	v_permlane32_swap_b32_e32 v35, v60
	v_add_f32_e32 v35, v35, v60
	v_fmamk_f32 v35, v35, 0x3a800000, v158
	v_mul_f32_e32 v60, 0x4b800000, v35
	v_cmp_gt_f32_e64 s[38:39], s82, v35
	s_nop 1
	v_cndmask_b32_e64 v35, v35, v60, s[38:39]
	v_rsq_f32_e32 v35, v35
	s_nop 0
	v_mul_f32_e32 v60, 0x45800000, v35
	v_cndmask_b32_e64 v60, v35, v60, s[38:39]
	v_pk_mul_f32 v[46:47], v[46:47], v[60:61] op_sel_hi:[1,0]
	v_pk_mul_f32 v[48:49], v[48:49], v[60:61] op_sel_hi:[1,0]
	v_pk_mul_f32 v[62:63], v[42:43], v[60:61] op_sel_hi:[1,0]
	v_pk_mul_f32 v[64:65], v[44:45], v[60:61] op_sel_hi:[1,0]
	v_pk_mul_f32 v[54:55], v[54:55], v[60:61] op_sel_hi:[1,0]
	v_pk_mul_f32 v[56:57], v[56:57], v[60:61] op_sel_hi:[1,0]
	v_pk_mul_f32 v[66:67], v[50:51], v[60:61] op_sel_hi:[1,0]
	v_pk_mul_f32 v[60:61], v[52:53], v[60:61] op_sel_hi:[1,0]
	v_pk_mul_f32 v[44:45], v[2:3], v[48:49]
	v_pk_mul_f32 v[42:43], v[0:1], v[46:47]
	v_pk_mul_f32 v[48:49], v[6:7], v[64:65]
	v_pk_mul_f32 v[46:47], v[4:5], v[62:63]
	v_pk_mul_f32 v[52:53], v[10:11], v[56:57]
	v_pk_mul_f32 v[50:51], v[8:9], v[54:55]
	v_pk_mul_f32 v[56:57], v[14:15], v[60:61]
	v_pk_mul_f32 v[54:55], v[12:13], v[66:67]
	global_store_dwordx4 v[58:59], v[42:45], off sc1
	global_store_dwordx4 v[58:59], v[46:49], off offset:1024 sc1
	global_store_dwordx4 v[58:59], v[50:53], off offset:2048 sc1
	global_store_dwordx4 v[58:59], v[54:57], off offset:3072 sc1
	s_and_saveexec_b64 s[2:3], vcc
	s_cbranch_execz .LBB0_83
	s_waitcnt vmcnt(7)
	v_mov_b32_e32 v44, v29
	s_waitcnt vmcnt(6)
	v_mov_b32_e32 v45, v25
	v_mov_b32_e32 v42, v28
	v_mov_b32_e32 v43, v24
	v_pk_mul_f32 v[44:45], v[44:45], v[44:45]
	s_waitcnt vmcnt(5)
	v_mov_b32_e32 v46, v21
	v_pk_fma_f32 v[42:43], v[42:43], v[42:43], v[44:45]
	v_mov_b32_e32 v44, v30
	v_mov_b32_e32 v45, v26
	v_pk_fma_f32 v[42:43], v[44:45], v[44:45], v[42:43]
	v_mov_b32_e32 v44, v31
	v_mov_b32_e32 v45, v27
	s_waitcnt vmcnt(4)
	v_mov_b32_e32 v47, v17
	v_pk_fma_f32 v[42:43], v[44:45], v[44:45], v[42:43]
	v_mov_b32_e32 v44, v20
	v_mov_b32_e32 v45, v16
	v_pk_mul_f32 v[46:47], v[46:47], v[46:47]
	v_add_f32_e32 v35, v42, v43
	v_pk_fma_f32 v[44:45], v[44:45], v[44:45], v[46:47]
	v_mov_b32_e32 v46, v22
	v_mov_b32_e32 v47, v18
	v_pk_fma_f32 v[44:45], v[46:47], v[46:47], v[44:45]
	v_mov_b32_e32 v46, v23
	v_mov_b32_e32 v47, v19
	v_pk_fma_f32 v[44:45], v[46:47], v[46:47], v[44:45]
	s_nop 0
	v_add_f32_e32 v35, v35, v44
	v_add_f32_e32 v35, v35, v45
	s_waitcnt lgkmcnt(0)
	s_nop 1
	v_add_f32_dpp v35, v35, v35 quad_perm:[1,0,3,2] row_mask:0xf bank_mask:0xf
	s_waitcnt lgkmcnt(0)
	s_nop 1
	v_add_f32_dpp v35, v35, v35 quad_perm:[2,3,0,1] row_mask:0xf bank_mask:0xf
	s_waitcnt lgkmcnt(0)
	s_nop 1
	v_add_f32_dpp v35, v35, v35 row_half_mirror row_mask:0xf bank_mask:0xf
	s_waitcnt lgkmcnt(0)
	s_nop 1
	v_add_f32_dpp v35, v35, v35 row_mirror row_mask:0xf bank_mask:0xf
	s_waitcnt lgkmcnt(0)
	v_mov_b32_e32 v42, v35
	s_nop 1
	v_permlane16_swap_b32_e32 v35, v42
	v_add_f32_e32 v35, v35, v42
	s_waitcnt lgkmcnt(0)
	v_mov_b32_e32 v42, v35
	s_nop 1
	v_permlane32_swap_b32_e32 v35, v42
	v_add_f32_e32 v35, v35, v42
	v_fmamk_f32 v35, v35, 0x3a800000, v158
	v_mul_f32_e32 v42, 0x4b800000, v35
	v_cmp_gt_f32_e32 vcc, s82, v35
	s_nop 1
	v_cndmask_b32_e32 v35, v35, v42, vcc
	v_rsq_f32_e32 v44, v35
	v_ashrrev_i32_e32 v35, 31, v34
	v_lshlrev_b64 v[42:43], 12, v[34:35]
	v_lshl_add_u64 v[42:43], v[32:33], 0, v[42:43]
	v_mul_f32_e32 v35, 0x45800000, v44
	v_cndmask_b32_e32 v44, v44, v35, vcc
	v_pk_mul_f32 v[28:29], v[28:29], v[44:45] op_sel_hi:[1,0]
	v_pk_mul_f32 v[30:31], v[30:31], v[44:45] op_sel_hi:[1,0]
	v_pk_mul_f32 v[46:47], v[24:25], v[44:45] op_sel_hi:[1,0]
	v_pk_mul_f32 v[48:49], v[26:27], v[44:45] op_sel_hi:[1,0]
	v_pk_mul_f32 v[26:27], v[2:3], v[30:31]
	v_pk_mul_f32 v[24:25], v[0:1], v[28:29]
	v_pk_mul_f32 v[20:21], v[20:21], v[44:45] op_sel_hi:[1,0]
	v_pk_mul_f32 v[22:23], v[22:23], v[44:45] op_sel_hi:[1,0]
	v_pk_mul_f32 v[16:17], v[16:17], v[44:45] op_sel_hi:[1,0]
	v_pk_mul_f32 v[18:19], v[18:19], v[44:45] op_sel_hi:[1,0]
	global_store_dwordx4 v[42:43], v[24:27], off sc1
	v_pk_mul_f32 v[22:23], v[10:11], v[22:23]
	v_pk_mul_f32 v[20:21], v[8:9], v[20:21]
	v_pk_mul_f32 v[26:27], v[6:7], v[48:49]
	v_pk_mul_f32 v[24:25], v[4:5], v[46:47]
	v_pk_mul_f32 v[18:19], v[14:15], v[18:19]
	v_pk_mul_f32 v[16:17], v[12:13], v[16:17]
	global_store_dwordx4 v[42:43], v[24:27], off offset:1024 sc1
	global_store_dwordx4 v[42:43], v[20:23], off offset:2048 sc1
	global_store_dwordx4 v[42:43], v[16:19], off offset:3072 sc1
	s_branch .LBB0_83

.LBB0_126:
	s_or_b64 exec, exec, s[2:3]
	s_waitcnt vmcnt(23)
	v_pk_add_f32 v[118:119], v[74:75], v[116:117]
	v_pk_add_f32 v[116:117], v[72:73], v[114:115]
	s_waitcnt vmcnt(20)
	v_pk_add_f32 v[114:115], v[90:91], v[140:141]
	v_pk_add_f32 v[112:113], v[88:89], v[112:113]
	s_waitcnt vmcnt(17)
	v_pk_add_f32 v[90:91], v[94:95], v[150:151]
	v_pk_add_f32 v[88:89], v[92:93], v[148:149]
	s_waitcnt vmcnt(14)
	v_pk_add_f32 v[74:75], v[102:103], v[162:163]
	v_pk_add_f32 v[72:73], v[100:101], v[146:147]
	s_and_saveexec_b64 s[2:3], s[38:39]
	s_cbranch_execz .LBB0_128
	v_lshl_add_u64 v[92:93], v[126:127], 0, v[136:137]
	global_store_dwordx4 v[92:93], v[116:119], off sc1
	global_store_dwordx4 v[92:93], v[112:115], off offset:1024 sc1
	global_store_dwordx4 v[92:93], v[88:91], off offset:2048 sc1
	global_store_dwordx4 v[92:93], v[72:75], off offset:3072 sc1
.LBB0_128:
	s_or_b64 exec, exec, s[2:3]
	v_mul_f32_e32 v92, v117, v117
	v_mul_f32_e32 v93, v113, v113
	v_fmac_f32_e32 v92, v116, v116
	v_fmac_f32_e32 v93, v112, v112
	v_fmac_f32_e32 v92, v118, v118
	v_fmac_f32_e32 v93, v114, v114
	v_fmac_f32_e32 v92, v119, v119
	v_fmac_f32_e32 v93, v115, v115
	v_add_f32_e32 v92, v92, v93
	v_mul_f32_e32 v93, v89, v89
	v_fmac_f32_e32 v93, v88, v88
	v_fmac_f32_e32 v93, v90, v90
	v_fmac_f32_e32 v93, v91, v91
	v_add_f32_e32 v92, v92, v93
	v_mul_f32_e32 v93, v73, v73
	v_fmac_f32_e32 v93, v72, v72
	v_fmac_f32_e32 v93, v74, v74
	v_fmac_f32_e32 v93, v75, v75
	v_add_f32_e32 v92, v92, v93
	v_pk_add_f32 v[20:21], v[20:21], 1.0 op_sel_hi:[1,0]
	v_pk_add_f32 v[22:23], v[22:23], 1.0 op_sel_hi:[1,0]
	s_waitcnt lgkmcnt(0)
	s_nop 1
	v_add_f32_dpp v92, v92, v92 quad_perm:[1,0,3,2] row_mask:0xf bank_mask:0xf
	s_waitcnt lgkmcnt(0)
	s_nop 1
	v_add_f32_dpp v92, v92, v92 quad_perm:[2,3,0,1] row_mask:0xf bank_mask:0xf
	s_waitcnt lgkmcnt(0)
	s_nop 1
	v_add_f32_dpp v92, v92, v92 row_half_mirror row_mask:0xf bank_mask:0xf
	s_waitcnt lgkmcnt(0)
	s_nop 1
	v_add_f32_dpp v92, v92, v92 row_mirror row_mask:0xf bank_mask:0xf
	s_waitcnt lgkmcnt(0)
	v_mov_b32_e32 v93, v92
	s_nop 1
	v_permlane16_swap_b32_e32 v92, v93
	v_add_f32_e32 v92, v92, v93
	s_waitcnt lgkmcnt(0)
	v_mov_b32_e32 v93, v92
	s_nop 1
	v_permlane32_swap_b32_e32 v92, v93
	v_add_f32_e32 v92, v92, v93
	v_fmamk_f32 v92, v92, 0x3a800000, v158
	v_cmp_gt_f32_e32 vcc, s82, v92
	v_mul_f32_e32 v93, 0x4b800000, v92
	s_nop 0
	v_cndmask_b32_e32 v92, v92, v93, vcc
	v_rsq_f32_e32 v92, v92
	s_nop 0
	v_mul_f32_e32 v93, 0x45800000, v92
	v_cndmask_b32_e32 v92, v92, v93, vcc
	v_pk_mul_f32 v[100:101], v[116:117], v[92:93] op_sel_hi:[1,0]
	v_pk_mul_f32 v[94:95], v[118:119], v[92:93] op_sel_hi:[1,0]
	v_pk_mul_f32 v[100:101], v[0:1], v[100:101]
	v_pk_mul_f32 v[94:95], v[2:3], v[94:95]
	v_pk_fma_f32 v[20:21], v[20:21], v[100:101], v[24:25]
	v_pk_fma_f32 v[22:23], v[22:23], v[94:95], v[26:27]
	v_cvt_pk_bf16_f32 v20, v20, v21
	v_pk_add_f32 v[24:25], v[30:31], 1.0 op_sel_hi:[1,0]
	v_cvt_pk_bf16_f32 v21, v22, v23
	global_store_dwordx2 v[132:133], v[20:21], off offset:-1024
	v_pk_mul_f32 v[20:21], v[114:115], v[92:93] op_sel_hi:[1,0]
	v_pk_mul_f32 v[22:23], v[112:113], v[92:93] op_sel_hi:[1,0]
	v_pk_mul_f32 v[20:21], v[6:7], v[20:21]
	v_pk_mul_f32 v[22:23], v[4:5], v[22:23]
	v_pk_add_f32 v[26:27], v[28:29], 1.0 op_sel_hi:[1,0]
	v_pk_fma_f32 v[18:19], v[24:25], v[20:21], v[18:19]
	v_pk_fma_f32 v[16:17], v[26:27], v[22:23], v[16:17]
	v_pk_add_f32 v[22:23], v[44:45], 1.0 op_sel_hi:[1,0]
	v_cvt_pk_bf16_f32 v16, v16, v17
	v_cvt_pk_bf16_f32 v17, v18, v19
	v_pk_mul_f32 v[18:19], v[88:89], v[92:93] op_sel_hi:[1,0]
	global_store_dwordx2 v[132:133], v[16:17], off offset:-512
	v_pk_mul_f32 v[16:17], v[90:91], v[92:93] op_sel_hi:[1,0]
	v_pk_mul_f32 v[18:19], v[8:9], v[18:19]
	v_pk_mul_f32 v[16:17], v[10:11], v[16:17]
	v_pk_add_f32 v[20:21], v[46:47], 1.0 op_sel_hi:[1,0]
	v_pk_fma_f32 v[18:19], v[22:23], v[18:19], v[36:37]
	v_pk_fma_f32 v[16:17], v[20:21], v[16:17], v[38:39]
	v_cvt_pk_bf16_f32 v18, v18, v19
	s_waitcnt vmcnt(15)
	v_pk_add_f32 v[22:23], v[68:69], 1.0 op_sel_hi:[1,0]
	v_cvt_pk_bf16_f32 v19, v16, v17
	global_store_dwordx2 v[132:133], v[18:19], off
	v_pk_mul_f32 v[18:19], v[72:73], v[92:93] op_sel_hi:[1,0]
	v_pk_mul_f32 v[16:17], v[74:75], v[92:93] op_sel_hi:[1,0]
	v_pk_mul_f32 v[18:19], v[12:13], v[18:19]
	v_pk_mul_f32 v[16:17], v[14:15], v[16:17]
	v_pk_add_f32 v[20:21], v[70:71], 1.0 op_sel_hi:[1,0]
	s_waitcnt vmcnt(15)
	v_pk_fma_f32 v[18:19], v[22:23], v[18:19], v[64:65]
	v_pk_fma_f32 v[16:17], v[20:21], v[16:17], v[66:67]
	v_cvt_pk_bf16_f32 v18, v18, v19
	s_nop 0
	v_cvt_pk_bf16_f32 v19, v16, v17
	global_store_dwordx2 v[132:133], v[18:19], off offset:512
	s_and_saveexec_b64 s[6:7], s[40:41]
	s_cbranch_execz .LBB0_101
	s_waitcnt vmcnt(15)
	v_pk_add_f32 v[30:31], v[86:87], v[144:145]
	v_pk_add_f32 v[28:29], v[84:85], v[142:143]
	s_waitcnt vmcnt(12)
	v_pk_add_f32 v[26:27], v[98:99], v[152:153]
	v_pk_add_f32 v[24:25], v[96:97], v[138:139]
	s_waitcnt vmcnt(9)
	v_pk_add_f32 v[22:23], v[106:107], v[166:167]
	v_pk_add_f32 v[20:21], v[104:105], v[164:165]
	s_waitcnt vmcnt(6)
	v_pk_add_f32 v[18:19], v[110:111], v[168:169]
	v_pk_add_f32 v[16:17], v[108:109], v[154:155]
	v_cmp_lt_i32_e32 vcc, s90, v134
	s_and_saveexec_b64 s[2:3], vcc
	s_cbranch_execz .LBB0_100
	v_add_u32_e32 v156, 0xffff8000, v134
	v_lshlrev_b64 v[36:37], 12, v[156:157]
	v_lshl_add_u64 v[36:37], v[126:127], 0, v[36:37]
	global_store_dwordx4 v[36:37], v[28:31], off sc1
	global_store_dwordx4 v[36:37], v[24:27], off offset:1024 sc1
	global_store_dwordx4 v[36:37], v[20:23], off offset:2048 sc1
	global_store_dwordx4 v[36:37], v[16:19], off offset:3072 sc1
	s_branch .LBB0_100

.Lpost_286:
	s_and_b64 s[2:3], s[36:37], exec
	s_mov_b32 s2, 0x125e0000
	s_cselect_b32 s2, s2, 0x135e0000
	s_add_u32 s2, s26, s2
	s_addc_u32 s3, s27, 0
	s_ashr_i32 s6, s35, 31
	v_mov_b32_e32 v129, s6
	s_lshl_b32 s6, s44, 2
	s_add_u32 s2, s2, s6
	v_or_b32_e32 v128, s35, v131
	s_addc_u32 s3, s3, 0
	v_mov_b32_e32 v131, v157
	v_lshl_add_u64 v[130:131], s[2:3], 0, v[130:131]
	s_lshl_b64 s[2:3], s[40:41], 21
	s_lshl_b64 s[6:7], s[38:39], 18
	v_lshl_add_u64 v[130:131], v[130:131], 0, s[2:3]
	v_lshlrev_b64 v[128:129], 10, v[128:129]
	v_lshl_add_u64 v[130:131], v[130:131], 0, s[6:7]
	v_lshl_add_u64 v[128:129], v[130:131], 0, v[128:129]
	s_movk_i32 s2, 0x4000
	global_store_dwordx4 v[128:129], v[124:127], off sc1
	global_store_dwordx4 v[128:129], v[120:123], off offset:64 sc1
	global_store_dwordx4 v[128:129], v[104:107], off offset:512 sc1
	global_store_dwordx4 v[128:129], v[96:99], off offset:576 sc1
	s_cmpk_lt_u32 s9, 0x100
	s_nop 0
	v_add_co_u32_e32 v96, vcc, s2, v128
	s_mov_b32 s2, 0xc000
	s_nop 0
	v_addc_co_u32_e32 v97, vcc, 0, v129, vcc
	global_store_dwordx4 v[96:97], v[116:119], off sc1
	global_store_dwordx4 v[96:97], v[112:115], off offset:64 sc1
	global_store_dwordx4 v[96:97], v[88:91], off offset:512 sc1
	global_store_dwordx4 v[96:97], v[80:83], off offset:576 sc1
	s_nop 1
	v_add_co_u32_e32 v80, vcc, s73, v128
	s_nop 1
	v_addc_co_u32_e32 v81, vcc, 0, v129, vcc
	global_store_dwordx4 v[80:81], v[108:111], off sc1
	global_store_dwordx4 v[80:81], v[100:103], off offset:64 sc1
	global_store_dwordx4 v[80:81], v[76:79], off offset:512 sc1
	global_store_dwordx4 v[80:81], v[72:75], off offset:576 sc1
	s_nop 1
	v_add_co_u32_e32 v72, vcc, s2, v128
	s_mov_b32 s2, 0x20000
	s_nop 0
	v_addc_co_u32_e32 v73, vcc, 0, v129, vcc
	global_store_dwordx4 v[72:73], v[92:95], off sc1
	global_store_dwordx4 v[72:73], v[84:87], off offset:64 sc1
	global_store_dwordx4 v[72:73], v[68:71], off offset:512 sc1
	global_store_dwordx4 v[72:73], v[64:67], off offset:576 sc1
	s_nop 1
	v_add_co_u32_e32 v64, vcc, s2, v128
	s_mov_b32 s2, 0x24000
	s_nop 0
	v_addc_co_u32_e32 v65, vcc, 0, v129, vcc
	global_store_dwordx4 v[64:65], v[60:63], off sc1
	global_store_dwordx4 v[64:65], v[56:59], off offset:64 sc1
	global_store_dwordx4 v[64:65], v[44:47], off offset:512 sc1
	global_store_dwordx4 v[64:65], v[36:39], off offset:576 sc1
	s_nop 1
	v_add_co_u32_e32 v36, vcc, s2, v128
	s_mov_b32 s2, 0x28000
	s_nop 0
	v_addc_co_u32_e32 v37, vcc, 0, v129, vcc
	global_store_dwordx4 v[36:37], v[52:55], off sc1
	global_store_dwordx4 v[36:37], v[48:51], off offset:64 sc1
	global_store_dwordx4 v[36:37], v[28:31], off offset:512 sc1
	global_store_dwordx4 v[36:37], v[20:23], off offset:576 sc1
	s_nop 1
	v_add_co_u32_e32 v20, vcc, s2, v128
	s_nop 1
	v_addc_co_u32_e32 v21, vcc, 0, v129, vcc
	global_store_dwordx4 v[20:21], v[40:43], off sc1
	global_store_dwordx4 v[20:21], v[32:35], off offset:64 sc1
	global_store_dwordx4 v[20:21], v[12:15], off offset:512 sc1
	global_store_dwordx4 v[20:21], v[8:11], off offset:576 sc1
	s_nop 1
	v_add_co_u32_e32 v8, vcc, 0x2c000, v128
	s_nop 1
	v_addc_co_u32_e32 v9, vcc, 0, v129, vcc
	global_store_dwordx4 v[8:9], v[24:27], off sc1
	global_store_dwordx4 v[8:9], v[16:19], off offset:64 sc1
	global_store_dwordx4 v[8:9], v[4:7], off offset:512 sc1
	global_store_dwordx4 v[8:9], v[0:3], off offset:576 sc1
	s_waitcnt vmcnt(0)
	s_cbranch_scc0 .LBB0_289
	s_barrier

.LBB0_314:
	s_waitcnt lgkmcnt(0)
	v_lshl_add_u64 v[0:1], s[26:27], 0, v[68:69]
	v_add_co_u32_e32 v2, vcc, 0x9660000, v0
	v_lshl_add_u64 v[12:13], s[26:27], 0, v[70:71]
	s_nop 0
	v_addc_co_u32_e32 v3, vcc, 0, v1, vcc
	v_add_co_u32_e32 v0, vcc, 0x9662000, v0
	global_load_dwordx4 v[44:47], v[2:3], off
	s_nop 0
	v_addc_co_u32_e32 v1, vcc, 0, v1, vcc
	v_add_co_u32_e32 v8, vcc, 0x9661000, v12
	global_load_dwordx4 v[48:51], v[0:1], off
	s_nop 0
	v_addc_co_u32_e32 v9, vcc, 0, v13, vcc
	s_mov_b64 s[2:3], 0x9661ff0
	v_add_co_u32_e32 v14, vcc, 0x9663000, v12
	v_lshl_add_u64 v[4:5], v[12:13], 0, s[2:3]
	global_load_dwordx4 v[52:55], v[8:9], off offset:4080
	global_load_dword v86, v[4:5], off offset:16
	s_mov_b64 s[2:3], 0x9663ff0
	v_addc_co_u32_e32 v15, vcc, 0, v13, vcc
	v_lshl_add_u64 v[4:5], v[12:13], 0, s[2:3]
	global_load_dwordx4 v[60:63], v[14:15], off offset:4080
	global_load_dword v87, v[4:5], off offset:16
	global_load_dwordx4 v[36:39], v[2:3], off offset:1024
	global_load_dwordx4 v[32:35], v[0:1], off offset:1024
	s_mov_b64 s[2:3], 0x9661bf0
	v_lshl_add_u64 v[4:5], v[12:13], 0, s[2:3]
	global_load_dwordx4 v[40:43], v[8:9], off offset:3056
	global_load_dword v83, v[4:5], off offset:16
	s_mov_b64 s[2:3], 0x9663bf0
	v_lshl_add_u64 v[4:5], v[12:13], 0, s[2:3]
	global_load_dwordx4 v[56:59], v[14:15], off offset:3056
	global_load_dword v88, v[4:5], off offset:16
	global_load_dwordx4 v[20:23], v[2:3], off offset:2048
	global_load_dwordx4 v[16:19], v[0:1], off offset:2048
	s_mov_b64 s[2:3], 0x96617f0
	v_lshl_add_u64 v[4:5], v[12:13], 0, s[2:3]
	global_load_dwordx4 v[24:27], v[8:9], off offset:2032
	global_load_dword v80, v[4:5], off offset:16
	s_mov_b64 s[2:3], 0x96637f0
	v_lshl_add_u64 v[4:5], v[12:13], 0, s[2:3]
	global_load_dwordx4 v[28:31], v[14:15], off offset:2032
	global_load_dword v82, v[4:5], off offset:16
	s_nop 0
	global_load_dwordx4 v[4:7], v[2:3], off offset:3072
	s_nop 0
	global_load_dwordx4 v[0:3], v[0:1], off offset:3072
	s_mov_b64 s[2:3], 0x96613f0
	v_lshl_add_u64 v[84:85], v[12:13], 0, s[2:3]
	global_load_dwordx4 v[8:11], v[8:9], off offset:1008
	s_nop 0
	global_load_dword v67, v[84:85], off offset:16
	s_mov_b64 s[2:3], 0x96633f0
	v_lshl_add_u64 v[84:85], v[12:13], 0, s[2:3]
	global_load_dwordx4 v[12:15], v[14:15], off offset:1008
	s_nop 0
	global_load_dword v81, v[84:85], off offset:16
	s_mov_b32 s2, 0x115e0000
	s_waitcnt vmcnt(23)
	v_lshlrev_b32_e32 v84, 16, v44
	v_and_b32_e32 v89, 0xffff0000, v44
	s_waitcnt vmcnt(22)
	v_lshlrev_b32_e32 v85, 16, v48
	v_and_b32_e32 v91, 0xffff0000, v48
	v_lshlrev_b32_e32 v93, 16, v49
	s_waitcnt vmcnt(20)
	v_lshlrev_b32_e32 v86, 16, v86
	v_cndmask_b32_e64 v86, v86, 0, s[38:39]
	s_waitcnt vmcnt(19)
	v_and_b32_e32 v90, 0xffff0000, v63
	s_waitcnt vmcnt(18)
	v_lshlrev_b32_e32 v87, 16, v87
	v_cndmask_b32_e64 v87, v87, v85, s[38:39]
	v_sub_f32_e32 v85, v85, v87
	v_and_b32_e32 v87, 0xffff0000, v55
	v_add_f32_e32 v84, v86, v84
	v_add_f32_e32 v87, v87, v89
	v_sub_f32_e32 v89, v91, v90
	v_lshlrev_b32_e32 v90, 16, v45
	v_lshlrev_b32_e32 v91, 16, v55
	v_lshlrev_b32_e32 v92, 16, v63
	v_pk_mov_b32 v[44:45], v[44:45], v[54:55] op_sel:[1,0]
	v_add_f32_e32 v86, 0, v84
	v_add_f32_e32 v90, v91, v90
	v_sub_f32_e32 v91, v93, v92
	v_and_b32_e32 v55, 0xffff0000, v45
	v_and_b32_e32 v92, 0xffff0000, v44
	v_pk_mov_b32 v[44:45], v[48:49], v[62:63] op_sel:[1,0]
	v_sub_f32_e32 v86, v86, v87
	v_and_b32_e32 v45, 0xffff0000, v45
	v_and_b32_e32 v44, 0xffff0000, v44
	v_add_f32_e32 v86, v90, v86
	v_add_f32_e32 v48, v55, v92
	v_sub_f32_e32 v55, v44, v45
	v_lshlrev_b32_e32 v45, 16, v46
	v_lshlrev_b32_e32 v49, 16, v54
	v_lshlrev_b32_e32 v54, 16, v62
	v_lshlrev_b32_e32 v62, 16, v50
	v_sub_f32_e32 v44, v86, v48
	v_add_f32_e32 v49, v49, v45
	v_sub_f32_e32 v54, v62, v54
	v_and_b32_e32 v45, 0xffff0000, v53
	v_and_b32_e32 v62, 0xffff0000, v46
	v_and_b32_e32 v63, 0xffff0000, v61
	v_and_b32_e32 v86, 0xffff0000, v50
	v_add_f32_e32 v44, v49, v44
	v_add_f32_e32 v62, v45, v62
	v_sub_f32_e32 v63, v86, v63
	v_lshlrev_b32_e32 v45, 16, v47
	v_lshlrev_b32_e32 v86, 16, v53
	v_sub_f32_e32 v44, v44, v62
	v_lshlrev_b32_e32 v92, 16, v61
	v_lshlrev_b32_e32 v93, 16, v51
	v_add_f32_e32 v86, v86, v45
	v_sub_f32_e32 v92, v93, v92
	v_add_f32_e32 v93, v86, v44
	v_pk_mov_b32 v[44:45], v[46:47], v[52:53] op_sel:[1,0]
	s_nop 0
	v_and_b32_e32 v46, 0xffff0000, v45
	v_and_b32_e32 v47, 0xffff0000, v44
	v_pk_mov_b32 v[44:45], v[50:51], v[60:61] op_sel:[1,0]
	v_add_f32_e32 v50, v46, v47
	v_and_b32_e32 v45, 0xffff0000, v45
	v_and_b32_e32 v44, 0xffff0000, v44
	v_sub_f32_e32 v44, v44, v45
	v_sub_f32_e32 v60, v93, v50
	v_cvt_pk_bf16_f32 v46, v84, v87
	v_cvt_pk_bf16_f32 v47, v90, v48
	v_cvt_pk_bf16_f32 v48, v49, v62
	v_cvt_pk_bf16_f32 v49, v86, v50
	v_cvt_pk_bf16_f32 v50, v85, v89
	v_cvt_pk_bf16_f32 v51, v91, v55
	v_cvt_pk_bf16_f32 v52, v54, v63
	v_lshl_add_u64 v[54:55], s[26:27], 0, v[64:65]
	v_cvt_pk_bf16_f32 v53, v92, v44
	v_add_co_u32_e32 v44, vcc, s2, v54
	s_mov_b32 s2, 0x11de0000
	s_nop 0
	v_addc_co_u32_e32 v45, vcc, 0, v55, vcc
	global_store_dwordx4 v[44:45], v[46:49], off sc1
	s_nop 1
	v_add_co_u32_e32 v46, vcc, s2, v54
	s_waitcnt vmcnt(17)
	v_lshlrev_b32_e32 v48, 16, v32
	v_addc_co_u32_e32 v47, vcc, 0, v55, vcc
	global_store_dwordx4 v[46:47], v[50:53], off sc1
	s_waitcnt vmcnt(14)
	v_lshlrev_b32_e32 v49, 16, v88
	v_and_b32_e32 v54, 0xffff0000, v32
	v_lshlrev_b32_e32 v50, 16, v36
	v_lshlrev_b32_e32 v51, 16, v83
	v_add_f32_e32 v50, v51, v50
	v_and_b32_e32 v51, 0xffff0000, v43
	v_and_b32_e32 v52, 0xffff0000, v36
	v_and_b32_e32 v53, 0xffff0000, v59
	v_sub_f32_e32 v48, v48, v49
	v_add_f32_e32 v49, v50, v60
	v_add_f32_e32 v51, v51, v52
	v_sub_f32_e32 v52, v54, v53
	v_lshlrev_b32_e32 v53, 16, v37
	v_lshlrev_b32_e32 v54, 16, v43
	v_pk_mov_b32 v[36:37], v[36:37], v[42:43] op_sel:[1,0]
	v_sub_f32_e32 v49, v49, v51
	v_lshlrev_b32_e32 v60, 16, v33
	v_add_f32_e32 v53, v54, v53
	v_and_b32_e32 v37, 0xffff0000, v37
	v_and_b32_e32 v36, 0xffff0000, v36
	v_pk_mov_b32 v[32:33], v[32:33], v[58:59] op_sel:[1,0]
	v_add_f32_e32 v49, v53, v49
	v_and_b32_e32 v33, 0xffff0000, v33
	v_and_b32_e32 v32, 0xffff0000, v32
	v_add_f32_e32 v36, v37, v36
	v_lshlrev_b32_e32 v55, 16, v59
	v_sub_f32_e32 v37, v32, v33
	v_sub_f32_e32 v32, v49, v36
	v_lshlrev_b32_e32 v33, 16, v38
	v_lshlrev_b32_e32 v42, 16, v42
	v_lshlrev_b32_e32 v43, 16, v58
	v_lshlrev_b32_e32 v49, 16, v34
	v_sub_f32_e32 v54, v60, v55
	v_add_f32_e32 v42, v42, v33
	v_sub_f32_e32 v43, v49, v43
	v_and_b32_e32 v33, 0xffff0000, v41
	v_and_b32_e32 v49, 0xffff0000, v38
	v_and_b32_e32 v55, 0xffff0000, v57
	v_and_b32_e32 v58, 0xffff0000, v34
	v_add_f32_e32 v32, v42, v32
	v_add_f32_e32 v49, v33, v49
	v_sub_f32_e32 v55, v58, v55
	v_lshlrev_b32_e32 v33, 16, v39
	v_lshlrev_b32_e32 v58, 16, v41
	v_sub_f32_e32 v32, v32, v49
	v_lshlrev_b32_e32 v59, 16, v57
	v_lshlrev_b32_e32 v60, 16, v35
	v_add_f32_e32 v58, v58, v33
	v_sub_f32_e32 v59, v60, v59
	v_add_f32_e32 v60, v58, v32
	v_pk_mov_b32 v[32:33], v[38:39], v[40:41] op_sel:[1,0]
	s_nop 0
	v_and_b32_e32 v38, 0xffff0000, v33
	v_and_b32_e32 v39, 0xffff0000, v32
	v_pk_mov_b32 v[32:33], v[34:35], v[56:57] op_sel:[1,0]
	v_add_f32_e32 v35, v38, v39
	v_and_b32_e32 v33, 0xffff0000, v33
	v_and_b32_e32 v32, 0xffff0000, v32
	v_sub_f32_e32 v39, v32, v33
	v_sub_f32_e32 v40, v60, v35
	v_cvt_pk_bf16_f32 v32, v50, v51
	v_cvt_pk_bf16_f32 v33, v53, v36
	v_cvt_pk_bf16_f32 v34, v42, v49
	v_cvt_pk_bf16_f32 v35, v58, v35
	v_cvt_pk_bf16_f32 v36, v48, v52
	v_cvt_pk_bf16_f32 v37, v54, v37
	v_cvt_pk_bf16_f32 v38, v43, v55
	v_cvt_pk_bf16_f32 v39, v59, v39
	global_store_dwordx4 v[44:45], v[32:35], off offset:1024 sc1
	global_store_dwordx4 v[46:47], v[36:39], off offset:1024 sc1
	s_waitcnt vmcnt(15)
	v_lshlrev_b32_e32 v34, 16, v20
	s_waitcnt vmcnt(12)
	v_lshlrev_b32_e32 v35, 16, v80
	v_lshlrev_b32_e32 v32, 16, v16
	s_waitcnt vmcnt(10)
	v_lshlrev_b32_e32 v33, 16, v82
	v_add_f32_e32 v34, v35, v34
	v_and_b32_e32 v35, 0xffff0000, v27
	v_and_b32_e32 v36, 0xffff0000, v20
	v_and_b32_e32 v37, 0xffff0000, v31
	v_and_b32_e32 v38, 0xffff0000, v16
	v_sub_f32_e32 v32, v32, v33
	v_add_f32_e32 v33, v34, v40
	v_add_f32_e32 v35, v35, v36
	v_sub_f32_e32 v36, v38, v37
	v_lshlrev_b32_e32 v37, 16, v21
	v_lshlrev_b32_e32 v38, 16, v27
	v_lshlrev_b32_e32 v40, 16, v17
	v_pk_mov_b32 v[20:21], v[20:21], v[26:27] op_sel:[1,0]
	v_pk_mov_b32 v[16:17], v[16:17], v[30:31] op_sel:[1,0]
	v_sub_f32_e32 v33, v33, v35
	v_add_f32_e32 v37, v38, v37
	v_and_b32_e32 v21, 0xffff0000, v21
	v_and_b32_e32 v20, 0xffff0000, v20
	v_and_b32_e32 v17, 0xffff0000, v17
	v_and_b32_e32 v16, 0xffff0000, v16
	v_add_f32_e32 v33, v37, v33
	v_add_f32_e32 v20, v21, v20
	v_sub_f32_e32 v21, v16, v17
	v_lshlrev_b32_e32 v17, 16, v22
	v_lshlrev_b32_e32 v26, 16, v26
	v_lshlrev_b32_e32 v27, 16, v30
	v_lshlrev_b32_e32 v30, 16, v18
	v_lshlrev_b32_e32 v39, 16, v31
	v_sub_f32_e32 v16, v33, v20
	v_add_f32_e32 v26, v26, v17
	v_sub_f32_e32 v27, v30, v27
	v_and_b32_e32 v17, 0xffff0000, v25
	v_and_b32_e32 v30, 0xffff0000, v22
	v_and_b32_e32 v31, 0xffff0000, v29
	v_and_b32_e32 v33, 0xffff0000, v18
	v_add_f32_e32 v16, v26, v16
	v_add_f32_e32 v30, v17, v30
	v_sub_f32_e32 v31, v33, v31
	v_lshlrev_b32_e32 v17, 16, v23
	v_lshlrev_b32_e32 v33, 16, v25
	v_sub_f32_e32 v38, v40, v39
	v_sub_f32_e32 v16, v16, v30
	v_lshlrev_b32_e32 v39, 16, v29
	v_lshlrev_b32_e32 v40, 16, v19
	v_add_f32_e32 v33, v33, v17
	v_sub_f32_e32 v39, v40, v39
	v_add_f32_e32 v40, v33, v16
	v_pk_mov_b32 v[16:17], v[22:23], v[24:25] op_sel:[1,0]
	s_nop 0
	v_and_b32_e32 v22, 0xffff0000, v17
	v_and_b32_e32 v23, 0xffff0000, v16
	v_pk_mov_b32 v[16:17], v[18:19], v[28:29] op_sel:[1,0]
	v_add_f32_e32 v19, v22, v23
	v_and_b32_e32 v17, 0xffff0000, v17
	v_and_b32_e32 v16, 0xffff0000, v16
	v_sub_f32_e32 v23, v16, v17
	v_sub_f32_e32 v24, v40, v19
	v_cvt_pk_bf16_f32 v16, v34, v35
	v_cvt_pk_bf16_f32 v17, v37, v20
	v_cvt_pk_bf16_f32 v18, v26, v30
	v_cvt_pk_bf16_f32 v19, v33, v19
	v_cvt_pk_bf16_f32 v20, v32, v36
	v_cvt_pk_bf16_f32 v21, v38, v21
	v_cvt_pk_bf16_f32 v22, v27, v31
	v_cvt_pk_bf16_f32 v23, v39, v23
	global_store_dwordx4 v[44:45], v[16:19], off offset:2048 sc1
	global_store_dwordx4 v[46:47], v[20:23], off offset:2048 sc1
	s_waitcnt vmcnt(11)
	v_lshlrev_b32_e32 v18, 16, v4
	s_waitcnt vmcnt(8)
	v_lshlrev_b32_e32 v19, 16, v67
	v_lshlrev_b32_e32 v16, 16, v0
	s_waitcnt vmcnt(6)
	v_lshlrev_b32_e32 v17, 16, v81
	v_add_f32_e32 v18, v19, v18
	v_and_b32_e32 v19, 0xffff0000, v11
	v_and_b32_e32 v20, 0xffff0000, v4
	v_and_b32_e32 v21, 0xffff0000, v15
	v_and_b32_e32 v22, 0xffff0000, v0
	v_sub_f32_e32 v16, v16, v17
	v_add_f32_e32 v17, v18, v24
	v_add_f32_e32 v19, v19, v20
	v_sub_f32_e32 v20, v22, v21
	v_lshlrev_b32_e32 v21, 16, v5
	v_lshlrev_b32_e32 v22, 16, v11
	v_lshlrev_b32_e32 v24, 16, v1
	v_pk_mov_b32 v[4:5], v[4:5], v[10:11] op_sel:[1,0]
	v_pk_mov_b32 v[0:1], v[0:1], v[14:15] op_sel:[1,0]
	v_sub_f32_e32 v17, v17, v19
	v_add_f32_e32 v21, v22, v21
	v_and_b32_e32 v5, 0xffff0000, v5
	v_and_b32_e32 v4, 0xffff0000, v4
	v_and_b32_e32 v1, 0xffff0000, v1
	v_and_b32_e32 v0, 0xffff0000, v0
	v_add_f32_e32 v17, v21, v17
	v_add_f32_e32 v4, v5, v4
	v_sub_f32_e32 v5, v0, v1
	v_lshlrev_b32_e32 v1, 16, v6
	v_lshlrev_b32_e32 v10, 16, v10
	v_lshlrev_b32_e32 v11, 16, v14
	v_lshlrev_b32_e32 v14, 16, v2
	v_lshlrev_b32_e32 v23, 16, v15
	v_sub_f32_e32 v0, v17, v4
	v_add_f32_e32 v10, v10, v1
	v_sub_f32_e32 v11, v14, v11
	v_and_b32_e32 v1, 0xffff0000, v9
	v_and_b32_e32 v14, 0xffff0000, v6
	v_and_b32_e32 v15, 0xffff0000, v13
	v_and_b32_e32 v17, 0xffff0000, v2
	v_add_f32_e32 v0, v10, v0
	v_add_f32_e32 v14, v1, v14
	v_sub_f32_e32 v15, v17, v15
	v_lshlrev_b32_e32 v1, 16, v7
	v_lshlrev_b32_e32 v17, 16, v9
	v_sub_f32_e32 v22, v24, v23
	v_sub_f32_e32 v0, v0, v14
	v_lshlrev_b32_e32 v23, 16, v13
	v_lshlrev_b32_e32 v24, 16, v3
	v_add_f32_e32 v17, v17, v1
	v_sub_f32_e32 v23, v24, v23
	v_add_f32_e32 v24, v17, v0
	v_pk_mov_b32 v[0:1], v[6:7], v[8:9] op_sel:[1,0]
	s_nop 0
	v_and_b32_e32 v6, 0xffff0000, v1
	v_and_b32_e32 v7, 0xffff0000, v0
	v_pk_mov_b32 v[0:1], v[2:3], v[12:13] op_sel:[1,0]
	v_add_f32_e32 v3, v6, v7
	v_and_b32_e32 v1, 0xffff0000, v1
	v_and_b32_e32 v0, 0xffff0000, v0
	v_sub_f32_e32 v7, v0, v1
	v_sub_f32_e32 v8, v24, v3
	v_cvt_pk_bf16_f32 v0, v18, v19
	v_cvt_pk_bf16_f32 v1, v21, v4
	v_cvt_pk_bf16_f32 v2, v10, v14
	v_cvt_pk_bf16_f32 v3, v17, v3
	v_cvt_pk_bf16_f32 v4, v16, v20
	v_cvt_pk_bf16_f32 v5, v22, v5
	v_cvt_pk_bf16_f32 v6, v11, v15
	v_cvt_pk_bf16_f32 v7, v23, v7
	global_store_dwordx4 v[44:45], v[0:3], off offset:3072 sc1
	global_store_dwordx4 v[46:47], v[4:7], off offset:3072 sc1
	ds_bpermute_b32 v0, v74, v8
	s_waitcnt lgkmcnt(0)
	v_add_f32_e32 v0, v8, v0
	ds_bpermute_b32 v1, v75, v0
	s_waitcnt lgkmcnt(0)
	v_add_f32_e32 v0, v0, v1
	ds_bpermute_b32 v1, v76, v0
	s_waitcnt lgkmcnt(0)
	v_add_f32_e32 v0, v0, v1
	ds_bpermute_b32 v1, v77, v0
	s_waitcnt lgkmcnt(0)
	v_add_f32_e32 v0, v0, v1
	ds_bpermute_b32 v1, v78, v0
	s_waitcnt lgkmcnt(0)
	v_add_f32_e32 v0, v0, v1
	ds_bpermute_b32 v1, v79, v0
	s_and_saveexec_b64 s[2:3], s[38:39]
	s_cbranch_execz .LBB0_313
	v_lshl_add_u64 v[2:3], s[26:27], 0, v[72:73]
	global_load_ushort v4, v[2:3], off
	v_ashrrev_i32_e32 v67, 31, v66
	s_waitcnt lgkmcnt(0)
	v_add_f32_e32 v0, v0, v1
	v_lshl_add_u64 v[2:3], v[66:67], 2, s[42:43]
	s_waitcnt vmcnt(0)
	v_lshlrev_b32_e32 v5, 16, v4
	v_add_f32_e32 v4, v0, v5
	global_store_dwordx2 v[2:3], v[4:5], off
	s_branch .LBB0_313

.Linp_fast:
	v_lshl_add_u32 v156, s10, 8, v142
	v_add_u32_e32 v138, s25, v140
	v_and_b32_e32 v162, 16, v197
	v_lshrrev_b32_e32 v162, 4, v162
	v_mul_u32_u24_e32 v162, 40, v162
	v_sub_u32_e32 v162, 32, v162
	v_lshl_add_u32 v164, v156, 1, v162
	v_mov_b32_e32 v165, 0
	v_mov_b64_e32 v[136:137], s[30:31]
	v_mad_i64_i32 v[182:183], s[2:3], v138, s73, v[136:137]
	v_lshl_add_u64 v[182:183], v[182:183], 0, v[164:165]
	v_cvt_pk_bf16_f32 v166, v120, v121
	v_cvt_pk_bf16_f32 v167, v122, v123
	v_cvt_pk_bf16_f32 v168, v124, v125
	v_cvt_pk_bf16_f32 v169, v126, v127
	s_nop 1
	v_permlane16_swap_b32_e32 v166, v168
	v_permlane16_swap_b32_e32 v167, v169
	global_store_dwordx4 v[182:183], v[166:169], off sc1
	v_cvt_pk_bf16_f32 v170, v112, v113
	v_cvt_pk_bf16_f32 v171, v114, v115
	v_cvt_pk_bf16_f32 v172, v116, v117
	v_cvt_pk_bf16_f32 v173, v118, v119
	s_nop 1
	v_permlane16_swap_b32_e32 v170, v172
	v_permlane16_swap_b32_e32 v171, v173
	global_store_dwordx4 v[182:183], v[170:173], off offset:256 sc1
	v_or_b32_e32 v163, 16, v138
	v_mad_i64_i32 v[184:185], s[2:3], v163, s73, v[136:137]
	v_lshl_add_u64 v[184:185], v[184:185], 0, v[164:165]
	v_cvt_pk_bf16_f32 v174, v104, v105
	v_cvt_pk_bf16_f32 v175, v106, v107
	v_cvt_pk_bf16_f32 v176, v108, v109
	v_cvt_pk_bf16_f32 v177, v110, v111
	s_nop 1
	v_permlane16_swap_b32_e32 v174, v176
	v_permlane16_swap_b32_e32 v175, v177
	global_store_dwordx4 v[184:185], v[174:177], off sc1
	v_cvt_pk_bf16_f32 v178, v96, v97
	v_cvt_pk_bf16_f32 v179, v98, v99
	v_cvt_pk_bf16_f32 v180, v100, v101
	v_cvt_pk_bf16_f32 v181, v102, v103
	s_nop 1
	v_permlane16_swap_b32_e32 v178, v180
	v_permlane16_swap_b32_e32 v179, v181
	global_store_dwordx4 v[184:185], v[178:181], off offset:256 sc1
	v_or_b32_e32 v163, 32, v138
	v_mad_i64_i32 v[186:187], s[2:3], v163, s73, v[136:137]
	v_lshl_add_u64 v[186:187], v[186:187], 0, v[164:165]
	v_cvt_pk_bf16_f32 v166, v88, v89
	v_cvt_pk_bf16_f32 v167, v90, v91
	v_cvt_pk_bf16_f32 v168, v92, v93
	v_cvt_pk_bf16_f32 v169, v94, v95
	s_nop 1
	v_permlane16_swap_b32_e32 v166, v168
	v_permlane16_swap_b32_e32 v167, v169
	global_store_dwordx4 v[186:187], v[166:169], off sc1
	v_cvt_pk_bf16_f32 v170, v80, v81
	v_cvt_pk_bf16_f32 v171, v82, v83
	v_cvt_pk_bf16_f32 v172, v84, v85
	v_cvt_pk_bf16_f32 v173, v86, v87
	s_nop 1
	v_permlane16_swap_b32_e32 v170, v172
	v_permlane16_swap_b32_e32 v171, v173
	global_store_dwordx4 v[186:187], v[170:173], off offset:256 sc1
	v_or_b32_e32 v163, 48, v138
	v_mad_i64_i32 v[188:189], s[2:3], v163, s73, v[136:137]
	v_lshl_add_u64 v[188:189], v[188:189], 0, v[164:165]
	v_cvt_pk_bf16_f32 v174, v72, v73
	v_cvt_pk_bf16_f32 v175, v74, v75
	v_cvt_pk_bf16_f32 v176, v76, v77
	v_cvt_pk_bf16_f32 v177, v78, v79
	s_nop 1
	v_permlane16_swap_b32_e32 v174, v176
	v_permlane16_swap_b32_e32 v175, v177
	global_store_dwordx4 v[188:189], v[174:177], off sc1
	v_cvt_pk_bf16_f32 v178, v64, v65
	v_cvt_pk_bf16_f32 v179, v66, v67
	v_cvt_pk_bf16_f32 v180, v68, v69
	v_cvt_pk_bf16_f32 v181, v70, v71
	s_nop 1
	v_permlane16_swap_b32_e32 v178, v180
	v_permlane16_swap_b32_e32 v179, v181
	global_store_dwordx4 v[188:189], v[178:181], off offset:256 sc1
	v_add_u32_e32 v163, 0x80, v138
	v_mad_i64_i32 v[182:183], s[2:3], v163, s73, v[136:137]
	v_lshl_add_u64 v[182:183], v[182:183], 0, v[164:165]
	v_cvt_pk_bf16_f32 v166, v56, v57
	v_cvt_pk_bf16_f32 v167, v58, v59
	v_cvt_pk_bf16_f32 v168, v60, v61
	v_cvt_pk_bf16_f32 v169, v62, v63
	s_nop 1
	v_permlane16_swap_b32_e32 v166, v168
	v_permlane16_swap_b32_e32 v167, v169
	global_store_dwordx4 v[182:183], v[166:169], off sc1
	v_cvt_pk_bf16_f32 v170, v48, v49
	v_cvt_pk_bf16_f32 v171, v50, v51
	v_cvt_pk_bf16_f32 v172, v52, v53
	v_cvt_pk_bf16_f32 v173, v54, v55
	s_nop 1
	v_permlane16_swap_b32_e32 v170, v172
	v_permlane16_swap_b32_e32 v171, v173
	global_store_dwordx4 v[182:183], v[170:173], off offset:256 sc1
	v_add_u32_e32 v163, 0x90, v138
	v_mad_i64_i32 v[184:185], s[2:3], v163, s73, v[136:137]
	v_lshl_add_u64 v[184:185], v[184:185], 0, v[164:165]
	v_cvt_pk_bf16_f32 v174, v40, v41
	v_cvt_pk_bf16_f32 v175, v42, v43
	v_cvt_pk_bf16_f32 v176, v44, v45
	v_cvt_pk_bf16_f32 v177, v46, v47
	s_nop 1
	v_permlane16_swap_b32_e32 v174, v176
	v_permlane16_swap_b32_e32 v175, v177
	global_store_dwordx4 v[184:185], v[174:177], off sc1
	v_cvt_pk_bf16_f32 v178, v32, v33
	v_cvt_pk_bf16_f32 v179, v34, v35
	v_cvt_pk_bf16_f32 v180, v36, v37
	v_cvt_pk_bf16_f32 v181, v38, v39
	s_nop 1
	v_permlane16_swap_b32_e32 v178, v180
	v_permlane16_swap_b32_e32 v179, v181
	global_store_dwordx4 v[184:185], v[178:181], off offset:256 sc1
	v_add_u32_e32 v163, 0xa0, v138
	v_mad_i64_i32 v[186:187], s[2:3], v163, s73, v[136:137]
	v_lshl_add_u64 v[186:187], v[186:187], 0, v[164:165]
	v_cvt_pk_bf16_f32 v166, v24, v25
	v_cvt_pk_bf16_f32 v167, v26, v27
	v_cvt_pk_bf16_f32 v168, v28, v29
	v_cvt_pk_bf16_f32 v169, v30, v31
	s_nop 1
	v_permlane16_swap_b32_e32 v166, v168
	v_permlane16_swap_b32_e32 v167, v169
	global_store_dwordx4 v[186:187], v[166:169], off sc1
	v_cvt_pk_bf16_f32 v170, v16, v17
	v_cvt_pk_bf16_f32 v171, v18, v19
	v_cvt_pk_bf16_f32 v172, v20, v21
	v_cvt_pk_bf16_f32 v173, v22, v23
	s_nop 1
	v_permlane16_swap_b32_e32 v170, v172
	v_permlane16_swap_b32_e32 v171, v173
	global_store_dwordx4 v[186:187], v[170:173], off offset:256 sc1
	v_add_u32_e32 v163, 0xb0, v138
	v_mad_i64_i32 v[188:189], s[2:3], v163, s73, v[136:137]
	v_lshl_add_u64 v[188:189], v[188:189], 0, v[164:165]
	v_cvt_pk_bf16_f32 v174, v8, v9
	v_cvt_pk_bf16_f32 v175, v10, v11
	v_cvt_pk_bf16_f32 v176, v12, v13
	v_cvt_pk_bf16_f32 v177, v14, v15
	s_nop 1
	v_permlane16_swap_b32_e32 v174, v176
	v_permlane16_swap_b32_e32 v175, v177
	global_store_dwordx4 v[188:189], v[174:177], off sc1
	v_cvt_pk_bf16_f32 v178, v0, v1
	v_cvt_pk_bf16_f32 v179, v2, v3
	v_cvt_pk_bf16_f32 v180, v4, v5
	v_cvt_pk_bf16_f32 v181, v6, v7
	s_nop 1
	v_permlane16_swap_b32_e32 v178, v180
	v_permlane16_swap_b32_e32 v179, v181
	global_store_dwordx4 v[188:189], v[178:181], off offset:256 sc1
	s_branch .LBB0_324

.LBB0_468:
	s_or_b64 exec, exec, s[2:3]
	v_mul_f32_e32 v92, v117, v117
	v_mul_f32_e32 v93, v113, v113
	v_fmac_f32_e32 v92, v116, v116
	v_fmac_f32_e32 v93, v112, v112
	v_fmac_f32_e32 v92, v118, v118
	v_fmac_f32_e32 v93, v114, v114
	v_fmac_f32_e32 v92, v119, v119
	v_fmac_f32_e32 v93, v115, v115
	v_add_f32_e32 v92, v92, v93
	v_mul_f32_e32 v93, v89, v89
	v_fmac_f32_e32 v93, v88, v88
	v_fmac_f32_e32 v93, v90, v90
	v_fmac_f32_e32 v93, v91, v91
	v_add_f32_e32 v92, v92, v93
	v_mul_f32_e32 v93, v73, v73
	v_fmac_f32_e32 v93, v72, v72
	v_fmac_f32_e32 v93, v74, v74
	v_fmac_f32_e32 v93, v75, v75
	v_add_f32_e32 v92, v92, v93
	v_pk_add_f32 v[20:21], v[20:21], 1.0 op_sel_hi:[1,0]
	v_pk_add_f32 v[22:23], v[22:23], 1.0 op_sel_hi:[1,0]
	s_waitcnt lgkmcnt(0)
	s_nop 1
	v_add_f32_dpp v92, v92, v92 quad_perm:[1,0,3,2] row_mask:0xf bank_mask:0xf
	s_waitcnt lgkmcnt(0)
	s_nop 1
	v_add_f32_dpp v92, v92, v92 quad_perm:[2,3,0,1] row_mask:0xf bank_mask:0xf
	s_waitcnt lgkmcnt(0)
	s_nop 1
	v_add_f32_dpp v92, v92, v92 row_half_mirror row_mask:0xf bank_mask:0xf
	s_waitcnt lgkmcnt(0)
	s_nop 1
	v_add_f32_dpp v92, v92, v92 row_mirror row_mask:0xf bank_mask:0xf
	s_waitcnt lgkmcnt(0)
	v_mov_b32_e32 v93, v92
	s_nop 1
	v_permlane16_swap_b32_e32 v92, v93
	v_add_f32_e32 v92, v92, v93
	s_waitcnt lgkmcnt(0)
	v_mov_b32_e32 v93, v92
	s_nop 1
	v_permlane32_swap_b32_e32 v92, v93
	v_add_f32_e32 v92, v92, v93
	v_fmamk_f32 v92, v92, 0x3a800000, v158
	v_cmp_gt_f32_e32 vcc, s82, v92
	v_mul_f32_e32 v93, 0x4b800000, v92
	s_nop 0
	v_cndmask_b32_e32 v92, v92, v93, vcc
	v_rsq_f32_e32 v92, v92
	s_nop 0
	v_mul_f32_e32 v93, 0x45800000, v92
	v_cndmask_b32_e32 v92, v92, v93, vcc
	v_pk_mul_f32 v[100:101], v[116:117], v[92:93] op_sel_hi:[1,0]
	v_pk_mul_f32 v[94:95], v[118:119], v[92:93] op_sel_hi:[1,0]
	v_pk_mul_f32 v[100:101], v[0:1], v[100:101]
	v_pk_mul_f32 v[94:95], v[2:3], v[94:95]
	v_pk_fma_f32 v[20:21], v[20:21], v[100:101], v[24:25]
	v_pk_fma_f32 v[22:23], v[22:23], v[94:95], v[26:27]
	v_cvt_pk_bf16_f32 v20, v20, v21
	v_pk_add_f32 v[24:25], v[30:31], 1.0 op_sel_hi:[1,0]
	v_cvt_pk_bf16_f32 v21, v22, v23
	global_store_dwordx2 v[132:133], v[20:21], off offset:-1024
	v_pk_mul_f32 v[20:21], v[114:115], v[92:93] op_sel_hi:[1,0]
	v_pk_mul_f32 v[22:23], v[112:113], v[92:93] op_sel_hi:[1,0]
	v_pk_mul_f32 v[20:21], v[6:7], v[20:21]
	v_pk_mul_f32 v[22:23], v[4:5], v[22:23]
	v_pk_add_f32 v[26:27], v[28:29], 1.0 op_sel_hi:[1,0]
	v_pk_fma_f32 v[18:19], v[24:25], v[20:21], v[18:19]
	v_pk_fma_f32 v[16:17], v[26:27], v[22:23], v[16:17]
	v_pk_add_f32 v[22:23], v[44:45], 1.0 op_sel_hi:[1,0]
	v_cvt_pk_bf16_f32 v16, v16, v17
	v_cvt_pk_bf16_f32 v17, v18, v19
	v_pk_mul_f32 v[18:19], v[88:89], v[92:93] op_sel_hi:[1,0]
	global_store_dwordx2 v[132:133], v[16:17], off offset:-512
	v_pk_mul_f32 v[16:17], v[90:91], v[92:93] op_sel_hi:[1,0]
	v_pk_mul_f32 v[18:19], v[8:9], v[18:19]
	v_pk_mul_f32 v[16:17], v[10:11], v[16:17]
	v_pk_add_f32 v[20:21], v[46:47], 1.0 op_sel_hi:[1,0]
	v_pk_fma_f32 v[18:19], v[22:23], v[18:19], v[40:41]
	v_pk_fma_f32 v[16:17], v[20:21], v[16:17], v[42:43]
	v_cvt_pk_bf16_f32 v18, v18, v19
	s_waitcnt vmcnt(15)
	v_pk_add_f32 v[22:23], v[68:69], 1.0 op_sel_hi:[1,0]
	v_cvt_pk_bf16_f32 v19, v16, v17
	global_store_dwordx2 v[132:133], v[18:19], off
	v_pk_mul_f32 v[18:19], v[72:73], v[92:93] op_sel_hi:[1,0]
	v_pk_mul_f32 v[16:17], v[74:75], v[92:93] op_sel_hi:[1,0]
	v_pk_mul_f32 v[18:19], v[12:13], v[18:19]
	v_pk_mul_f32 v[16:17], v[14:15], v[16:17]
	v_pk_add_f32 v[20:21], v[70:71], 1.0 op_sel_hi:[1,0]
	s_waitcnt vmcnt(15)
	v_pk_fma_f32 v[18:19], v[22:23], v[18:19], v[64:65]
	v_pk_fma_f32 v[16:17], v[20:21], v[16:17], v[66:67]
	v_cvt_pk_bf16_f32 v18, v18, v19
	s_nop 0
	v_cvt_pk_bf16_f32 v19, v16, v17
	global_store_dwordx2 v[132:133], v[18:19], off offset:512
	s_and_saveexec_b64 s[6:7], s[40:41]
	s_cbranch_execz .LBB0_441
	s_waitcnt vmcnt(15)
	v_pk_add_f32 v[30:31], v[86:87], v[144:145]
	v_pk_add_f32 v[28:29], v[84:85], v[142:143]
	s_waitcnt vmcnt(12)
	v_pk_add_f32 v[26:27], v[98:99], v[152:153]
	v_pk_add_f32 v[24:25], v[96:97], v[138:139]
	s_waitcnt vmcnt(9)
	v_pk_add_f32 v[22:23], v[106:107], v[166:167]
	v_pk_add_f32 v[20:21], v[104:105], v[164:165]
	s_waitcnt vmcnt(6)
	v_pk_add_f32 v[18:19], v[110:111], v[168:169]
	v_pk_add_f32 v[16:17], v[108:109], v[154:155]
	v_cmp_lt_i32_e32 vcc, s90, v134
	s_and_saveexec_b64 s[2:3], vcc
	s_cbranch_execz .LBB0_440
	v_add_u32_e32 v156, 0xffff8000, v134
	v_lshlrev_b64 v[40:41], 12, v[156:157]
	v_lshl_add_u64 v[40:41], v[126:127], 0, v[40:41]
	global_store_dwordx4 v[40:41], v[28:31], off sc1
	global_store_dwordx4 v[40:41], v[24:27], off offset:1024 sc1
	global_store_dwordx4 v[40:41], v[20:23], off offset:2048 sc1
	global_store_dwordx4 v[40:41], v[16:19], off offset:3072 sc1
	s_branch .LBB0_440

.LBB0_497:
	v_lshl_add_u64 v[0:1], v[170:171], 2, s[82:83]
	v_add_co_u32_e32 v0, vcc, 0xb0000, v0
	s_mov_b32 s85, s25
	s_nop 0
	v_addc_co_u32_e32 v1, vcc, 0, v1, vcc
	s_and_b64 vcc, exec, s[78:79]
	s_mov_b32 s24, s73
	s_mov_b32 s10, s92
	s_mov_b32 s84, s93
	s_mov_b64 s[6:7], s[38:39]
	s_mov_b64 s[60:61], s[80:81]
	s_mov_b32 s82, 0x800000
	s_movk_i32 s83, 0x24af
	global_store_dwordx4 v[0:1], v[128:131], off offset:576 sc1
	s_cbranch_vccnz .LBB0_519

.Lpost_514:
	s_min_i32 s2, s85, 0x80
	s_ashr_i32 s2, s2, 4
	s_lshl_b32 s84, s85, 8
	s_mul_hi_i32 s3, s2, 0x9000
	s_mul_i32 s2, s2, 0x9000
	s_add_u32 s2, s42, s2
	v_lshl_or_b32 v144, s24, 8, v213
	s_addc_u32 s3, s43, s3
	v_ashrrev_i32_e32 v145, 31, v144
	v_lshl_add_u64 v[140:141], v[144:145], 2, s[2:3]
	global_load_dwordx4 v[128:131], v[140:141], off
	global_load_dwordx4 v[132:135], v[140:141], off offset:64
	global_load_dwordx4 v[136:139], v[140:141], off offset:512
	s_nop 0
	global_load_dwordx4 v[140:143], v[140:141], off offset:576
	v_lshl_add_u64 v[170:171], v[164:165], 0, v[144:145]
	s_cmpk_lt_i32 s85, 0x80
	s_mov_b64 s[2:3], -1
	s_waitcnt vmcnt(0)
	v_pk_mul_f32 v[184:185], s[68:69], v[130:131]
	v_pk_mul_f32 v[186:187], s[46:47], v[128:129]
	v_pk_mul_f32 v[180:181], s[68:69], v[134:135]
	v_pk_mul_f32 v[182:183], s[46:47], v[132:133]
	v_pk_mul_f32 v[176:177], s[68:69], v[138:139]
	v_pk_mul_f32 v[178:179], s[46:47], v[136:137]
	v_pk_mul_f32 v[172:173], s[68:69], v[142:143]
	v_pk_mul_f32 v[174:175], s[46:47], v[140:141]
	s_cbranch_scc0 .LBB0_517
	s_ashr_i32 s85, s84, 31
	s_lshl_b64 s[2:3], s[84:85], 12
	s_add_u32 s6, s62, s2
	s_addc_u32 s7, s63, s3
	v_lshlrev_b64 v[128:129], 2, v[170:171]
	v_lshl_add_u64 v[140:141], s[6:7], 0, v[128:129]
	s_add_u32 s82, s66, s2
	global_load_dwordx4 v[142:145], v[140:141], off
	global_load_dwordx4 v[146:149], v[140:141], off offset:64
	global_load_dwordx4 v[150:153], v[140:141], off offset:512
	global_load_dwordx4 v[216:219], v[140:141], off offset:576
	s_addc_u32 s83, s67, s3
	s_mov_b32 s2, 0x10000
	v_lshl_add_u64 v[188:189], s[82:83], 0, v[128:129]
	v_add_co_u32_e32 v128, vcc, s2, v140
	s_mov_b32 s3, 0x20000
	s_nop 0
	v_addc_co_u32_e32 v129, vcc, 0, v141, vcc
	global_load_dwordx4 v[220:223], v[128:129], off
	global_load_dwordx4 v[224:227], v[128:129], off offset:64
	global_load_dwordx4 v[228:231], v[128:129], off offset:512
	global_load_dwordx4 v[232:235], v[128:129], off offset:576
	v_add_co_u32_e32 v128, vcc, s3, v140
	s_mov_b32 s6, 0x30000
	s_nop 0
	v_addc_co_u32_e32 v129, vcc, 0, v141, vcc
	global_load_dwordx4 v[236:239], v[128:129], off
	global_load_dwordx4 v[240:243], v[128:129], off offset:64
	global_load_dwordx4 v[244:247], v[128:129], off offset:512
	global_load_dwordx4 v[248:251], v[128:129], off offset:576
	v_add_co_u32_e32 v128, vcc, s6, v140
	s_mov_b32 s7, 0xb0000
	s_nop 0
	v_addc_co_u32_e32 v129, vcc, 0, v141, vcc
	global_load_dwordx4 v[206:209], v[128:129], off
	global_load_dwordx4 v[136:139], v[128:129], off offset:64
	global_load_dwordx4 v[132:135], v[128:129], off offset:512
	s_nop 0
	global_load_dwordx4 v[128:131], v[128:129], off offset:576
	s_waitcnt vmcnt(0)
	v_pk_fma_f32 v[144:145], v[126:127], v[184:185], v[144:145]
	v_pk_fma_f32 v[142:143], v[124:125], v[186:187], v[142:143]
	global_store_dwordx4 v[188:189], v[142:145], off sc1
	v_pk_fma_f32 v[138:139], v[78:79], v[180:181], v[138:139]
	s_nop 0
	v_pk_fma_f32 v[144:145], v[122:123], v[180:181], v[148:149]
	v_pk_fma_f32 v[142:143], v[120:121], v[182:183], v[146:147]
	global_store_dwordx4 v[188:189], v[142:145], off offset:64 sc1
	v_add_co_u32_e32 v146, vcc, s2, v188
	s_nop 0
	v_pk_fma_f32 v[144:145], v[114:115], v[176:177], v[152:153]
	v_pk_fma_f32 v[142:143], v[112:113], v[178:179], v[150:151]
	global_store_dwordx4 v[188:189], v[142:145], off offset:512 sc1
	v_addc_co_u32_e32 v147, vcc, 0, v189, vcc
	s_nop 0
	v_pk_fma_f32 v[144:145], v[106:107], v[172:173], v[218:219]
	v_pk_fma_f32 v[142:143], v[104:105], v[174:175], v[216:217]
	global_store_dwordx4 v[188:189], v[142:145], off offset:576 sc1
	v_pk_fma_f32 v[130:131], v[66:67], v[172:173], v[130:131]
	v_pk_fma_f32 v[128:129], v[64:65], v[174:175], v[128:129]
	v_pk_fma_f32 v[144:145], v[118:119], v[184:185], v[222:223]
	v_pk_fma_f32 v[142:143], v[116:117], v[186:187], v[220:221]
	global_store_dwordx4 v[146:147], v[142:145], off sc1
	s_mov_b32 s2, 0x80000
	v_pk_fma_f32 v[136:137], v[76:77], v[182:183], v[136:137]
	v_pk_fma_f32 v[144:145], v[110:111], v[180:181], v[226:227]
	v_pk_fma_f32 v[142:143], v[108:109], v[182:183], v[224:225]
	global_store_dwordx4 v[146:147], v[142:145], off offset:64 sc1
	v_pk_fma_f32 v[134:135], v[70:71], v[176:177], v[134:135]
	v_pk_fma_f32 v[132:133], v[68:69], v[178:179], v[132:133]
	v_pk_fma_f32 v[144:145], v[98:99], v[176:177], v[230:231]
	v_pk_fma_f32 v[142:143], v[96:97], v[178:179], v[228:229]
	global_store_dwordx4 v[146:147], v[142:145], off offset:512 sc1
	s_nop 1
	v_pk_fma_f32 v[144:145], v[90:91], v[172:173], v[234:235]
	v_pk_fma_f32 v[142:143], v[88:89], v[174:175], v[232:233]
	global_store_dwordx4 v[146:147], v[142:145], off offset:576 sc1
	v_add_co_u32_e32 v146, vcc, s3, v188
	s_nop 0
	v_pk_fma_f32 v[144:145], v[102:103], v[184:185], v[238:239]
	v_pk_fma_f32 v[142:143], v[100:101], v[186:187], v[236:237]
	v_addc_co_u32_e32 v147, vcc, 0, v189, vcc
	global_store_dwordx4 v[146:147], v[142:145], off sc1
	s_mov_b32 s3, 0x90000
	s_nop 0
	v_pk_fma_f32 v[144:145], v[94:95], v[180:181], v[242:243]
	v_pk_fma_f32 v[142:143], v[92:93], v[182:183], v[240:241]
	global_store_dwordx4 v[146:147], v[142:145], off offset:64 sc1
	s_nop 1
	v_pk_fma_f32 v[144:145], v[82:83], v[176:177], v[246:247]
	v_pk_fma_f32 v[142:143], v[80:81], v[178:179], v[244:245]
	global_store_dwordx4 v[146:147], v[142:145], off offset:512 sc1
	s_nop 1
	v_pk_fma_f32 v[144:145], v[74:75], v[172:173], v[250:251]
	v_pk_fma_f32 v[142:143], v[72:73], v[174:175], v[248:249]
	global_store_dwordx4 v[146:147], v[142:145], off offset:576 sc1
	v_add_co_u32_e32 v146, vcc, s6, v188
	s_nop 0
	v_pk_fma_f32 v[144:145], v[86:87], v[184:185], v[208:209]
	v_addc_co_u32_e32 v147, vcc, 0, v189, vcc
	v_pk_fma_f32 v[142:143], v[84:85], v[186:187], v[206:207]
	global_store_dwordx4 v[146:147], v[128:131], off offset:576 sc1
	global_store_dwordx4 v[146:147], v[142:145], off sc1
	global_store_dwordx4 v[146:147], v[136:139], off offset:64 sc1
	v_add_co_u32_e32 v128, vcc, s2, v140
	global_store_dwordx4 v[146:147], v[132:135], off offset:512 sc1
	s_nop 0
	v_addc_co_u32_e32 v129, vcc, 0, v141, vcc
	global_load_dwordx4 v[206:209], v[128:129], off
	global_load_dwordx4 v[216:219], v[128:129], off offset:64
	global_load_dwordx4 v[220:223], v[128:129], off offset:512
	global_load_dwordx4 v[224:227], v[128:129], off offset:576
	v_add_co_u32_e32 v128, vcc, s3, v140
	s_mov_b32 s6, 0xa0000
	s_nop 0
	v_addc_co_u32_e32 v129, vcc, 0, v141, vcc
	global_load_dwordx4 v[228:231], v[128:129], off
	global_load_dwordx4 v[232:235], v[128:129], off offset:64
	global_load_dwordx4 v[236:239], v[128:129], off offset:512
	global_load_dwordx4 v[240:243], v[128:129], off offset:576
	v_add_co_u32_e32 v128, vcc, s6, v140
	s_waitcnt vmcnt(0)
	v_pk_fma_f32 v[208:209], v[62:63], v[184:185], v[208:209]
	v_addc_co_u32_e32 v129, vcc, 0, v141, vcc
	global_load_dwordx4 v[244:247], v[128:129], off
	global_load_dwordx4 v[152:155], v[128:129], off offset:64
	global_load_dwordx4 v[148:151], v[128:129], off offset:512
	global_load_dwordx4 v[144:147], v[128:129], off offset:576
	v_add_co_u32_e32 v128, vcc, s7, v140
	v_pk_fma_f32 v[206:207], v[60:61], v[186:187], v[206:207]
	s_nop 0
	v_addc_co_u32_e32 v129, vcc, 0, v141, vcc
	global_load_dwordx4 v[140:143], v[128:129], off
	global_load_dwordx4 v[136:139], v[128:129], off offset:64
	global_load_dwordx4 v[132:135], v[128:129], off offset:512
	s_nop 0
	global_load_dwordx4 v[128:131], v[128:129], off offset:576
	v_add_co_u32_e32 v248, vcc, s2, v188
	s_waitcnt vmcnt(0)
	v_pk_fma_f32 v[154:155], v[30:31], v[180:181], v[154:155]
	v_addc_co_u32_e32 v249, vcc, 0, v189, vcc
	global_store_dwordx4 v[248:249], v[206:209], off sc1
	v_pk_fma_f32 v[146:147], v[10:11], v[172:173], v[146:147]
	v_pk_fma_f32 v[144:145], v[8:9], v[174:175], v[144:145]
	v_pk_fma_f32 v[208:209], v[58:59], v[180:181], v[218:219]
	v_pk_fma_f32 v[206:207], v[56:57], v[182:183], v[216:217]
	global_store_dwordx4 v[248:249], v[206:209], off offset:64 sc1
	v_add_co_u32_e32 v216, vcc, s3, v188
	s_nop 0
	v_pk_fma_f32 v[208:209], v[50:51], v[176:177], v[222:223]
	v_pk_fma_f32 v[206:207], v[48:49], v[178:179], v[220:221]
	global_store_dwordx4 v[248:249], v[206:209], off offset:512 sc1
	v_addc_co_u32_e32 v217, vcc, 0, v189, vcc
	s_nop 0
	v_pk_fma_f32 v[208:209], v[42:43], v[172:173], v[226:227]
	v_pk_fma_f32 v[206:207], v[40:41], v[174:175], v[224:225]
	global_store_dwordx4 v[248:249], v[206:209], off offset:576 sc1
	v_pk_fma_f32 v[152:153], v[28:29], v[182:183], v[152:153]
	v_pk_fma_f32 v[150:151], v[18:19], v[176:177], v[150:151]
	v_pk_fma_f32 v[208:209], v[54:55], v[184:185], v[230:231]
	v_pk_fma_f32 v[206:207], v[52:53], v[186:187], v[228:229]
	global_store_dwordx4 v[216:217], v[206:209], off sc1
	v_pk_fma_f32 v[148:149], v[16:17], v[178:179], v[148:149]
	v_pk_fma_f32 v[142:143], v[22:23], v[184:185], v[142:143]
	v_pk_fma_f32 v[208:209], v[46:47], v[180:181], v[234:235]
	v_pk_fma_f32 v[206:207], v[44:45], v[182:183], v[232:233]
	global_store_dwordx4 v[216:217], v[206:209], off offset:64 sc1
	v_pk_fma_f32 v[140:141], v[20:21], v[186:187], v[140:141]
	v_pk_fma_f32 v[138:139], v[14:15], v[180:181], v[138:139]
	v_pk_fma_f32 v[208:209], v[34:35], v[176:177], v[238:239]
	v_pk_fma_f32 v[206:207], v[32:33], v[178:179], v[236:237]
	global_store_dwordx4 v[216:217], v[206:209], off offset:512 sc1
	v_pk_fma_f32 v[136:137], v[12:13], v[182:183], v[136:137]
	v_pk_fma_f32 v[134:135], v[6:7], v[176:177], v[134:135]
	v_pk_fma_f32 v[208:209], v[26:27], v[172:173], v[242:243]
	v_pk_fma_f32 v[206:207], v[24:25], v[174:175], v[240:241]
	global_store_dwordx4 v[216:217], v[206:209], off offset:576 sc1
	v_add_co_u32_e32 v216, vcc, s6, v188
	s_nop 0
	v_pk_fma_f32 v[208:209], v[38:39], v[184:185], v[246:247]
	v_addc_co_u32_e32 v217, vcc, 0, v189, vcc
	global_store_dwordx4 v[216:217], v[144:147], off offset:576 sc1
	v_pk_fma_f32 v[206:207], v[36:37], v[186:187], v[244:245]
	v_pk_fma_f32 v[132:133], v[4:5], v[178:179], v[132:133]
	v_add_co_u32_e32 v144, vcc, s7, v188
	global_store_dwordx4 v[216:217], v[206:209], off sc1
	s_nop 0
	v_addc_co_u32_e32 v145, vcc, 0, v189, vcc
	global_store_dwordx4 v[216:217], v[152:155], off offset:64 sc1
	global_store_dwordx4 v[216:217], v[148:151], off offset:512 sc1
	global_store_dwordx4 v[144:145], v[140:143], off sc1
	global_store_dwordx4 v[144:145], v[136:139], off offset:64 sc1
	global_store_dwordx4 v[144:145], v[132:135], off offset:512 sc1
	v_pk_fma_f32 v[130:131], v[2:3], v[172:173], v[130:131]
	v_pk_fma_f32 v[128:129], v[0:1], v[174:175], v[128:129]
	s_mov_b64 s[2:3], 0
.LBB0_517:
	s_andn2_b64 vcc, exec, s[2:3]
	s_cbranch_vccnz .LBB0_497
	s_lshl_b32 s2, s10, 11
	s_and_b32 s2, s2, 0x1800
	s_add_i32 s2, s84, s2
	s_add_i32 s10, s2, 0xffff8000
	s_lshl_b64 s[2:3], s[10:11], 12
	s_add_u32 s82, s28, s2
	s_addc_u32 s83, s29, s3
	v_lshl_add_u64 v[128:129], v[170:171], 2, s[82:83]
	v_pk_mul_f32 v[114:115], v[114:115], v[176:177]
	v_pk_mul_f32 v[112:113], v[112:113], v[178:179]
	s_mov_b32 s2, 0x10000
	global_store_dwordx4 v[128:129], v[112:115], off offset:512 sc1
	v_pk_mul_f32 v[98:99], v[98:99], v[176:177]
	v_pk_mul_f32 v[96:97], v[96:97], v[178:179]
	v_add_co_u32_e32 v112, vcc, s2, v128
	s_mov_b32 s2, 0x20000
	s_nop 0
	v_addc_co_u32_e32 v113, vcc, 0, v129, vcc
	global_store_dwordx4 v[112:113], v[96:99], off offset:512 sc1
	v_pk_mul_f32 v[82:83], v[82:83], v[176:177]
	v_pk_mul_f32 v[80:81], v[80:81], v[178:179]
	v_add_co_u32_e32 v96, vcc, s2, v128
	s_mov_b32 s2, 0x30000
	s_nop 0
	v_addc_co_u32_e32 v97, vcc, 0, v129, vcc
	global_store_dwordx4 v[96:97], v[80:83], off offset:512 sc1
	v_pk_mul_f32 v[66:67], v[66:67], v[172:173]
	v_pk_mul_f32 v[64:65], v[64:65], v[174:175]
	v_add_co_u32_e32 v80, vcc, s2, v128
	s_mov_b32 s2, 0x80000
	s_nop 0
	v_addc_co_u32_e32 v81, vcc, 0, v129, vcc
	global_store_dwordx4 v[80:81], v[64:67], off offset:576 sc1
	v_pk_mul_f32 v[50:51], v[50:51], v[176:177]
	v_pk_mul_f32 v[48:49], v[48:49], v[178:179]
	v_add_co_u32_e32 v64, vcc, s2, v128
	s_mov_b32 s2, 0x90000
	s_nop 0
	v_addc_co_u32_e32 v65, vcc, 0, v129, vcc
	global_store_dwordx4 v[64:65], v[48:51], off offset:512 sc1
	v_pk_mul_f32 v[34:35], v[34:35], v[176:177]
	v_pk_mul_f32 v[32:33], v[32:33], v[178:179]
	v_add_co_u32_e32 v48, vcc, s2, v128
	s_mov_b32 s2, 0xa0000
	s_nop 0
	v_addc_co_u32_e32 v49, vcc, 0, v129, vcc
	global_store_dwordx4 v[48:49], v[32:35], off offset:512 sc1
	v_pk_mul_f32 v[18:19], v[18:19], v[176:177]
	v_pk_mul_f32 v[16:17], v[16:17], v[178:179]
	v_add_co_u32_e32 v32, vcc, s2, v128
	s_mov_b32 s2, 0xb0000
	s_nop 0
	v_addc_co_u32_e32 v33, vcc, 0, v129, vcc
	v_pk_mul_f32 v[106:107], v[106:107], v[172:173]
	v_pk_mul_f32 v[104:105], v[104:105], v[174:175]
	v_pk_mul_f32 v[90:91], v[90:91], v[172:173]
	v_pk_mul_f32 v[88:89], v[88:89], v[174:175]
	v_pk_mul_f32 v[74:75], v[74:75], v[172:173]
	v_pk_mul_f32 v[72:73], v[72:73], v[174:175]
	v_pk_mul_f32 v[42:43], v[42:43], v[172:173]
	v_pk_mul_f32 v[40:41], v[40:41], v[174:175]
	v_pk_mul_f32 v[26:27], v[26:27], v[172:173]
	v_pk_mul_f32 v[24:25], v[24:25], v[174:175]
	global_store_dwordx4 v[32:33], v[16:19], off offset:512 sc1
	v_pk_mul_f32 v[10:11], v[10:11], v[172:173]
	v_pk_mul_f32 v[8:9], v[8:9], v[174:175]
	v_add_co_u32_e32 v16, vcc, s2, v128
	v_pk_mul_f32 v[126:127], v[126:127], v[184:185]
	v_pk_mul_f32 v[124:125], v[124:125], v[186:187]
	v_pk_mul_f32 v[122:123], v[122:123], v[180:181]
	v_pk_mul_f32 v[120:121], v[120:121], v[182:183]
	global_store_dwordx4 v[128:129], v[104:107], off offset:576 sc1
	global_store_dwordx4 v[112:113], v[88:91], off offset:576 sc1
	global_store_dwordx4 v[96:97], v[72:75], off offset:576 sc1
	v_pk_mul_f32 v[106:107], v[118:119], v[184:185]
	v_pk_mul_f32 v[104:105], v[116:117], v[186:187]
	v_pk_mul_f32 v[90:91], v[102:103], v[184:185]
	v_pk_mul_f32 v[88:89], v[100:101], v[186:187]
	v_pk_mul_f32 v[74:75], v[86:87], v[184:185]
	v_pk_mul_f32 v[72:73], v[84:85], v[186:187]
	global_store_dwordx4 v[64:65], v[40:43], off offset:576 sc1
	global_store_dwordx4 v[48:49], v[24:27], off offset:576 sc1
	global_store_dwordx4 v[32:33], v[8:11], off offset:576 sc1
	v_pk_mul_f32 v[42:43], v[54:55], v[184:185]
	v_pk_mul_f32 v[40:41], v[52:53], v[186:187]
	v_pk_mul_f32 v[26:27], v[38:39], v[184:185]
	v_pk_mul_f32 v[24:25], v[36:37], v[186:187]
	v_pk_mul_f32 v[10:11], v[22:23], v[184:185]
	v_pk_mul_f32 v[8:9], v[20:21], v[186:187]
	v_addc_co_u32_e32 v17, vcc, 0, v129, vcc
	global_store_dwordx4 v[128:129], v[124:127], off sc1
	global_store_dwordx4 v[128:129], v[120:123], off offset:64 sc1
	global_store_dwordx4 v[112:113], v[104:107], off sc1
	global_store_dwordx4 v[96:97], v[88:91], off sc1
	global_store_dwordx4 v[80:81], v[72:75], off sc1
	v_pk_mul_f32 v[106:107], v[110:111], v[180:181]
	v_pk_mul_f32 v[104:105], v[108:109], v[182:183]
	v_pk_mul_f32 v[90:91], v[94:95], v[180:181]
	v_pk_mul_f32 v[88:89], v[92:93], v[182:183]
	v_pk_mul_f32 v[74:75], v[78:79], v[180:181]
	v_pk_mul_f32 v[72:73], v[76:77], v[182:183]
	v_pk_mul_f32 v[70:71], v[70:71], v[176:177]
	v_pk_mul_f32 v[68:69], v[68:69], v[178:179]
	v_pk_mul_f32 v[62:63], v[62:63], v[184:185]
	v_pk_mul_f32 v[60:61], v[60:61], v[186:187]
	v_pk_mul_f32 v[58:59], v[58:59], v[180:181]
	v_pk_mul_f32 v[56:57], v[56:57], v[182:183]
	global_store_dwordx4 v[48:49], v[40:43], off sc1
	global_store_dwordx4 v[32:33], v[24:27], off sc1
	global_store_dwordx4 v[16:17], v[8:11], off sc1
	v_pk_mul_f32 v[42:43], v[46:47], v[180:181]
	v_pk_mul_f32 v[40:41], v[44:45], v[182:183]
	v_pk_mul_f32 v[26:27], v[30:31], v[180:181]
	v_pk_mul_f32 v[24:25], v[28:29], v[182:183]
	v_pk_mul_f32 v[10:11], v[14:15], v[180:181]
	v_pk_mul_f32 v[8:9], v[12:13], v[182:183]
	v_pk_mul_f32 v[6:7], v[6:7], v[176:177]
	v_pk_mul_f32 v[4:5], v[4:5], v[178:179]
	v_pk_mul_f32 v[130:131], v[2:3], v[172:173]
	v_pk_mul_f32 v[128:129], v[0:1], v[174:175]
	global_store_dwordx4 v[112:113], v[104:107], off offset:64 sc1
	global_store_dwordx4 v[96:97], v[88:91], off offset:64 sc1
	global_store_dwordx4 v[80:81], v[72:75], off offset:64 sc1
	global_store_dwordx4 v[80:81], v[68:71], off offset:512 sc1
	global_store_dwordx4 v[64:65], v[60:63], off sc1
	global_store_dwordx4 v[64:65], v[56:59], off offset:64 sc1
	global_store_dwordx4 v[48:49], v[40:43], off offset:64 sc1
	global_store_dwordx4 v[32:33], v[24:27], off offset:64 sc1
	global_store_dwordx4 v[16:17], v[8:11], off offset:64 sc1
	global_store_dwordx4 v[16:17], v[4:7], off offset:512 sc1
	s_branch .LBB0_497

.LBB0_527:
	v_cmp_lt_i32_e32 vcc, s22, v1
	s_and_saveexec_b64 s[6:7], vcc
	s_xor_b64 s[40:41], exec, s[6:7]
	s_cbranch_execz .LBB0_545
	s_movk_i32 s6, 0x15ff
	v_cmp_lt_u32_e32 vcc, s6, v1
	s_and_saveexec_b64 s[6:7], vcc
	s_xor_b64 s[42:43], exec, s[6:7]
	s_cbranch_execz .LBB0_542
	s_movk_i32 s6, 0x1b7f
	v_cmp_lt_u32_e32 vcc, s6, v1
	s_and_saveexec_b64 s[6:7], vcc
	s_xor_b64 s[46:47], exec, s[6:7]
	s_cbranch_execz .LBB0_539
	s_movk_i32 s6, 0x20ff
	v_cmp_lt_u32_e32 vcc, s6, v1
	s_and_saveexec_b64 s[6:7], vcc
	s_xor_b64 s[48:49], exec, s[6:7]
	s_cbranch_execz .LBB0_536
	s_movk_i32 s6, 0x22af
	v_cmp_lt_u32_e32 vcc, s6, v1
	s_and_saveexec_b64 s[6:7], vcc
	s_xor_b64 s[6:7], exec, s[6:7]
	s_cbranch_execz .LBB0_533
	s_load_dwordx2 s[24:25], s[0:1], 0xa8
	v_add_u32_e32 v16, 0xfffbaa00, v26
	v_and_b32_e32 v28, 0x3e0, v16
	v_and_b32_e32 v29, 0x1ffc0, v27
	v_lshlrev_b32_e32 v156, 2, v28
	v_or_b32_e32 v30, v29, v15
	s_waitcnt lgkmcnt(0)
	v_lshl_add_u64 v[16:17], s[24:25], 0, v[156:157]
	v_lshlrev_b32_e32 v156, 2, v0
	v_lshl_add_u64 v[16:17], v[16:17], 0, v[156:157]
	v_lshlrev_b32_e32 v156, 12, v30
	v_lshl_add_u64 v[16:17], v[16:17], 0, v[156:157]
	v_add_co_u32_e32 v30, vcc, 0x400000, v16
	v_lshlrev_b32_e32 v156, 1, v29
	s_nop 0
	v_addc_co_u32_e32 v31, vcc, 0, v17, vcc
	global_load_dword v32, v[30:31], off
	v_add_co_u32_e32 v30, vcc, 0x402000, v16
	v_or_b32_e32 v29, v28, v19
	s_nop 0
	v_addc_co_u32_e32 v31, vcc, 0, v17, vcc
	global_load_dword v33, v[30:31], off
	v_add_co_u32_e32 v30, vcc, 0x404000, v16
	s_nop 1
	v_addc_co_u32_e32 v31, vcc, 0, v17, vcc
	global_load_dword v34, v[30:31], off
	v_add_co_u32_e32 v30, vcc, 0x406000, v16
	s_nop 1
	v_addc_co_u32_e32 v31, vcc, 0, v17, vcc
	global_load_dword v35, v[30:31], off
	v_add_co_u32_e32 v30, vcc, 0x408000, v16
	s_nop 1
	v_addc_co_u32_e32 v31, vcc, 0, v17, vcc
	global_load_dword v36, v[30:31], off
	v_add_co_u32_e32 v30, vcc, 0x40a000, v16
	s_nop 1
	v_addc_co_u32_e32 v31, vcc, 0, v17, vcc
	global_load_dword v37, v[30:31], off
	v_add_co_u32_e32 v30, vcc, 0x40c000, v16
	s_nop 1
	v_addc_co_u32_e32 v31, vcc, 0, v17, vcc
	global_load_dword v38, v[30:31], off
	v_add_co_u32_e32 v30, vcc, 0x40e000, v16
	s_nop 1
	v_addc_co_u32_e32 v31, vcc, 0, v17, vcc
	global_load_dword v39, v[30:31], off
	v_add_co_u32_e32 v30, vcc, 0x410000, v16
	s_nop 1
	v_addc_co_u32_e32 v31, vcc, 0, v17, vcc
	global_load_dword v40, v[30:31], off
	v_add_co_u32_e32 v30, vcc, 0x412000, v16
	s_nop 1
	v_addc_co_u32_e32 v31, vcc, 0, v17, vcc
	global_load_dword v41, v[30:31], off
	v_add_co_u32_e32 v30, vcc, 0x414000, v16
	s_nop 1
	v_addc_co_u32_e32 v31, vcc, 0, v17, vcc
	global_load_dword v42, v[30:31], off
	v_add_co_u32_e32 v30, vcc, 0x416000, v16
	s_nop 1
	v_addc_co_u32_e32 v31, vcc, 0, v17, vcc
	global_load_dword v43, v[30:31], off
	v_add_co_u32_e32 v30, vcc, 0x418000, v16
	s_nop 1
	v_addc_co_u32_e32 v31, vcc, 0, v17, vcc
	global_load_dword v44, v[30:31], off
	v_add_co_u32_e32 v30, vcc, 0x41a000, v16
	s_nop 1
	v_addc_co_u32_e32 v31, vcc, 0, v17, vcc
	global_load_dword v45, v[30:31], off
	v_add_co_u32_e32 v30, vcc, 0x41c000, v16
	s_nop 1
	v_addc_co_u32_e32 v31, vcc, 0, v17, vcc
	global_load_dword v46, v[30:31], off
	v_add_co_u32_e32 v30, vcc, 0x41e000, v16
	s_nop 1
	v_addc_co_u32_e32 v31, vcc, 0, v17, vcc
	global_load_dword v47, v[30:31], off
	v_add_co_u32_e32 v30, vcc, 0x420000, v16
	s_nop 1
	v_addc_co_u32_e32 v31, vcc, 0, v17, vcc
	global_load_dword v48, v[30:31], off
	v_add_co_u32_e32 v30, vcc, 0x422000, v16
	s_nop 1
	v_addc_co_u32_e32 v31, vcc, 0, v17, vcc
	global_load_dword v49, v[30:31], off
	v_add_co_u32_e32 v30, vcc, 0x424000, v16
	s_nop 1
	v_addc_co_u32_e32 v31, vcc, 0, v17, vcc
	global_load_dword v50, v[30:31], off
	v_add_co_u32_e32 v30, vcc, 0x426000, v16
	s_nop 1
	v_addc_co_u32_e32 v31, vcc, 0, v17, vcc
	global_load_dword v51, v[30:31], off
	v_add_co_u32_e32 v30, vcc, 0x428000, v16
	s_nop 1
	v_addc_co_u32_e32 v31, vcc, 0, v17, vcc
	global_load_dword v52, v[30:31], off
	v_add_co_u32_e32 v30, vcc, 0x42a000, v16
	s_nop 1
	v_addc_co_u32_e32 v31, vcc, 0, v17, vcc
	global_load_dword v53, v[30:31], off
	v_add_co_u32_e32 v30, vcc, 0x42c000, v16
	s_nop 1
	v_addc_co_u32_e32 v31, vcc, 0, v17, vcc
	global_load_dword v54, v[30:31], off
	v_add_co_u32_e32 v30, vcc, 0x42e000, v16
	s_nop 1
	v_addc_co_u32_e32 v31, vcc, 0, v17, vcc
	global_load_dword v55, v[30:31], off
	v_add_co_u32_e32 v30, vcc, 0x430000, v16
	s_nop 1
	v_addc_co_u32_e32 v31, vcc, 0, v17, vcc
	global_load_dword v56, v[30:31], off
	v_add_co_u32_e32 v30, vcc, 0x432000, v16
	s_nop 1
	v_addc_co_u32_e32 v31, vcc, 0, v17, vcc
	global_load_dword v57, v[30:31], off
	v_add_co_u32_e32 v30, vcc, 0x434000, v16
	s_nop 1
	v_addc_co_u32_e32 v31, vcc, 0, v17, vcc
	global_load_dword v58, v[30:31], off
	v_add_co_u32_e32 v30, vcc, 0x436000, v16
	s_nop 1
	v_addc_co_u32_e32 v31, vcc, 0, v17, vcc
	global_load_dword v59, v[30:31], off
	v_add_co_u32_e32 v30, vcc, 0x438000, v16
	s_nop 1
	v_addc_co_u32_e32 v31, vcc, 0, v17, vcc
	global_load_dword v60, v[30:31], off
	v_add_co_u32_e32 v30, vcc, 0x43a000, v16
	s_nop 1
	v_addc_co_u32_e32 v31, vcc, 0, v17, vcc
	global_load_dword v61, v[30:31], off
	v_add_co_u32_e32 v30, vcc, 0x43c000, v16
	s_nop 1
	v_addc_co_u32_e32 v31, vcc, 0, v17, vcc
	v_add_co_u32_e32 v16, vcc, 0x43e000, v16
	global_load_dword v30, v[30:31], off
	s_nop 0
	v_addc_co_u32_e32 v17, vcc, 0, v17, vcc
	global_load_dword v16, v[16:17], off
	v_add_u32_e32 v17, 0x400, v18
	s_waitcnt vmcnt(30)
	ds_write2_b32 v18, v32, v33 offset1:66
	s_waitcnt vmcnt(28)
	ds_write2_b32 v18, v34, v35 offset0:132 offset1:198
	s_waitcnt vmcnt(26)
	ds_write2_b32 v17, v36, v37 offset0:8 offset1:74
	s_waitcnt vmcnt(24)
	ds_write2_b32 v17, v38, v39 offset0:140 offset1:206
	v_add_u32_e32 v17, 0x800, v18
	s_waitcnt vmcnt(22)
	ds_write2_b32 v17, v40, v41 offset0:16 offset1:82
	s_waitcnt vmcnt(20)
	ds_write2_b32 v17, v42, v43 offset0:148 offset1:214
	v_add_u32_e32 v17, 0xc00, v18
	s_waitcnt vmcnt(18)
	ds_write2_b32 v17, v44, v45 offset0:24 offset1:90
	s_waitcnt vmcnt(16)
	ds_write2_b32 v17, v46, v47 offset0:156 offset1:222
	v_add_u32_e32 v17, 0x1000, v18
	s_waitcnt vmcnt(14)
	ds_write2_b32 v17, v48, v49 offset0:32 offset1:98
	s_waitcnt vmcnt(12)
	ds_write2_b32 v17, v50, v51 offset0:164 offset1:230
	v_add_u32_e32 v17, 0x1400, v18
	s_waitcnt vmcnt(10)
	ds_write2_b32 v17, v52, v53 offset0:40 offset1:106
	s_waitcnt vmcnt(8)
	ds_write2_b32 v17, v54, v55 offset0:172 offset1:238
	v_add_u32_e32 v17, 0x1800, v18
	s_waitcnt vmcnt(6)
	ds_write2_b32 v17, v56, v57 offset0:48 offset1:114
	s_waitcnt vmcnt(4)
	ds_write2_b32 v17, v58, v59 offset0:180 offset1:246
	v_add_u32_e32 v17, 0x1c00, v18
	s_waitcnt vmcnt(2)
	ds_write2_b32 v17, v60, v61 offset0:56 offset1:122
	s_waitcnt vmcnt(0)
	ds_write2_b32 v17, v30, v16 offset0:188 offset1:254
	s_waitcnt lgkmcnt(0)
	ds_read2_b32 v[30:31], v21 offset1:33
	s_waitcnt lgkmcnt(0)
	v_cvt_pk_bf16_f32 v30, v30, v31
	ds_read2_b32 v[32:33], v21 offset0:66 offset1:99
	s_waitcnt lgkmcnt(0)
	v_cvt_pk_bf16_f32 v31, v32, v33
	ds_read2_b32 v[32:33], v21 offset0:132 offset1:165
	v_lshl_add_u64 v[16:17], v[2:3], 0, v[156:157]
	s_waitcnt lgkmcnt(0)
	v_cvt_pk_bf16_f32 v32, v32, v33
	ds_read2_b32 v[34:35], v21 offset0:198 offset1:231
	v_lshlrev_b32_e32 v156, 11, v29
	s_waitcnt lgkmcnt(0)
	v_cvt_pk_bf16_f32 v33, v34, v35
	v_lshl_add_u64 v[34:35], v[16:17], 0, v[156:157]
	global_store_dwordx4 v[34:35], v[30:33], off sc1
	ds_read2_b32 v[30:31], v21 offset0:8 offset1:41
	v_or_b32_e32 v29, v28, v22
	s_waitcnt lgkmcnt(0)
	v_cvt_pk_bf16_f32 v30, v30, v31
	ds_read2_b32 v[32:33], v21 offset0:74 offset1:107
	s_waitcnt lgkmcnt(0)
	v_cvt_pk_bf16_f32 v31, v32, v33
	ds_read2_b32 v[32:33], v21 offset0:140 offset1:173
	s_waitcnt lgkmcnt(0)
	v_cvt_pk_bf16_f32 v32, v32, v33
	ds_read2_b32 v[34:35], v21 offset0:206 offset1:239
	v_lshlrev_b32_e32 v156, 11, v29
	s_waitcnt lgkmcnt(0)
	v_cvt_pk_bf16_f32 v33, v34, v35
	v_lshl_add_u64 v[34:35], v[16:17], 0, v[156:157]
	global_store_dwordx4 v[34:35], v[30:33], off sc1
	ds_read2_b32 v[30:31], v21 offset0:16 offset1:49
	v_or_b32_e32 v29, v28, v23
	s_waitcnt lgkmcnt(0)
	v_cvt_pk_bf16_f32 v30, v30, v31
	ds_read2_b32 v[32:33], v21 offset0:82 offset1:115
	s_waitcnt lgkmcnt(0)
	v_cvt_pk_bf16_f32 v31, v32, v33
	ds_read2_b32 v[32:33], v21 offset0:148 offset1:181
	s_waitcnt lgkmcnt(0)
	v_cvt_pk_bf16_f32 v32, v32, v33
	ds_read2_b32 v[34:35], v21 offset0:214 offset1:247
	v_lshlrev_b32_e32 v156, 11, v29
	s_waitcnt lgkmcnt(0)
	v_cvt_pk_bf16_f32 v33, v34, v35
	v_lshl_add_u64 v[34:35], v[16:17], 0, v[156:157]
	global_store_dwordx4 v[34:35], v[30:33], off sc1
	ds_read2_b32 v[30:31], v21 offset0:24 offset1:57
	v_or_b32_e32 v28, v28, v24
	s_waitcnt lgkmcnt(0)
	v_cvt_pk_bf16_f32 v30, v30, v31
	ds_read2_b32 v[32:33], v21 offset0:90 offset1:123
	v_lshlrev_b32_e32 v156, 11, v28
	s_waitcnt lgkmcnt(0)
	v_cvt_pk_bf16_f32 v31, v32, v33
	ds_read2_b32 v[32:33], v21 offset0:156 offset1:189
	v_lshl_add_u64 v[16:17], v[16:17], 0, v[156:157]
	s_waitcnt lgkmcnt(0)
	v_cvt_pk_bf16_f32 v32, v32, v33
	ds_read2_b32 v[34:35], v21 offset0:222 offset1:255
	s_waitcnt lgkmcnt(0)
	v_cvt_pk_bf16_f32 v33, v34, v35
	global_store_dwordx4 v[16:17], v[30:33], off sc1
	s_waitcnt lgkmcnt(0)
.LBB0_533:
	s_andn2_saveexec_b64 s[6:7], s[6:7]
	s_cbranch_execz .LBB0_535
	v_add_u16_e32 v16, 0xdf00, v1
	v_mul_u32_u24_e32 v17, 0x2f69, v16
	v_sub_u16_sdwa v28, v16, v17 dst_sel:DWORD dst_unused:UNUSED_PAD src0_sel:DWORD src1_sel:WORD_1
	v_lshrrev_b16_e32 v28, 1, v28
	v_add_u16_sdwa v17, v28, v17 dst_sel:DWORD dst_unused:UNUSED_PAD src0_sel:DWORD src1_sel:WORD_1
	s_load_dwordx2 s[24:25], s[0:1], 0x50
	v_lshrrev_b16_e32 v30, 4, v17
	v_mul_lo_u16_e32 v17, 27, v30
	v_sub_u16_e32 v16, v16, v17
	v_lshlrev_b16_e32 v31, 5, v16
	v_lshl_or_b32 v28, v30, 6, v15
	v_lshlrev_b32_e32 v156, 2, v31
	s_waitcnt lgkmcnt(0)
	v_lshl_add_u64 v[16:17], s[24:25], 0, v[156:157]
	v_lshlrev_b32_e32 v156, 2, v0
	v_mul_u32_u24_e32 v28, 0x560, v28
	v_lshl_add_u64 v[16:17], v[16:17], 0, v[156:157]
	v_lshlrev_b32_e32 v156, 2, v28
	v_lshl_add_u64 v[16:17], v[16:17], 0, v[156:157]
	s_mov_b32 s10, 0x560000
	v_add_co_u32_e32 v28, vcc, s10, v16
	s_mov_b32 s10, 0x562000
	s_nop 0
	v_addc_co_u32_e32 v29, vcc, 0, v17, vcc
	global_load_dword v32, v[28:29], off offset:1024
	v_add_co_u32_e32 v28, vcc, s10, v16
	s_mov_b32 s10, 0x565000
	s_nop 0
	v_addc_co_u32_e32 v29, vcc, 0, v17, vcc
	global_load_dword v33, v[28:29], off offset:3840
	v_add_co_u32_e32 v28, vcc, s10, v16
	s_mov_b32 s10, 0x568000
	s_nop 0
	v_addc_co_u32_e32 v29, vcc, 0, v17, vcc
	global_load_dword v34, v[28:29], off offset:2560
	v_add_co_u32_e32 v28, vcc, s10, v16
	s_mov_b32 s10, 0x56b000
	s_nop 0
	v_addc_co_u32_e32 v29, vcc, 0, v17, vcc
	global_load_dword v35, v[28:29], off offset:1280
	v_add_co_u32_e32 v28, vcc, s10, v16
	s_mov_b32 s10, 0x56d000
	s_nop 0
	v_addc_co_u32_e32 v29, vcc, 0, v17, vcc
	global_load_dword v36, v[28:29], off
	v_add_co_u32_e32 v28, vcc, s10, v16
	s_mov_b32 s10, 0x570000
	s_nop 0
	v_addc_co_u32_e32 v29, vcc, 0, v17, vcc
	global_load_dword v37, v[28:29], off offset:2816
	v_add_co_u32_e32 v28, vcc, s10, v16
	s_mov_b32 s10, 0x573000
	s_nop 0
	v_addc_co_u32_e32 v29, vcc, 0, v17, vcc
	global_load_dword v38, v[28:29], off offset:1536
	v_add_co_u32_e32 v28, vcc, s10, v16
	s_mov_b32 s10, 0x575000
	s_nop 0
	v_addc_co_u32_e32 v29, vcc, 0, v17, vcc
	global_load_dword v39, v[28:29], off offset:256
	v_add_co_u32_e32 v28, vcc, s10, v16
	s_mov_b32 s10, 0x578000
	s_nop 0
	v_addc_co_u32_e32 v29, vcc, 0, v17, vcc
	global_load_dword v40, v[28:29], off offset:3072
	v_add_co_u32_e32 v28, vcc, s10, v16
	s_mov_b32 s10, 0x57b000
	s_nop 0
	v_addc_co_u32_e32 v29, vcc, 0, v17, vcc
	global_load_dword v41, v[28:29], off offset:1792
	v_add_co_u32_e32 v28, vcc, s10, v16
	s_mov_b32 s10, 0x57d000
	s_nop 0
	v_addc_co_u32_e32 v29, vcc, 0, v17, vcc
	global_load_dword v42, v[28:29], off offset:512
	v_add_co_u32_e32 v28, vcc, s10, v16
	s_mov_b32 s10, 0x580000
	s_nop 0
	v_addc_co_u32_e32 v29, vcc, 0, v17, vcc
	global_load_dword v43, v[28:29], off offset:3328
	v_add_co_u32_e32 v28, vcc, s10, v16
	s_mov_b32 s10, 0x583000
	s_nop 0
	v_addc_co_u32_e32 v29, vcc, 0, v17, vcc
	global_load_dword v44, v[28:29], off offset:2048
	v_add_co_u32_e32 v28, vcc, s10, v16
	s_mov_b32 s10, 0x585000
	s_nop 0
	v_addc_co_u32_e32 v29, vcc, 0, v17, vcc
	global_load_dword v45, v[28:29], off offset:768
	v_add_co_u32_e32 v28, vcc, s10, v16
	s_mov_b32 s10, 0x588000
	s_nop 0
	v_addc_co_u32_e32 v29, vcc, 0, v17, vcc
	global_load_dword v46, v[28:29], off offset:3584
	v_add_co_u32_e32 v28, vcc, s10, v16
	s_mov_b32 s10, 0x58b000
	s_nop 0
	v_addc_co_u32_e32 v29, vcc, 0, v17, vcc
	global_load_dword v47, v[28:29], off offset:2304
	v_add_co_u32_e32 v28, vcc, s10, v16
	s_mov_b32 s10, 0x58d000
	s_nop 0
	v_addc_co_u32_e32 v29, vcc, 0, v17, vcc
	global_load_dword v48, v[28:29], off offset:1024
	v_add_co_u32_e32 v28, vcc, s10, v16
	s_mov_b32 s10, 0x590000
	s_nop 0
	v_addc_co_u32_e32 v29, vcc, 0, v17, vcc
	global_load_dword v49, v[28:29], off offset:3840
	v_add_co_u32_e32 v28, vcc, s10, v16
	s_mov_b32 s10, 0x593000
	s_nop 0
	v_addc_co_u32_e32 v29, vcc, 0, v17, vcc
	global_load_dword v50, v[28:29], off offset:2560
	v_add_co_u32_e32 v28, vcc, s10, v16
	s_mov_b32 s10, 0x596000
	s_nop 0
	v_addc_co_u32_e32 v29, vcc, 0, v17, vcc
	global_load_dword v51, v[28:29], off offset:1280
	v_add_co_u32_e32 v28, vcc, s10, v16
	s_mov_b32 s10, 0x598000
	s_nop 0
	v_addc_co_u32_e32 v29, vcc, 0, v17, vcc
	global_load_dword v52, v[28:29], off
	v_add_co_u32_e32 v28, vcc, s10, v16
	s_mov_b32 s10, 0x59b000
	s_nop 0
	v_addc_co_u32_e32 v29, vcc, 0, v17, vcc
	global_load_dword v53, v[28:29], off offset:2816
	v_add_co_u32_e32 v28, vcc, s10, v16
	s_mov_b32 s10, 0x59e000
	s_nop 0
	v_addc_co_u32_e32 v29, vcc, 0, v17, vcc
	global_load_dword v54, v[28:29], off offset:1536
	v_add_co_u32_e32 v28, vcc, s10, v16
	s_mov_b32 s10, 0x5a0000
	s_nop 0
	v_addc_co_u32_e32 v29, vcc, 0, v17, vcc
	global_load_dword v55, v[28:29], off offset:256
	v_add_co_u32_e32 v28, vcc, s10, v16
	s_mov_b32 s10, 0x5a3000
	s_nop 0
	v_addc_co_u32_e32 v29, vcc, 0, v17, vcc
	global_load_dword v56, v[28:29], off offset:3072
	v_add_co_u32_e32 v28, vcc, s10, v16
	s_mov_b32 s10, 0x5a6000
	s_nop 0
	v_addc_co_u32_e32 v29, vcc, 0, v17, vcc
	global_load_dword v57, v[28:29], off offset:1792
	v_add_co_u32_e32 v28, vcc, s10, v16
	s_mov_b32 s10, 0x5a8000
	s_nop 0
	v_addc_co_u32_e32 v29, vcc, 0, v17, vcc
	global_load_dword v58, v[28:29], off offset:512
	v_add_co_u32_e32 v28, vcc, s10, v16
	s_mov_b32 s10, 0x5ab000
	s_nop 0
	v_addc_co_u32_e32 v29, vcc, 0, v17, vcc
	global_load_dword v59, v[28:29], off offset:3328
	v_add_co_u32_e32 v28, vcc, s10, v16
	s_mov_b32 s10, 0x5ae000
	s_nop 0
	v_addc_co_u32_e32 v29, vcc, 0, v17, vcc
	global_load_dword v60, v[28:29], off offset:2048
	v_add_co_u32_e32 v28, vcc, s10, v16
	s_mov_b32 s10, 0x5b0000
	s_nop 0
	v_addc_co_u32_e32 v29, vcc, 0, v17, vcc
	global_load_dword v61, v[28:29], off offset:768
	v_add_co_u32_e32 v28, vcc, s10, v16
	s_mov_b32 s10, 0x5b3000
	s_nop 0
	v_addc_co_u32_e32 v29, vcc, 0, v17, vcc
	v_add_co_u32_e32 v16, vcc, s10, v16
	global_load_dword v28, v[28:29], off offset:3584
	s_nop 0
	v_addc_co_u32_e32 v17, vcc, 0, v17, vcc
	global_load_dword v16, v[16:17], off offset:2304
	v_add_u32_e32 v17, 0x400, v18
	s_waitcnt vmcnt(30)
	ds_write2_b32 v18, v32, v33 offset1:66
	s_waitcnt vmcnt(28)
	ds_write2_b32 v18, v34, v35 offset0:132 offset1:198
	s_waitcnt vmcnt(26)
	ds_write2_b32 v17, v36, v37 offset0:8 offset1:74
	s_waitcnt vmcnt(24)
	ds_write2_b32 v17, v38, v39 offset0:140 offset1:206
	v_add_u32_e32 v17, 0x800, v18
	s_waitcnt vmcnt(22)
	ds_write2_b32 v17, v40, v41 offset0:16 offset1:82
	s_waitcnt vmcnt(20)
	ds_write2_b32 v17, v42, v43 offset0:148 offset1:214
	v_add_u32_e32 v17, 0xc00, v18
	s_waitcnt vmcnt(18)
	ds_write2_b32 v17, v44, v45 offset0:24 offset1:90
	s_waitcnt vmcnt(16)
	ds_write2_b32 v17, v46, v47 offset0:156 offset1:222
	v_add_u32_e32 v17, 0x1000, v18
	s_waitcnt vmcnt(14)
	ds_write2_b32 v17, v48, v49 offset0:32 offset1:98
	s_waitcnt vmcnt(12)
	ds_write2_b32 v17, v50, v51 offset0:164 offset1:230
	v_add_u32_e32 v17, 0x1400, v18
	s_waitcnt vmcnt(10)
	ds_write2_b32 v17, v52, v53 offset0:40 offset1:106
	s_waitcnt vmcnt(8)
	ds_write2_b32 v17, v54, v55 offset0:172 offset1:238
	v_add_u32_e32 v17, 0x1800, v18
	s_waitcnt vmcnt(6)
	ds_write2_b32 v17, v56, v57 offset0:48 offset1:114
	s_waitcnt vmcnt(4)
	ds_write2_b32 v17, v58, v59 offset0:180 offset1:246
	v_add_u32_e32 v17, 0x1c00, v18
	s_waitcnt vmcnt(2)
	ds_write2_b32 v17, v60, v61 offset0:56 offset1:122
	s_waitcnt vmcnt(0)
	ds_write2_b32 v17, v28, v16 offset0:188 offset1:254
	s_waitcnt lgkmcnt(0)
	ds_read2_b32 v[28:29], v21 offset1:33
	v_add_u16_e32 v34, 0x200, v31
	v_lshlrev_b32_e32 v156, 7, v30
	s_waitcnt lgkmcnt(0)
	v_cvt_pk_bf16_f32 v28, v28, v29
	ds_read2_b32 v[30:31], v21 offset0:66 offset1:99
	s_waitcnt lgkmcnt(0)
	v_cvt_pk_bf16_f32 v29, v30, v31
	ds_read2_b32 v[30:31], v21 offset0:132 offset1:165
	s_waitcnt lgkmcnt(0)
	v_cvt_pk_bf16_f32 v30, v30, v31
	ds_read2_b32 v[32:33], v21 offset0:198 offset1:231
	s_waitcnt lgkmcnt(0)
	v_cvt_pk_bf16_f32 v31, v32, v33
	v_or_b32_e32 v32, v19, v34
	v_lshl_add_u64 v[16:17], v[4:5], 0, v[156:157]
	v_lshlrev_b32_e32 v156, 11, v32
	v_lshl_add_u64 v[32:33], v[16:17], 0, v[156:157]
	global_store_dwordx4 v[32:33], v[28:31], off sc1
	ds_read2_b32 v[28:29], v21 offset0:8 offset1:41
	s_waitcnt lgkmcnt(0)
	v_cvt_pk_bf16_f32 v28, v28, v29
	ds_read2_b32 v[30:31], v21 offset0:74 offset1:107
	s_waitcnt lgkmcnt(0)
	v_cvt_pk_bf16_f32 v29, v30, v31
	ds_read2_b32 v[30:31], v21 offset0:140 offset1:173
	s_waitcnt lgkmcnt(0)
	v_cvt_pk_bf16_f32 v30, v30, v31
	ds_read2_b32 v[32:33], v21 offset0:206 offset1:239
	s_waitcnt lgkmcnt(0)
	v_cvt_pk_bf16_f32 v31, v32, v33
	v_or_b32_e32 v32, v22, v34
	v_lshlrev_b32_e32 v156, 11, v32
	v_lshl_add_u64 v[32:33], v[16:17], 0, v[156:157]
	global_store_dwordx4 v[32:33], v[28:31], off sc1
	ds_read2_b32 v[28:29], v21 offset0:16 offset1:49
	s_waitcnt lgkmcnt(0)
	v_cvt_pk_bf16_f32 v28, v28, v29
	ds_read2_b32 v[30:31], v21 offset0:82 offset1:115
	s_waitcnt lgkmcnt(0)
	v_cvt_pk_bf16_f32 v29, v30, v31
	ds_read2_b32 v[30:31], v21 offset0:148 offset1:181
	s_waitcnt lgkmcnt(0)
	v_cvt_pk_bf16_f32 v30, v30, v31
	ds_read2_b32 v[32:33], v21 offset0:214 offset1:247
	s_waitcnt lgkmcnt(0)
	v_cvt_pk_bf16_f32 v31, v32, v33
	v_or_b32_e32 v32, v23, v34
	v_lshlrev_b32_e32 v156, 11, v32
	v_lshl_add_u64 v[32:33], v[16:17], 0, v[156:157]
	global_store_dwordx4 v[32:33], v[28:31], off sc1
	ds_read2_b32 v[28:29], v21 offset0:24 offset1:57
	s_waitcnt lgkmcnt(0)
	v_cvt_pk_bf16_f32 v28, v28, v29
	ds_read2_b32 v[30:31], v21 offset0:90 offset1:123
	s_waitcnt lgkmcnt(0)
	v_cvt_pk_bf16_f32 v29, v30, v31
	ds_read2_b32 v[30:31], v21 offset0:156 offset1:189
	s_waitcnt lgkmcnt(0)
	v_cvt_pk_bf16_f32 v30, v30, v31
	ds_read2_b32 v[32:33], v21 offset0:222 offset1:255
	s_waitcnt lgkmcnt(0)
	v_cvt_pk_bf16_f32 v31, v32, v33
	v_or_b32_e32 v32, v24, v34
	v_lshlrev_b32_e32 v156, 11, v32
	v_lshl_add_u64 v[16:17], v[16:17], 0, v[156:157]
	global_store_dwordx4 v[16:17], v[28:31], off sc1
	s_waitcnt lgkmcnt(0)

.LBB0_536:
	s_andn2_saveexec_b64 s[6:7], s[48:49]
	s_cbranch_execz .LBB0_538
	s_load_dwordx2 s[24:25], s[0:1], 0xc0
	v_add_u32_e32 v16, 0x20e60, v27
	v_and_b32_e32 v28, 0x3e0, v26
	v_and_b32_e32 v29, 0x1ffc0, v16
	v_lshlrev_b32_e32 v156, 2, v28
	v_or_b32_e32 v30, v29, v15
	s_waitcnt lgkmcnt(0)
	v_lshl_add_u64 v[16:17], s[24:25], 0, v[156:157]
	v_lshlrev_b32_e32 v156, 2, v0
	v_lshl_add_u64 v[16:17], v[16:17], 0, v[156:157]
	v_lshlrev_b32_e32 v156, 12, v30
	v_lshl_add_u64 v[16:17], v[16:17], 0, v[156:157]
	v_add_co_u32_e32 v30, vcc, 0xb00000, v16
	v_lshlrev_b32_e32 v156, 1, v29
	s_nop 0
	v_addc_co_u32_e32 v31, vcc, 0, v17, vcc
	global_load_dword v32, v[30:31], off
	v_add_co_u32_e32 v30, vcc, 0xb02000, v16
	v_or_b32_e32 v29, v28, v19
	s_nop 0
	v_addc_co_u32_e32 v31, vcc, 0, v17, vcc
	global_load_dword v33, v[30:31], off
	v_add_co_u32_e32 v30, vcc, 0xb04000, v16
	v_mul_u32_u24_e32 v29, 0xb00, v29
	s_nop 0
	v_addc_co_u32_e32 v31, vcc, 0, v17, vcc
	global_load_dword v34, v[30:31], off
	v_add_co_u32_e32 v30, vcc, 0xb06000, v16
	s_nop 1
	v_addc_co_u32_e32 v31, vcc, 0, v17, vcc
	global_load_dword v35, v[30:31], off
	v_add_co_u32_e32 v30, vcc, 0xb08000, v16
	s_nop 1
	v_addc_co_u32_e32 v31, vcc, 0, v17, vcc
	global_load_dword v36, v[30:31], off
	v_add_co_u32_e32 v30, vcc, 0xb0a000, v16
	s_nop 1
	v_addc_co_u32_e32 v31, vcc, 0, v17, vcc
	global_load_dword v37, v[30:31], off
	v_add_co_u32_e32 v30, vcc, 0xb0c000, v16
	s_nop 1
	v_addc_co_u32_e32 v31, vcc, 0, v17, vcc
	global_load_dword v38, v[30:31], off
	v_add_co_u32_e32 v30, vcc, 0xb0e000, v16
	s_nop 1
	v_addc_co_u32_e32 v31, vcc, 0, v17, vcc
	global_load_dword v39, v[30:31], off
	v_add_co_u32_e32 v30, vcc, 0xb10000, v16
	s_nop 1
	v_addc_co_u32_e32 v31, vcc, 0, v17, vcc
	global_load_dword v40, v[30:31], off
	v_add_co_u32_e32 v30, vcc, 0xb12000, v16
	s_nop 1
	v_addc_co_u32_e32 v31, vcc, 0, v17, vcc
	global_load_dword v41, v[30:31], off
	v_add_co_u32_e32 v30, vcc, 0xb14000, v16
	s_nop 1
	v_addc_co_u32_e32 v31, vcc, 0, v17, vcc
	global_load_dword v42, v[30:31], off
	v_add_co_u32_e32 v30, vcc, 0xb16000, v16
	s_nop 1
	v_addc_co_u32_e32 v31, vcc, 0, v17, vcc
	global_load_dword v43, v[30:31], off
	v_add_co_u32_e32 v30, vcc, 0xb18000, v16
	s_nop 1
	v_addc_co_u32_e32 v31, vcc, 0, v17, vcc
	global_load_dword v44, v[30:31], off
	v_add_co_u32_e32 v30, vcc, 0xb1a000, v16
	s_nop 1
	v_addc_co_u32_e32 v31, vcc, 0, v17, vcc
	global_load_dword v45, v[30:31], off
	v_add_co_u32_e32 v30, vcc, 0xb1c000, v16
	s_nop 1
	v_addc_co_u32_e32 v31, vcc, 0, v17, vcc
	global_load_dword v46, v[30:31], off
	v_add_co_u32_e32 v30, vcc, 0xb1e000, v16
	s_nop 1
	v_addc_co_u32_e32 v31, vcc, 0, v17, vcc
	global_load_dword v47, v[30:31], off
	v_add_co_u32_e32 v30, vcc, 0xb20000, v16
	s_nop 1
	v_addc_co_u32_e32 v31, vcc, 0, v17, vcc
	global_load_dword v48, v[30:31], off
	v_add_co_u32_e32 v30, vcc, 0xb22000, v16
	s_nop 1
	v_addc_co_u32_e32 v31, vcc, 0, v17, vcc
	global_load_dword v49, v[30:31], off
	v_add_co_u32_e32 v30, vcc, 0xb24000, v16
	s_nop 1
	v_addc_co_u32_e32 v31, vcc, 0, v17, vcc
	global_load_dword v50, v[30:31], off
	v_add_co_u32_e32 v30, vcc, 0xb26000, v16
	s_nop 1
	v_addc_co_u32_e32 v31, vcc, 0, v17, vcc
	global_load_dword v51, v[30:31], off
	v_add_co_u32_e32 v30, vcc, 0xb28000, v16
	s_nop 1
	v_addc_co_u32_e32 v31, vcc, 0, v17, vcc
	global_load_dword v52, v[30:31], off
	v_add_co_u32_e32 v30, vcc, 0xb2a000, v16
	s_nop 1
	v_addc_co_u32_e32 v31, vcc, 0, v17, vcc
	global_load_dword v53, v[30:31], off
	v_add_co_u32_e32 v30, vcc, 0xb2c000, v16
	s_nop 1
	v_addc_co_u32_e32 v31, vcc, 0, v17, vcc
	global_load_dword v54, v[30:31], off
	v_add_co_u32_e32 v30, vcc, 0xb2e000, v16
	s_nop 1
	v_addc_co_u32_e32 v31, vcc, 0, v17, vcc
	global_load_dword v55, v[30:31], off
	v_add_co_u32_e32 v30, vcc, 0xb30000, v16
	s_nop 1
	v_addc_co_u32_e32 v31, vcc, 0, v17, vcc
	global_load_dword v56, v[30:31], off
	v_add_co_u32_e32 v30, vcc, 0xb32000, v16
	s_nop 1
	v_addc_co_u32_e32 v31, vcc, 0, v17, vcc
	global_load_dword v57, v[30:31], off
	v_add_co_u32_e32 v30, vcc, 0xb34000, v16
	s_nop 1
	v_addc_co_u32_e32 v31, vcc, 0, v17, vcc
	global_load_dword v58, v[30:31], off
	v_add_co_u32_e32 v30, vcc, 0xb36000, v16
	s_nop 1
	v_addc_co_u32_e32 v31, vcc, 0, v17, vcc
	global_load_dword v59, v[30:31], off
	v_add_co_u32_e32 v30, vcc, 0xb38000, v16
	s_nop 1
	v_addc_co_u32_e32 v31, vcc, 0, v17, vcc
	global_load_dword v60, v[30:31], off
	v_add_co_u32_e32 v30, vcc, 0xb3a000, v16
	s_nop 1
	v_addc_co_u32_e32 v31, vcc, 0, v17, vcc
	global_load_dword v61, v[30:31], off
	v_add_co_u32_e32 v30, vcc, 0xb3c000, v16
	s_nop 1
	v_addc_co_u32_e32 v31, vcc, 0, v17, vcc
	v_add_co_u32_e32 v16, vcc, 0xb3e000, v16
	global_load_dword v30, v[30:31], off
	s_nop 0
	v_addc_co_u32_e32 v17, vcc, 0, v17, vcc
	global_load_dword v16, v[16:17], off
	v_add_u32_e32 v17, 0x400, v18
	s_waitcnt vmcnt(30)
	ds_write2_b32 v18, v32, v33 offset1:66
	s_waitcnt vmcnt(28)
	ds_write2_b32 v18, v34, v35 offset0:132 offset1:198
	s_waitcnt vmcnt(26)
	ds_write2_b32 v17, v36, v37 offset0:8 offset1:74
	s_waitcnt vmcnt(24)
	ds_write2_b32 v17, v38, v39 offset0:140 offset1:206
	v_add_u32_e32 v17, 0x800, v18
	s_waitcnt vmcnt(22)
	ds_write2_b32 v17, v40, v41 offset0:16 offset1:82
	s_waitcnt vmcnt(20)
	ds_write2_b32 v17, v42, v43 offset0:148 offset1:214
	v_add_u32_e32 v17, 0xc00, v18
	s_waitcnt vmcnt(18)
	ds_write2_b32 v17, v44, v45 offset0:24 offset1:90
	s_waitcnt vmcnt(16)
	ds_write2_b32 v17, v46, v47 offset0:156 offset1:222
	v_add_u32_e32 v17, 0x1000, v18
	s_waitcnt vmcnt(14)
	ds_write2_b32 v17, v48, v49 offset0:32 offset1:98
	s_waitcnt vmcnt(12)
	ds_write2_b32 v17, v50, v51 offset0:164 offset1:230
	v_add_u32_e32 v17, 0x1400, v18
	s_waitcnt vmcnt(10)
	ds_write2_b32 v17, v52, v53 offset0:40 offset1:106
	s_waitcnt vmcnt(8)
	ds_write2_b32 v17, v54, v55 offset0:172 offset1:238
	v_add_u32_e32 v17, 0x1800, v18
	s_waitcnt vmcnt(6)
	ds_write2_b32 v17, v56, v57 offset0:48 offset1:114
	s_waitcnt vmcnt(4)
	ds_write2_b32 v17, v58, v59 offset0:180 offset1:246
	v_add_u32_e32 v17, 0x1c00, v18
	s_waitcnt vmcnt(2)
	ds_write2_b32 v17, v60, v61 offset0:56 offset1:122
	s_waitcnt vmcnt(0)
	ds_write2_b32 v17, v30, v16 offset0:188 offset1:254
	s_waitcnt lgkmcnt(0)
	ds_read2_b32 v[30:31], v21 offset1:33
	s_waitcnt lgkmcnt(0)
	v_cvt_pk_bf16_f32 v30, v30, v31
	ds_read2_b32 v[32:33], v21 offset0:66 offset1:99
	s_waitcnt lgkmcnt(0)
	v_cvt_pk_bf16_f32 v31, v32, v33
	ds_read2_b32 v[32:33], v21 offset0:132 offset1:165
	v_lshl_add_u64 v[16:17], v[6:7], 0, v[156:157]
	s_waitcnt lgkmcnt(0)
	v_cvt_pk_bf16_f32 v32, v32, v33
	ds_read2_b32 v[34:35], v21 offset0:198 offset1:231
	v_lshlrev_b32_e32 v156, 1, v29
	s_waitcnt lgkmcnt(0)
	v_cvt_pk_bf16_f32 v33, v34, v35
	v_lshl_add_u64 v[34:35], v[16:17], 0, v[156:157]
	global_store_dwordx4 v[34:35], v[30:33], off sc1
	ds_read2_b32 v[30:31], v21 offset0:8 offset1:41
	v_or_b32_e32 v29, v28, v22
	s_waitcnt lgkmcnt(0)
	v_cvt_pk_bf16_f32 v30, v30, v31
	ds_read2_b32 v[32:33], v21 offset0:74 offset1:107
	s_waitcnt lgkmcnt(0)
	v_cvt_pk_bf16_f32 v31, v32, v33
	ds_read2_b32 v[32:33], v21 offset0:140 offset1:173
	v_mul_u32_u24_e32 v29, 0xb00, v29
	s_waitcnt lgkmcnt(0)
	v_cvt_pk_bf16_f32 v32, v32, v33
	ds_read2_b32 v[34:35], v21 offset0:206 offset1:239
	v_lshlrev_b32_e32 v156, 1, v29
	s_waitcnt lgkmcnt(0)
	v_cvt_pk_bf16_f32 v33, v34, v35
	v_lshl_add_u64 v[34:35], v[16:17], 0, v[156:157]
	global_store_dwordx4 v[34:35], v[30:33], off sc1
	ds_read2_b32 v[30:31], v21 offset0:16 offset1:49
	v_or_b32_e32 v29, v28, v23
	s_waitcnt lgkmcnt(0)
	v_cvt_pk_bf16_f32 v30, v30, v31
	ds_read2_b32 v[32:33], v21 offset0:82 offset1:115
	s_waitcnt lgkmcnt(0)
	v_cvt_pk_bf16_f32 v31, v32, v33
	ds_read2_b32 v[32:33], v21 offset0:148 offset1:181
	v_mul_u32_u24_e32 v29, 0xb00, v29
	s_waitcnt lgkmcnt(0)
	v_cvt_pk_bf16_f32 v32, v32, v33
	ds_read2_b32 v[34:35], v21 offset0:214 offset1:247
	v_lshlrev_b32_e32 v156, 1, v29
	s_waitcnt lgkmcnt(0)
	v_cvt_pk_bf16_f32 v33, v34, v35
	v_lshl_add_u64 v[34:35], v[16:17], 0, v[156:157]
	v_or_b32_e32 v28, v28, v24
	global_store_dwordx4 v[34:35], v[30:33], off sc1
	ds_read2_b32 v[30:31], v21 offset0:24 offset1:57
	v_mul_u32_u24_e32 v28, 0xb00, v28
	s_waitcnt lgkmcnt(0)
	v_cvt_pk_bf16_f32 v30, v30, v31
	ds_read2_b32 v[32:33], v21 offset0:90 offset1:123
	v_lshlrev_b32_e32 v156, 1, v28
	s_waitcnt lgkmcnt(0)
	v_cvt_pk_bf16_f32 v31, v32, v33
	ds_read2_b32 v[32:33], v21 offset0:156 offset1:189
	v_lshl_add_u64 v[16:17], v[16:17], 0, v[156:157]
	s_waitcnt lgkmcnt(0)
	v_cvt_pk_bf16_f32 v32, v32, v33
	ds_read2_b32 v[34:35], v21 offset0:222 offset1:255
	s_waitcnt lgkmcnt(0)
	v_cvt_pk_bf16_f32 v33, v34, v35
	global_store_dwordx4 v[16:17], v[30:33], off sc1
	s_waitcnt lgkmcnt(0)

.LBB0_539:
	s_andn2_saveexec_b64 s[6:7], s[46:47]
	s_cbranch_execz .LBB0_541
	s_load_dwordx2 s[24:25], s[0:1], 0x40
	v_add_u32_e32 v16, 0x21960, v27
	v_and_b32_e32 v28, 0x3e0, v26
	v_and_b32_e32 v29, 0x1ffc0, v16
	v_lshlrev_b32_e32 v156, 2, v28
	v_or_b32_e32 v30, v29, v15
	s_waitcnt lgkmcnt(0)
	v_lshl_add_u64 v[16:17], s[24:25], 0, v[156:157]
	v_lshlrev_b32_e32 v156, 2, v0
	v_lshl_add_u64 v[16:17], v[16:17], 0, v[156:157]
	v_lshlrev_b32_e32 v156, 12, v30
	v_lshl_add_u64 v[16:17], v[16:17], 0, v[156:157]
	v_add_co_u32_e32 v30, vcc, 0xb00000, v16
	v_lshlrev_b32_e32 v156, 1, v29
	s_nop 0
	v_addc_co_u32_e32 v31, vcc, 0, v17, vcc
	global_load_dword v32, v[30:31], off
	v_add_co_u32_e32 v30, vcc, 0xb02000, v16
	v_or_b32_e32 v29, v28, v19
	s_nop 0
	v_addc_co_u32_e32 v31, vcc, 0, v17, vcc
	global_load_dword v33, v[30:31], off
	v_add_co_u32_e32 v30, vcc, 0xb04000, v16
	v_mul_u32_u24_e32 v29, 0xb00, v29
	s_nop 0
	v_addc_co_u32_e32 v31, vcc, 0, v17, vcc
	global_load_dword v34, v[30:31], off
	v_add_co_u32_e32 v30, vcc, 0xb06000, v16
	s_nop 1
	v_addc_co_u32_e32 v31, vcc, 0, v17, vcc
	global_load_dword v35, v[30:31], off
	v_add_co_u32_e32 v30, vcc, 0xb08000, v16
	s_nop 1
	v_addc_co_u32_e32 v31, vcc, 0, v17, vcc
	global_load_dword v36, v[30:31], off
	v_add_co_u32_e32 v30, vcc, 0xb0a000, v16
	s_nop 1
	v_addc_co_u32_e32 v31, vcc, 0, v17, vcc
	global_load_dword v37, v[30:31], off
	v_add_co_u32_e32 v30, vcc, 0xb0c000, v16
	s_nop 1
	v_addc_co_u32_e32 v31, vcc, 0, v17, vcc
	global_load_dword v38, v[30:31], off
	v_add_co_u32_e32 v30, vcc, 0xb0e000, v16
	s_nop 1
	v_addc_co_u32_e32 v31, vcc, 0, v17, vcc
	global_load_dword v39, v[30:31], off
	v_add_co_u32_e32 v30, vcc, 0xb10000, v16
	s_nop 1
	v_addc_co_u32_e32 v31, vcc, 0, v17, vcc
	global_load_dword v40, v[30:31], off
	v_add_co_u32_e32 v30, vcc, 0xb12000, v16
	s_nop 1
	v_addc_co_u32_e32 v31, vcc, 0, v17, vcc
	global_load_dword v41, v[30:31], off
	v_add_co_u32_e32 v30, vcc, 0xb14000, v16
	s_nop 1
	v_addc_co_u32_e32 v31, vcc, 0, v17, vcc
	global_load_dword v42, v[30:31], off
	v_add_co_u32_e32 v30, vcc, 0xb16000, v16
	s_nop 1
	v_addc_co_u32_e32 v31, vcc, 0, v17, vcc
	global_load_dword v43, v[30:31], off
	v_add_co_u32_e32 v30, vcc, 0xb18000, v16
	s_nop 1
	v_addc_co_u32_e32 v31, vcc, 0, v17, vcc
	global_load_dword v44, v[30:31], off
	v_add_co_u32_e32 v30, vcc, 0xb1a000, v16
	s_nop 1
	v_addc_co_u32_e32 v31, vcc, 0, v17, vcc
	global_load_dword v45, v[30:31], off
	v_add_co_u32_e32 v30, vcc, 0xb1c000, v16
	s_nop 1
	v_addc_co_u32_e32 v31, vcc, 0, v17, vcc
	global_load_dword v46, v[30:31], off
	v_add_co_u32_e32 v30, vcc, 0xb1e000, v16
	s_nop 1
	v_addc_co_u32_e32 v31, vcc, 0, v17, vcc
	global_load_dword v47, v[30:31], off
	v_add_co_u32_e32 v30, vcc, 0xb20000, v16
	s_nop 1
	v_addc_co_u32_e32 v31, vcc, 0, v17, vcc
	global_load_dword v48, v[30:31], off
	v_add_co_u32_e32 v30, vcc, 0xb22000, v16
	s_nop 1
	v_addc_co_u32_e32 v31, vcc, 0, v17, vcc
	global_load_dword v49, v[30:31], off
	v_add_co_u32_e32 v30, vcc, 0xb24000, v16
	s_nop 1
	v_addc_co_u32_e32 v31, vcc, 0, v17, vcc
	global_load_dword v50, v[30:31], off
	v_add_co_u32_e32 v30, vcc, 0xb26000, v16
	s_nop 1
	v_addc_co_u32_e32 v31, vcc, 0, v17, vcc
	global_load_dword v51, v[30:31], off
	v_add_co_u32_e32 v30, vcc, 0xb28000, v16
	s_nop 1
	v_addc_co_u32_e32 v31, vcc, 0, v17, vcc
	global_load_dword v52, v[30:31], off
	v_add_co_u32_e32 v30, vcc, 0xb2a000, v16
	s_nop 1
	v_addc_co_u32_e32 v31, vcc, 0, v17, vcc
	global_load_dword v53, v[30:31], off
	v_add_co_u32_e32 v30, vcc, 0xb2c000, v16
	s_nop 1
	v_addc_co_u32_e32 v31, vcc, 0, v17, vcc
	global_load_dword v54, v[30:31], off
	v_add_co_u32_e32 v30, vcc, 0xb2e000, v16
	s_nop 1
	v_addc_co_u32_e32 v31, vcc, 0, v17, vcc
	global_load_dword v55, v[30:31], off
	v_add_co_u32_e32 v30, vcc, 0xb30000, v16
	s_nop 1
	v_addc_co_u32_e32 v31, vcc, 0, v17, vcc
	global_load_dword v56, v[30:31], off
	v_add_co_u32_e32 v30, vcc, 0xb32000, v16
	s_nop 1
	v_addc_co_u32_e32 v31, vcc, 0, v17, vcc
	global_load_dword v57, v[30:31], off
	v_add_co_u32_e32 v30, vcc, 0xb34000, v16
	s_nop 1
	v_addc_co_u32_e32 v31, vcc, 0, v17, vcc
	global_load_dword v58, v[30:31], off
	v_add_co_u32_e32 v30, vcc, 0xb36000, v16
	s_nop 1
	v_addc_co_u32_e32 v31, vcc, 0, v17, vcc
	global_load_dword v59, v[30:31], off
	v_add_co_u32_e32 v30, vcc, 0xb38000, v16
	s_nop 1
	v_addc_co_u32_e32 v31, vcc, 0, v17, vcc
	global_load_dword v60, v[30:31], off
	v_add_co_u32_e32 v30, vcc, 0xb3a000, v16
	s_nop 1
	v_addc_co_u32_e32 v31, vcc, 0, v17, vcc
	global_load_dword v61, v[30:31], off
	v_add_co_u32_e32 v30, vcc, 0xb3c000, v16
	s_nop 1
	v_addc_co_u32_e32 v31, vcc, 0, v17, vcc
	v_add_co_u32_e32 v16, vcc, 0xb3e000, v16
	global_load_dword v30, v[30:31], off
	s_nop 0
	v_addc_co_u32_e32 v17, vcc, 0, v17, vcc
	global_load_dword v16, v[16:17], off
	v_add_u32_e32 v17, 0x400, v18
	s_waitcnt vmcnt(30)
	ds_write2_b32 v18, v32, v33 offset1:66
	s_waitcnt vmcnt(28)
	ds_write2_b32 v18, v34, v35 offset0:132 offset1:198
	s_waitcnt vmcnt(26)
	ds_write2_b32 v17, v36, v37 offset0:8 offset1:74
	s_waitcnt vmcnt(24)
	ds_write2_b32 v17, v38, v39 offset0:140 offset1:206
	v_add_u32_e32 v17, 0x800, v18
	s_waitcnt vmcnt(22)
	ds_write2_b32 v17, v40, v41 offset0:16 offset1:82
	s_waitcnt vmcnt(20)
	ds_write2_b32 v17, v42, v43 offset0:148 offset1:214
	v_add_u32_e32 v17, 0xc00, v18
	s_waitcnt vmcnt(18)
	ds_write2_b32 v17, v44, v45 offset0:24 offset1:90
	s_waitcnt vmcnt(16)
	ds_write2_b32 v17, v46, v47 offset0:156 offset1:222
	v_add_u32_e32 v17, 0x1000, v18
	s_waitcnt vmcnt(14)
	ds_write2_b32 v17, v48, v49 offset0:32 offset1:98
	s_waitcnt vmcnt(12)
	ds_write2_b32 v17, v50, v51 offset0:164 offset1:230
	v_add_u32_e32 v17, 0x1400, v18
	s_waitcnt vmcnt(10)
	ds_write2_b32 v17, v52, v53 offset0:40 offset1:106
	s_waitcnt vmcnt(8)
	ds_write2_b32 v17, v54, v55 offset0:172 offset1:238
	v_add_u32_e32 v17, 0x1800, v18
	s_waitcnt vmcnt(6)
	ds_write2_b32 v17, v56, v57 offset0:48 offset1:114
	s_waitcnt vmcnt(4)
	ds_write2_b32 v17, v58, v59 offset0:180 offset1:246
	v_add_u32_e32 v17, 0x1c00, v18
	s_waitcnt vmcnt(2)
	ds_write2_b32 v17, v60, v61 offset0:56 offset1:122
	s_waitcnt vmcnt(0)
	ds_write2_b32 v17, v30, v16 offset0:188 offset1:254
	s_waitcnt lgkmcnt(0)
	ds_read2_b32 v[30:31], v21 offset1:33
	s_waitcnt lgkmcnt(0)
	v_cvt_pk_bf16_f32 v30, v30, v31
	ds_read2_b32 v[32:33], v21 offset0:66 offset1:99
	s_waitcnt lgkmcnt(0)
	v_cvt_pk_bf16_f32 v31, v32, v33
	ds_read2_b32 v[32:33], v21 offset0:132 offset1:165
	v_lshl_add_u64 v[16:17], v[8:9], 0, v[156:157]
	s_waitcnt lgkmcnt(0)
	v_cvt_pk_bf16_f32 v32, v32, v33
	ds_read2_b32 v[34:35], v21 offset0:198 offset1:231
	v_lshlrev_b32_e32 v156, 1, v29
	s_waitcnt lgkmcnt(0)
	v_cvt_pk_bf16_f32 v33, v34, v35
	v_lshl_add_u64 v[34:35], v[16:17], 0, v[156:157]
	global_store_dwordx4 v[34:35], v[30:33], off sc1
	ds_read2_b32 v[30:31], v21 offset0:8 offset1:41
	v_or_b32_e32 v29, v28, v22
	s_waitcnt lgkmcnt(0)
	v_cvt_pk_bf16_f32 v30, v30, v31
	ds_read2_b32 v[32:33], v21 offset0:74 offset1:107
	s_waitcnt lgkmcnt(0)
	v_cvt_pk_bf16_f32 v31, v32, v33
	ds_read2_b32 v[32:33], v21 offset0:140 offset1:173
	v_mul_u32_u24_e32 v29, 0xb00, v29
	s_waitcnt lgkmcnt(0)
	v_cvt_pk_bf16_f32 v32, v32, v33
	ds_read2_b32 v[34:35], v21 offset0:206 offset1:239
	v_lshlrev_b32_e32 v156, 1, v29
	s_waitcnt lgkmcnt(0)
	v_cvt_pk_bf16_f32 v33, v34, v35
	v_lshl_add_u64 v[34:35], v[16:17], 0, v[156:157]
	global_store_dwordx4 v[34:35], v[30:33], off sc1
	ds_read2_b32 v[30:31], v21 offset0:16 offset1:49
	v_or_b32_e32 v29, v28, v23
	s_waitcnt lgkmcnt(0)
	v_cvt_pk_bf16_f32 v30, v30, v31
	ds_read2_b32 v[32:33], v21 offset0:82 offset1:115
	s_waitcnt lgkmcnt(0)
	v_cvt_pk_bf16_f32 v31, v32, v33
	ds_read2_b32 v[32:33], v21 offset0:148 offset1:181
	v_mul_u32_u24_e32 v29, 0xb00, v29
	s_waitcnt lgkmcnt(0)
	v_cvt_pk_bf16_f32 v32, v32, v33
	ds_read2_b32 v[34:35], v21 offset0:214 offset1:247
	v_lshlrev_b32_e32 v156, 1, v29
	s_waitcnt lgkmcnt(0)
	v_cvt_pk_bf16_f32 v33, v34, v35
	v_lshl_add_u64 v[34:35], v[16:17], 0, v[156:157]
	v_or_b32_e32 v28, v28, v24
	global_store_dwordx4 v[34:35], v[30:33], off sc1
	ds_read2_b32 v[30:31], v21 offset0:24 offset1:57
	v_mul_u32_u24_e32 v28, 0xb00, v28
	s_waitcnt lgkmcnt(0)
	v_cvt_pk_bf16_f32 v30, v30, v31
	ds_read2_b32 v[32:33], v21 offset0:90 offset1:123
	v_lshlrev_b32_e32 v156, 1, v28
	s_waitcnt lgkmcnt(0)
	v_cvt_pk_bf16_f32 v31, v32, v33
	ds_read2_b32 v[32:33], v21 offset0:156 offset1:189
	v_lshl_add_u64 v[16:17], v[16:17], 0, v[156:157]
	s_waitcnt lgkmcnt(0)
	v_cvt_pk_bf16_f32 v32, v32, v33
	ds_read2_b32 v[34:35], v21 offset0:222 offset1:255
	s_waitcnt lgkmcnt(0)
	v_cvt_pk_bf16_f32 v33, v34, v35
	global_store_dwordx4 v[16:17], v[30:33], off sc1
	s_waitcnt lgkmcnt(0)

.LBB0_542:
	s_andn2_saveexec_b64 s[6:7], s[42:43]
	s_cbranch_execz .LBB0_544
	v_add_u16_e32 v16, 0xf500, v1
	v_mul_u32_u24_e32 v17, 0xba2f, v16
	s_load_dwordx2 s[24:25], s[0:1], 0xb8
	v_lshrrev_b32_e32 v17, 23, v17
	v_mul_lo_u16_e32 v28, 0xb0, v17
	v_sub_u16_e32 v34, v16, v28
	v_lshlrev_b16_e32 v30, 6, v17
	v_lshlrev_b16_e32 v35, 5, v34
	v_or_b32_e32 v28, v15, v30
	v_lshlrev_b32_e32 v156, 2, v35
	s_waitcnt lgkmcnt(0)
	v_lshl_add_u64 v[16:17], s[24:25], 0, v[156:157]
	v_lshlrev_b32_e32 v156, 2, v0
	v_mul_u32_u24_e32 v28, 0x1600, v28
	v_lshl_add_u64 v[16:17], v[16:17], 0, v[156:157]
	v_lshlrev_b32_e32 v156, 2, v28
	v_lshl_add_u64 v[16:17], v[16:17], 0, v[156:157]
	s_mov_b32 s10, 0x1600000
	v_add_co_u32_e32 v28, vcc, s10, v16
	s_mov_b32 s10, 0x160b000
	s_nop 0
	v_addc_co_u32_e32 v29, vcc, 0, v17, vcc
	global_load_dword v31, v[28:29], off
	v_add_co_u32_e32 v28, vcc, s10, v16
	s_mov_b32 s10, 0x1616000
	s_nop 0
	v_addc_co_u32_e32 v29, vcc, 0, v17, vcc
	global_load_dword v32, v[28:29], off
	v_add_co_u32_e32 v28, vcc, s10, v16
	s_mov_b32 s10, 0x1621000
	s_nop 0
	v_addc_co_u32_e32 v29, vcc, 0, v17, vcc
	global_load_dword v33, v[28:29], off
	v_add_co_u32_e32 v28, vcc, s10, v16
	s_mov_b32 s10, 0x162c000
	s_nop 0
	v_addc_co_u32_e32 v29, vcc, 0, v17, vcc
	global_load_dword v36, v[28:29], off
	v_add_co_u32_e32 v28, vcc, s10, v16
	s_mov_b32 s10, 0x1637000
	s_nop 0
	v_addc_co_u32_e32 v29, vcc, 0, v17, vcc
	global_load_dword v37, v[28:29], off
	v_add_co_u32_e32 v28, vcc, s10, v16
	s_mov_b32 s10, 0x1642000
	s_nop 0
	v_addc_co_u32_e32 v29, vcc, 0, v17, vcc
	global_load_dword v38, v[28:29], off
	v_add_co_u32_e32 v28, vcc, s10, v16
	s_mov_b32 s10, 0x164d000
	s_nop 0
	v_addc_co_u32_e32 v29, vcc, 0, v17, vcc
	global_load_dword v39, v[28:29], off
	v_add_co_u32_e32 v28, vcc, s10, v16
	s_mov_b32 s10, 0x1658000
	s_nop 0
	v_addc_co_u32_e32 v29, vcc, 0, v17, vcc
	global_load_dword v40, v[28:29], off
	v_add_co_u32_e32 v28, vcc, s10, v16
	s_mov_b32 s10, 0x1663000
	s_nop 0
	v_addc_co_u32_e32 v29, vcc, 0, v17, vcc
	global_load_dword v41, v[28:29], off
	v_add_co_u32_e32 v28, vcc, s10, v16
	s_mov_b32 s10, 0x166e000
	s_nop 0
	v_addc_co_u32_e32 v29, vcc, 0, v17, vcc
	global_load_dword v42, v[28:29], off
	v_add_co_u32_e32 v28, vcc, s10, v16
	s_mov_b32 s10, 0x1679000
	s_nop 0
	v_addc_co_u32_e32 v29, vcc, 0, v17, vcc
	global_load_dword v43, v[28:29], off
	v_add_co_u32_e32 v28, vcc, s10, v16
	s_mov_b32 s10, 0x1684000
	s_nop 0
	v_addc_co_u32_e32 v29, vcc, 0, v17, vcc
	global_load_dword v44, v[28:29], off
	v_add_co_u32_e32 v28, vcc, s10, v16
	s_mov_b32 s10, 0x168f000
	s_nop 0
	v_addc_co_u32_e32 v29, vcc, 0, v17, vcc
	global_load_dword v45, v[28:29], off
	v_add_co_u32_e32 v28, vcc, s10, v16
	s_mov_b32 s10, 0x169a000
	s_nop 0
	v_addc_co_u32_e32 v29, vcc, 0, v17, vcc
	global_load_dword v46, v[28:29], off
	v_add_co_u32_e32 v28, vcc, s10, v16
	s_mov_b32 s10, 0x16a5000
	s_nop 0
	v_addc_co_u32_e32 v29, vcc, 0, v17, vcc
	global_load_dword v47, v[28:29], off
	v_add_co_u32_e32 v28, vcc, s10, v16
	s_mov_b32 s10, 0x16b0000
	s_nop 0
	v_addc_co_u32_e32 v29, vcc, 0, v17, vcc
	global_load_dword v48, v[28:29], off
	v_add_co_u32_e32 v28, vcc, s10, v16
	s_mov_b32 s10, 0x16bb000
	s_nop 0
	v_addc_co_u32_e32 v29, vcc, 0, v17, vcc
	global_load_dword v49, v[28:29], off
	v_add_co_u32_e32 v28, vcc, s10, v16
	s_mov_b32 s10, 0x16c6000
	s_nop 0
	v_addc_co_u32_e32 v29, vcc, 0, v17, vcc
	global_load_dword v50, v[28:29], off
	v_add_co_u32_e32 v28, vcc, s10, v16
	s_mov_b32 s10, 0x16d1000
	s_nop 0
	v_addc_co_u32_e32 v29, vcc, 0, v17, vcc
	global_load_dword v51, v[28:29], off
	v_add_co_u32_e32 v28, vcc, s10, v16
	s_mov_b32 s10, 0x16dc000
	s_nop 0
	v_addc_co_u32_e32 v29, vcc, 0, v17, vcc
	global_load_dword v52, v[28:29], off
	v_add_co_u32_e32 v28, vcc, s10, v16
	s_mov_b32 s10, 0x16e7000
	s_nop 0
	v_addc_co_u32_e32 v29, vcc, 0, v17, vcc
	global_load_dword v53, v[28:29], off
	v_add_co_u32_e32 v28, vcc, s10, v16
	s_mov_b32 s10, 0x16f2000
	s_nop 0
	v_addc_co_u32_e32 v29, vcc, 0, v17, vcc
	global_load_dword v54, v[28:29], off
	v_add_co_u32_e32 v28, vcc, s10, v16
	s_mov_b32 s10, 0x16fd000
	s_nop 0
	v_addc_co_u32_e32 v29, vcc, 0, v17, vcc
	global_load_dword v55, v[28:29], off
	v_add_co_u32_e32 v28, vcc, s10, v16
	s_mov_b32 s10, 0x1708000
	s_nop 0
	v_addc_co_u32_e32 v29, vcc, 0, v17, vcc
	global_load_dword v56, v[28:29], off
	v_add_co_u32_e32 v28, vcc, s10, v16
	s_mov_b32 s10, 0x1713000
	s_nop 0
	v_addc_co_u32_e32 v29, vcc, 0, v17, vcc
	global_load_dword v57, v[28:29], off
	v_add_co_u32_e32 v28, vcc, s10, v16
	s_mov_b32 s10, 0x171e000
	s_nop 0
	v_addc_co_u32_e32 v29, vcc, 0, v17, vcc
	global_load_dword v58, v[28:29], off
	v_add_co_u32_e32 v28, vcc, s10, v16
	s_mov_b32 s10, 0x1729000
	s_nop 0
	v_addc_co_u32_e32 v29, vcc, 0, v17, vcc
	global_load_dword v59, v[28:29], off
	v_add_co_u32_e32 v28, vcc, s10, v16
	s_mov_b32 s10, 0x1734000
	s_nop 0
	v_addc_co_u32_e32 v29, vcc, 0, v17, vcc
	global_load_dword v60, v[28:29], off
	v_add_co_u32_e32 v28, vcc, s10, v16
	s_mov_b32 s10, 0x173f000
	s_nop 0
	v_addc_co_u32_e32 v29, vcc, 0, v17, vcc
	global_load_dword v61, v[28:29], off
	v_add_co_u32_e32 v28, vcc, s10, v16
	s_mov_b32 s10, 0x174a000
	s_nop 0
	v_addc_co_u32_e32 v29, vcc, 0, v17, vcc
	global_load_dword v62, v[28:29], off
	v_add_co_u32_e32 v28, vcc, s10, v16
	s_mov_b32 s10, 0x1755000
	s_nop 0
	v_addc_co_u32_e32 v29, vcc, 0, v17, vcc
	v_add_co_u32_e32 v16, vcc, s10, v16
	global_load_dword v28, v[28:29], off
	s_nop 0
	v_addc_co_u32_e32 v17, vcc, 0, v17, vcc
	global_load_dword v16, v[16:17], off
	v_add_u32_e32 v17, 0x400, v18
	s_waitcnt vmcnt(30)
	ds_write2_b32 v18, v31, v32 offset1:66
	s_waitcnt vmcnt(28)
	ds_write2_b32 v18, v33, v36 offset0:132 offset1:198
	s_waitcnt vmcnt(26)
	ds_write2_b32 v17, v37, v38 offset0:8 offset1:74
	s_waitcnt vmcnt(24)
	ds_write2_b32 v17, v39, v40 offset0:140 offset1:206
	v_add_u32_e32 v17, 0x800, v18
	s_waitcnt vmcnt(22)
	ds_write2_b32 v17, v41, v42 offset0:16 offset1:82
	s_waitcnt vmcnt(20)
	ds_write2_b32 v17, v43, v44 offset0:148 offset1:214
	v_add_u32_e32 v17, 0xc00, v18
	s_waitcnt vmcnt(18)
	ds_write2_b32 v17, v45, v46 offset0:24 offset1:90
	s_waitcnt vmcnt(16)
	ds_write2_b32 v17, v47, v48 offset0:156 offset1:222
	v_add_u32_e32 v17, 0x1000, v18
	s_waitcnt vmcnt(14)
	ds_write2_b32 v17, v49, v50 offset0:32 offset1:98
	s_waitcnt vmcnt(12)
	ds_write2_b32 v17, v51, v52 offset0:164 offset1:230
	v_add_u32_e32 v17, 0x1400, v18
	s_waitcnt vmcnt(10)
	ds_write2_b32 v17, v53, v54 offset0:40 offset1:106
	s_waitcnt vmcnt(8)
	ds_write2_b32 v17, v55, v56 offset0:172 offset1:238
	v_add_u32_e32 v17, 0x1800, v18
	s_waitcnt vmcnt(6)
	ds_write2_b32 v17, v57, v58 offset0:48 offset1:114
	s_waitcnt vmcnt(4)
	ds_write2_b32 v17, v59, v60 offset0:180 offset1:246
	v_add_u32_e32 v17, 0x1c00, v18
	s_waitcnt vmcnt(2)
	ds_write2_b32 v17, v61, v62 offset0:56 offset1:122
	s_waitcnt vmcnt(0)
	ds_write2_b32 v17, v28, v16 offset0:188 offset1:254
	s_waitcnt lgkmcnt(0)
	ds_read2_b32 v[28:29], v21 offset1:33
	v_lshlrev_b32_e32 v156, 1, v30
	s_waitcnt lgkmcnt(0)
	v_cvt_pk_bf16_f32 v28, v28, v29
	ds_read2_b32 v[30:31], v21 offset0:66 offset1:99
	s_waitcnt lgkmcnt(0)
	v_cvt_pk_bf16_f32 v29, v30, v31
	ds_read2_b32 v[30:31], v21 offset0:132 offset1:165
	s_movk_i32 s10, 0x57
	s_waitcnt lgkmcnt(0)
	v_cvt_pk_bf16_f32 v30, v30, v31
	ds_read2_b32 v[32:33], v21 offset0:198 offset1:231
	v_cmp_lt_u16_e32 vcc, s10, v34
	s_waitcnt lgkmcnt(0)
	v_cvt_pk_bf16_f32 v31, v32, v33
	s_movk_i32 s10, 0x63
	v_bitop3_b32 v38, v19, s10, v35 bitop3:0xc8
	v_cndmask_b32_e32 v32, 0, v210, vcc
	v_add_lshl_u32 v32, v32, v35, 1
	v_cndmask_b32_e32 v37, 0, v211, vcc
	v_and_b32_e32 v36, 0xffffff00, v32
	v_or_b32_e32 v32, v37, v25
	v_or3_b32 v32, v32, v38, v36
	v_ashrrev_i32_e32 v33, 31, v32
	v_lshl_add_u64 v[16:17], v[10:11], 0, v[156:157]
	v_lshlrev_b64 v[34:35], 11, v[32:33]
	v_lshl_add_u64 v[34:35], v[16:17], 0, v[34:35]
	global_store_dwordx4 v[34:35], v[28:31], off sc1
	ds_read2_b32 v[28:29], v21 offset0:8 offset1:41
	s_waitcnt lgkmcnt(0)
	v_cvt_pk_bf16_f32 v28, v28, v29
	ds_read2_b32 v[30:31], v21 offset0:74 offset1:107
	s_waitcnt lgkmcnt(0)
	v_cvt_pk_bf16_f32 v29, v30, v31
	ds_read2_b32 v[30:31], v21 offset0:140 offset1:173
	s_waitcnt lgkmcnt(0)
	v_cvt_pk_bf16_f32 v30, v30, v31
	ds_read2_b32 v[34:35], v21 offset0:206 offset1:239
	s_waitcnt lgkmcnt(0)
	v_cvt_pk_bf16_f32 v31, v34, v35
	v_or_b32_e32 v34, 4, v32
	v_ashrrev_i32_e32 v35, 31, v34
	v_lshlrev_b64 v[34:35], 11, v[34:35]
	v_lshl_add_u64 v[34:35], v[16:17], 0, v[34:35]
	v_or_b32_e32 v32, 8, v32
	global_store_dwordx4 v[34:35], v[28:31], off sc1
	ds_read2_b32 v[28:29], v21 offset0:16 offset1:49
	v_ashrrev_i32_e32 v33, 31, v32
	s_waitcnt lgkmcnt(0)
	v_cvt_pk_bf16_f32 v28, v28, v29
	ds_read2_b32 v[30:31], v21 offset0:82 offset1:115
	v_lshlrev_b64 v[32:33], 11, v[32:33]
	s_waitcnt lgkmcnt(0)
	v_cvt_pk_bf16_f32 v29, v30, v31
	ds_read2_b32 v[30:31], v21 offset0:148 offset1:181
	v_lshl_add_u64 v[32:33], v[16:17], 0, v[32:33]
	s_waitcnt lgkmcnt(0)
	v_cvt_pk_bf16_f32 v30, v30, v31
	ds_read2_b32 v[34:35], v21 offset0:214 offset1:247
	s_waitcnt lgkmcnt(0)
	v_cvt_pk_bf16_f32 v31, v34, v35
	global_store_dwordx4 v[32:33], v[28:31], off sc1
	ds_read2_b32 v[28:29], v21 offset0:24 offset1:57
	s_waitcnt lgkmcnt(0)
	v_cvt_pk_bf16_f32 v28, v28, v29
	ds_read2_b32 v[30:31], v21 offset0:90 offset1:123
	s_waitcnt lgkmcnt(0)
	v_cvt_pk_bf16_f32 v29, v30, v31
	ds_read2_b32 v[30:31], v21 offset0:156 offset1:189
	s_waitcnt lgkmcnt(0)
	v_cvt_pk_bf16_f32 v30, v30, v31
	ds_read2_b32 v[32:33], v21 offset0:222 offset1:255
	s_waitcnt lgkmcnt(0)
	v_cvt_pk_bf16_f32 v31, v32, v33
	v_or3_b32 v32, v20, v37, v38
	v_or3_b32 v32, v32, v36, 12
	v_ashrrev_i32_e32 v33, 31, v32
	v_lshlrev_b64 v[32:33], 11, v[32:33]
	v_lshl_add_u64 v[16:17], v[16:17], 0, v[32:33]
	global_store_dwordx4 v[16:17], v[28:31], off sc1
	s_waitcnt lgkmcnt(0)

.LBB0_545:
	s_andn2_saveexec_b64 s[6:7], s[40:41]
	s_cbranch_execz .LBB0_526
	s_mov_b32 s10, 0x2e8ba2e9
	v_mul_hi_i32 v16, v1, s10
	s_load_dwordx2 s[24:25], s[0:1], 0x38
	v_lshrrev_b32_e32 v17, 31, v16
	v_ashrrev_i32_e32 v16, 5, v16
	v_add_u32_e32 v34, v16, v17
	s_movk_i32 s10, 0xea00
	v_mul_lo_u32 v35, v34, s10
	v_add_u32_e32 v28, v26, v35
	v_ashrrev_i32_e32 v29, 31, v28
	s_waitcnt lgkmcnt(0)
	v_lshl_add_u64 v[28:29], v[28:29], 2, s[24:25]
	v_lshlrev_b32_e32 v156, 2, v0
	v_lshlrev_b32_e32 v16, 6, v34
	v_lshl_add_u64 v[28:29], v[28:29], 0, v[156:157]
	s_mov_b64 s[24:25], 0x1600000
	v_or_b32_e32 v17, v16, v15
	v_lshl_add_u64 v[28:29], v[28:29], 0, s[24:25]
	v_mad_i64_i32 v[30:31], s[24:25], v17, s75, v[28:29]
	global_load_dword v32, v[30:31], off
	v_or_b32_e32 v30, 2, v17
	v_mad_i64_i32 v[30:31], s[24:25], v30, s75, v[28:29]
	global_load_dword v33, v[30:31], off
	v_or_b32_e32 v30, 4, v17
	v_mad_i64_i32 v[30:31], s[24:25], v30, s75, v[28:29]
	global_load_dword v36, v[30:31], off
	v_or_b32_e32 v30, 6, v17
	v_mad_i64_i32 v[30:31], s[24:25], v30, s75, v[28:29]
	global_load_dword v37, v[30:31], off
	v_or_b32_e32 v30, 8, v17
	v_mad_i64_i32 v[30:31], s[24:25], v30, s75, v[28:29]
	global_load_dword v38, v[30:31], off
	v_or_b32_e32 v30, 10, v17
	v_mad_i64_i32 v[30:31], s[24:25], v30, s75, v[28:29]
	global_load_dword v39, v[30:31], off
	v_or_b32_e32 v30, 12, v17
	v_mad_i64_i32 v[30:31], s[24:25], v30, s75, v[28:29]
	global_load_dword v40, v[30:31], off
	v_or_b32_e32 v30, 14, v17
	v_mad_i64_i32 v[30:31], s[24:25], v30, s75, v[28:29]
	global_load_dword v41, v[30:31], off
	v_or_b32_e32 v30, 16, v17
	v_mad_i64_i32 v[30:31], s[24:25], v30, s75, v[28:29]
	global_load_dword v42, v[30:31], off
	v_or_b32_e32 v30, 18, v17
	v_mad_i64_i32 v[30:31], s[24:25], v30, s75, v[28:29]
	global_load_dword v43, v[30:31], off
	v_or_b32_e32 v30, 20, v17
	v_mad_i64_i32 v[30:31], s[24:25], v30, s75, v[28:29]
	global_load_dword v44, v[30:31], off
	v_or_b32_e32 v30, 22, v17
	v_mad_i64_i32 v[30:31], s[24:25], v30, s75, v[28:29]
	global_load_dword v45, v[30:31], off
	v_or_b32_e32 v30, 24, v17
	v_mad_i64_i32 v[30:31], s[24:25], v30, s75, v[28:29]
	global_load_dword v46, v[30:31], off
	v_or_b32_e32 v30, 26, v17
	v_mad_i64_i32 v[30:31], s[24:25], v30, s75, v[28:29]
	global_load_dword v47, v[30:31], off
	v_or_b32_e32 v30, 28, v17
	v_mad_i64_i32 v[30:31], s[24:25], v30, s75, v[28:29]
	global_load_dword v48, v[30:31], off
	v_or_b32_e32 v30, 30, v17
	v_mad_i64_i32 v[30:31], s[24:25], v30, s75, v[28:29]
	global_load_dword v49, v[30:31], off
	v_or_b32_e32 v30, 32, v17
	v_mad_i64_i32 v[30:31], s[24:25], v30, s75, v[28:29]
	global_load_dword v50, v[30:31], off
	v_or_b32_e32 v30, 34, v17
	v_mad_i64_i32 v[30:31], s[24:25], v30, s75, v[28:29]
	global_load_dword v51, v[30:31], off
	v_or_b32_e32 v30, 36, v17
	v_mad_i64_i32 v[30:31], s[24:25], v30, s75, v[28:29]
	global_load_dword v52, v[30:31], off
	v_or_b32_e32 v30, 38, v17
	v_mad_i64_i32 v[30:31], s[24:25], v30, s75, v[28:29]
	global_load_dword v53, v[30:31], off
	v_or_b32_e32 v30, 40, v17
	v_mad_i64_i32 v[30:31], s[24:25], v30, s75, v[28:29]
	global_load_dword v54, v[30:31], off
	v_or_b32_e32 v30, 42, v17
	v_mad_i64_i32 v[30:31], s[24:25], v30, s75, v[28:29]
	global_load_dword v55, v[30:31], off
	v_or_b32_e32 v30, 44, v17
	v_mad_i64_i32 v[30:31], s[24:25], v30, s75, v[28:29]
	global_load_dword v56, v[30:31], off
	v_or_b32_e32 v30, 46, v17
	v_mad_i64_i32 v[30:31], s[24:25], v30, s75, v[28:29]
	global_load_dword v57, v[30:31], off
	v_or_b32_e32 v30, 48, v17
	v_mad_i64_i32 v[30:31], s[24:25], v30, s75, v[28:29]
	global_load_dword v58, v[30:31], off
	v_or_b32_e32 v30, 50, v17
	v_mad_i64_i32 v[30:31], s[24:25], v30, s75, v[28:29]
	global_load_dword v59, v[30:31], off
	v_or_b32_e32 v30, 52, v17
	v_mad_i64_i32 v[30:31], s[24:25], v30, s75, v[28:29]
	global_load_dword v60, v[30:31], off
	v_or_b32_e32 v30, 54, v17
	v_mad_i64_i32 v[30:31], s[24:25], v30, s75, v[28:29]
	global_load_dword v61, v[30:31], off
	v_or_b32_e32 v30, 56, v17
	v_mad_i64_i32 v[30:31], s[24:25], v30, s75, v[28:29]
	global_load_dword v62, v[30:31], off
	v_or_b32_e32 v30, 58, v17
	v_mad_i64_i32 v[30:31], s[24:25], v30, s75, v[28:29]
	global_load_dword v63, v[30:31], off
	v_or_b32_e32 v30, 60, v17
	v_or_b32_e32 v17, 62, v17
	v_mad_i64_i32 v[30:31], s[24:25], v30, s75, v[28:29]
	v_mad_i64_i32 v[28:29], s[24:25], v17, s75, v[28:29]
	global_load_dword v30, v[30:31], off
	s_movk_i32 s10, 0xa800
	global_load_dword v17, v[28:29], off
	v_add_u32_e32 v28, 0x400, v18
	s_waitcnt vmcnt(30)
	ds_write2_b32 v18, v32, v33 offset1:66
	s_waitcnt vmcnt(28)
	ds_write2_b32 v18, v36, v37 offset0:132 offset1:198
	s_waitcnt vmcnt(26)
	ds_write2_b32 v28, v38, v39 offset0:8 offset1:74
	s_waitcnt vmcnt(24)
	ds_write2_b32 v28, v40, v41 offset0:140 offset1:206
	v_add_u32_e32 v28, 0x800, v18
	s_waitcnt vmcnt(22)
	ds_write2_b32 v28, v42, v43 offset0:16 offset1:82
	s_waitcnt vmcnt(20)
	ds_write2_b32 v28, v44, v45 offset0:148 offset1:214
	v_add_u32_e32 v28, 0xc00, v18
	s_waitcnt vmcnt(18)
	ds_write2_b32 v28, v46, v47 offset0:24 offset1:90
	s_waitcnt vmcnt(16)
	ds_write2_b32 v28, v48, v49 offset0:156 offset1:222
	v_add_u32_e32 v28, 0x1000, v18
	s_waitcnt vmcnt(14)
	ds_write2_b32 v28, v50, v51 offset0:32 offset1:98
	s_waitcnt vmcnt(12)
	ds_write2_b32 v28, v52, v53 offset0:164 offset1:230
	v_add_u32_e32 v28, 0x1400, v18
	s_waitcnt vmcnt(10)
	ds_write2_b32 v28, v54, v55 offset0:40 offset1:106
	s_waitcnt vmcnt(8)
	ds_write2_b32 v28, v56, v57 offset0:172 offset1:238
	v_add_u32_e32 v28, 0x1800, v18
	s_waitcnt vmcnt(6)
	ds_write2_b32 v28, v58, v59 offset0:48 offset1:114
	s_waitcnt vmcnt(4)
	ds_write2_b32 v28, v60, v61 offset0:180 offset1:246
	v_add_u32_e32 v28, 0x1c00, v18
	s_waitcnt vmcnt(2)
	ds_write2_b32 v28, v62, v63 offset0:56 offset1:122
	s_waitcnt vmcnt(0)
	ds_write2_b32 v28, v30, v17 offset0:188 offset1:254
	s_waitcnt lgkmcnt(0)
	ds_read2_b32 v[28:29], v21 offset1:33
	s_waitcnt lgkmcnt(0)
	v_cvt_pk_bf16_f32 v28, v28, v29
	ds_read2_b32 v[30:31], v21 offset0:66 offset1:99
	v_add_u32_e32 v36, v19, v26
	s_waitcnt lgkmcnt(0)
	v_cvt_pk_bf16_f32 v29, v30, v31
	ds_read2_b32 v[30:31], v21 offset0:132 offset1:165
	v_add_u32_e32 v37, v36, v35
	s_waitcnt lgkmcnt(0)
	v_cvt_pk_bf16_f32 v30, v30, v31
	ds_read2_b32 v[32:33], v21 offset0:198 offset1:231
	v_cmp_lt_i32_e32 vcc, s22, v37
	s_waitcnt lgkmcnt(0)
	v_cvt_pk_bf16_f32 v31, v32, v33
	v_mul_lo_u32 v38, v34, s33
	v_ashrrev_i32_e32 v17, 31, v16
	v_cndmask_b32_e32 v32, 0, v210, vcc
	v_sub_u32_e32 v32, v32, v38
	v_add_lshl_u32 v32, v36, v32, 1
	v_and_b32_e32 v35, 0xffffff00, v32
	v_cndmask_b32_e32 v39, 0, v211, vcc
	v_mad_u64_u32 v[32:33], s[24:25], v34, s10, v[14:15]
	s_movk_i32 s10, 0x63
	v_and_b32_e32 v33, 16, v32
	v_and_or_b32 v34, v37, s10, v39
	v_or3_b32 v34, v34, v33, v35
	v_ashrrev_i32_e32 v35, 31, v34
	v_lshl_add_u64 v[16:17], v[16:17], 1, v[12:13]
	v_lshlrev_b64 v[34:35], 11, v[34:35]
	v_lshl_add_u64 v[34:35], v[16:17], 0, v[34:35]
	global_store_dwordx4 v[34:35], v[28:31], off sc1
	ds_read2_b32 v[28:29], v21 offset0:8 offset1:41
	v_add_u32_e32 v33, 8, v37
	s_waitcnt lgkmcnt(0)
	v_cvt_pk_bf16_f32 v28, v28, v29
	ds_read2_b32 v[30:31], v21 offset0:74 offset1:107
	s_waitcnt lgkmcnt(0)
	v_cvt_pk_bf16_f32 v29, v30, v31
	ds_read2_b32 v[30:31], v21 offset0:140 offset1:173
	s_waitcnt lgkmcnt(0)
	v_cvt_pk_bf16_f32 v30, v30, v31
	ds_read2_b32 v[34:35], v21 offset0:206 offset1:239
	v_cmp_lt_i32_e32 vcc, s22, v33
	s_waitcnt lgkmcnt(0)
	v_cvt_pk_bf16_f32 v31, v34, v35
	v_add_u32_e32 v39, 32, v32
	v_and_b32_e32 v39, 16, v39
	v_cndmask_b32_e32 v34, 0, v210, vcc
	v_sub_u32_e32 v34, v34, v38
	v_add_u32_e32 v34, v36, v34
	v_lshl_add_u32 v34, v34, 1, 16
	v_cndmask_b32_e32 v35, 0, v211, vcc
	v_and_b32_e32 v33, 0x63, v33
	v_and_b32_e32 v34, 0xffffff00, v34
	v_or3_b32 v33, v33, v35, v39
	v_or3_b32 v34, v33, v34, 4
	v_ashrrev_i32_e32 v35, 31, v34
	v_lshlrev_b64 v[34:35], 11, v[34:35]
	v_lshl_add_u64 v[34:35], v[16:17], 0, v[34:35]
	global_store_dwordx4 v[34:35], v[28:31], off sc1
	ds_read2_b32 v[28:29], v21 offset0:16 offset1:49
	v_add_u32_e32 v33, 16, v37
	s_waitcnt lgkmcnt(0)
	v_cvt_pk_bf16_f32 v28, v28, v29
	ds_read2_b32 v[30:31], v21 offset0:82 offset1:115
	s_waitcnt lgkmcnt(0)
	v_cvt_pk_bf16_f32 v29, v30, v31
	ds_read2_b32 v[30:31], v21 offset0:148 offset1:181
	s_waitcnt lgkmcnt(0)
	v_cvt_pk_bf16_f32 v30, v30, v31
	ds_read2_b32 v[34:35], v21 offset0:214 offset1:247
	v_cmp_lt_i32_e32 vcc, s22, v33
	s_waitcnt lgkmcnt(0)
	v_cvt_pk_bf16_f32 v31, v34, v35
	v_add_u32_e32 v39, 64, v32
	v_and_b32_e32 v39, 16, v39
	v_cndmask_b32_e32 v34, 0, v210, vcc
	v_sub_u32_e32 v34, v34, v38
	v_add_u32_e32 v34, v36, v34
	v_lshl_add_u32 v34, v34, 1, 32
	v_cndmask_b32_e32 v35, 0, v211, vcc
	v_and_b32_e32 v33, 0x63, v33
	v_and_b32_e32 v34, 0xffffff00, v34
	v_or3_b32 v33, v33, v35, v39
	v_or3_b32 v34, v33, v34, 8
	v_ashrrev_i32_e32 v35, 31, v34
	v_lshlrev_b64 v[34:35], 11, v[34:35]
	v_lshl_add_u64 v[34:35], v[16:17], 0, v[34:35]
	global_store_dwordx4 v[34:35], v[28:31], off sc1
	ds_read2_b32 v[28:29], v21 offset0:24 offset1:57
	v_add_u32_e32 v33, 24, v37
	s_waitcnt lgkmcnt(0)
	v_cvt_pk_bf16_f32 v28, v28, v29
	ds_read2_b32 v[30:31], v21 offset0:90 offset1:123
	s_waitcnt lgkmcnt(0)
	v_cvt_pk_bf16_f32 v29, v30, v31
	ds_read2_b32 v[30:31], v21 offset0:156 offset1:189
	s_waitcnt lgkmcnt(0)
	v_cvt_pk_bf16_f32 v30, v30, v31
	ds_read2_b32 v[34:35], v21 offset0:222 offset1:255
	v_cmp_lt_i32_e32 vcc, s22, v33
	s_waitcnt lgkmcnt(0)
	v_cvt_pk_bf16_f32 v31, v34, v35
	v_add_u32_e32 v32, 0x60, v32
	v_and_b32_e32 v32, 16, v32
	v_cndmask_b32_e32 v34, 0, v210, vcc
	v_sub_u32_e32 v34, v34, v38
	v_add_u32_e32 v34, v36, v34
	v_lshl_add_u32 v34, v34, 1, 48
	v_cndmask_b32_e32 v35, 0, v211, vcc
	v_and_b32_e32 v33, 0x63, v33
	v_and_b32_e32 v34, 0xffffff00, v34
	v_or3_b32 v32, v33, v35, v32
	v_or3_b32 v32, v32, v34, 12
	v_ashrrev_i32_e32 v33, 31, v32
	v_lshlrev_b64 v[32:33], 11, v[32:33]
	v_lshl_add_u64 v[16:17], v[16:17], 0, v[32:33]
	global_store_dwordx4 v[16:17], v[28:31], off sc1
	s_waitcnt lgkmcnt(0)
	s_branch .LBB0_526

.Lpost_555:
	v_lshl_or_b32 v136, s46, 7, v140
	v_lshl_add_u32 v142, s48, 8, v138
	v_ashrrev_i32_e32 v137, 31, v136
	v_mov_b64_e32 v[134:135], s[30:31]
	v_lshlrev_b64 v[136:137], 1, v[136:137]
	s_and_b64 vcc, exec, s[38:39]
	s_mov_b32 s48, s42
	s_mov_b32 s46, s40
	v_mov_b32_e32 v188, 0xbfb8aa3b
	v_mov_b32_e32 v189, 0xbfb8aa3b
	v_mad_i64_i32 v[144:145], s[2:3], v142, s33, v[134:135]
	v_or_b32_e32 v186, 16, v142
	v_pk_mul_f32 v[162:163], v[124:125], v[188:189]
	v_mad_i64_i32 v[186:187], s[2:3], v186, s33, v[134:135]
	v_pk_mul_f32 v[164:165], v[126:127], v[188:189]
	v_pk_mul_f32 v[170:171], v[108:109], v[188:189]
	v_pk_mul_f32 v[166:167], v[116:117], v[188:189]
	v_pk_mul_f32 v[172:173], v[110:111], v[188:189]
	v_pk_mul_f32 v[168:169], v[118:119], v[188:189]
	v_pk_mul_f32 v[174:175], v[100:101], v[188:189]
	v_lshl_add_u64 v[144:145], v[144:145], 0, v[136:137]
	v_pk_mul_f32 v[176:177], v[102:103], v[188:189]
	v_exp_f32_e32 v162, v162
	v_lshl_add_u64 v[186:187], v[186:187], 0, v[136:137]
	v_exp_f32_e32 v163, v163
	v_exp_f32_e32 v170, v170
	v_exp_f32_e32 v164, v164
	v_exp_f32_e32 v171, v171
	v_exp_f32_e32 v165, v165
	v_exp_f32_e32 v172, v172
	v_exp_f32_e32 v166, v166
	v_exp_f32_e32 v173, v173
	v_exp_f32_e32 v167, v167
	v_exp_f32_e32 v174, v174
	v_exp_f32_e32 v168, v168
	v_exp_f32_e32 v175, v175
	v_exp_f32_e32 v169, v169
	v_exp_f32_e32 v176, v176
	v_pk_add_f32 v[162:163], v[162:163], 1.0 op_sel_hi:[1,0]
	v_exp_f32_e32 v177, v177
	v_pk_add_f32 v[164:165], v[164:165], 1.0 op_sel_hi:[1,0]
	v_pk_add_f32 v[170:171], v[170:171], 1.0 op_sel_hi:[1,0]
	v_pk_add_f32 v[166:167], v[166:167], 1.0 op_sel_hi:[1,0]
	v_pk_add_f32 v[172:173], v[172:173], 1.0 op_sel_hi:[1,0]
	v_pk_add_f32 v[168:169], v[168:169], 1.0 op_sel_hi:[1,0]
	v_pk_add_f32 v[174:175], v[174:175], 1.0 op_sel_hi:[1,0]
	v_rcp_f32_e32 v162, v162
	v_pk_add_f32 v[176:177], v[176:177], 1.0 op_sel_hi:[1,0]
	v_rcp_f32_e32 v163, v163
	v_rcp_f32_e32 v170, v170
	v_rcp_f32_e32 v164, v164
	v_rcp_f32_e32 v171, v171
	v_rcp_f32_e32 v165, v165
	v_rcp_f32_e32 v172, v172
	v_rcp_f32_e32 v166, v166
	v_rcp_f32_e32 v173, v173
	v_rcp_f32_e32 v167, v167
	v_rcp_f32_e32 v174, v174
	v_rcp_f32_e32 v168, v168
	v_rcp_f32_e32 v175, v175
	v_rcp_f32_e32 v169, v169
	v_rcp_f32_e32 v176, v176
	v_pk_mul_f32 v[162:163], v[124:125], v[162:163]
	v_rcp_f32_e32 v177, v177
	v_pk_mul_f32 v[164:165], v[126:127], v[164:165]
	v_pk_mul_f32 v[170:171], v[108:109], v[170:171]
	v_pk_mul_f32 v[166:167], v[116:117], v[166:167]
	v_pk_mul_f32 v[172:173], v[110:111], v[172:173]
	v_pk_mul_f32 v[168:169], v[118:119], v[168:169]
	v_pk_mul_f32 v[174:175], v[100:101], v[174:175]
	v_pk_mul_f32 v[162:163], v[162:163], v[120:121]
	v_pk_mul_f32 v[176:177], v[102:103], v[176:177]
	v_pk_mul_f32 v[164:165], v[164:165], v[122:123]
	v_pk_mul_f32 v[170:171], v[170:171], v[104:105]
	v_pk_mul_f32 v[166:167], v[166:167], v[112:113]
	v_pk_mul_f32 v[172:173], v[172:173], v[106:107]
	v_pk_mul_f32 v[168:169], v[168:169], v[114:115]
	v_pk_mul_f32 v[174:175], v[174:175], v[96:97]
	v_cvt_pk_bf16_f32 v178, v162, v163
	v_pk_mul_f32 v[176:177], v[176:177], v[98:99]
	v_cvt_pk_bf16_f32 v179, v164, v165
	v_cvt_pk_bf16_f32 v182, v170, v171
	v_cvt_pk_bf16_f32 v180, v166, v167
	v_cvt_pk_bf16_f32 v183, v172, v173
	v_cvt_pk_bf16_f32 v181, v168, v169
	v_cvt_pk_bf16_f32 v184, v174, v175
	global_store_dwordx4 v[144:145], v[178:181], off sc1
	v_cvt_pk_bf16_f32 v185, v176, v177
	global_store_dwordx4 v[186:187], v[182:185], off sc1
	v_or_b32_e32 v144, 32, v142
	v_or_b32_e32 v186, 48, v142
	v_mad_i64_i32 v[144:145], s[2:3], v144, s33, v[134:135]
	v_mad_i64_i32 v[186:187], s[2:3], v186, s33, v[134:135]
	v_pk_mul_f32 v[162:163], v[92:93], v[188:189]
	v_pk_mul_f32 v[170:171], v[76:77], v[188:189]
	v_pk_mul_f32 v[164:165], v[94:95], v[188:189]
	v_pk_mul_f32 v[172:173], v[78:79], v[188:189]
	v_pk_mul_f32 v[166:167], v[84:85], v[188:189]
	v_pk_mul_f32 v[174:175], v[68:69], v[188:189]
	v_pk_mul_f32 v[168:169], v[86:87], v[188:189]
	v_pk_mul_f32 v[176:177], v[70:71], v[188:189]
	v_lshl_add_u64 v[144:145], v[144:145], 0, v[136:137]
	v_lshl_add_u64 v[186:187], v[186:187], 0, v[136:137]
	v_exp_f32_e32 v162, v162
	v_exp_f32_e32 v170, v170
	v_exp_f32_e32 v163, v163
	v_exp_f32_e32 v171, v171
	v_exp_f32_e32 v164, v164
	v_exp_f32_e32 v172, v172
	v_exp_f32_e32 v165, v165
	v_exp_f32_e32 v173, v173
	v_exp_f32_e32 v166, v166
	v_exp_f32_e32 v174, v174
	v_exp_f32_e32 v167, v167
	v_exp_f32_e32 v175, v175
	v_exp_f32_e32 v168, v168
	v_exp_f32_e32 v176, v176
	v_exp_f32_e32 v169, v169
	v_exp_f32_e32 v177, v177
	v_pk_add_f32 v[162:163], v[162:163], 1.0 op_sel_hi:[1,0]
	v_pk_add_f32 v[170:171], v[170:171], 1.0 op_sel_hi:[1,0]
	v_pk_add_f32 v[164:165], v[164:165], 1.0 op_sel_hi:[1,0]
	v_pk_add_f32 v[172:173], v[172:173], 1.0 op_sel_hi:[1,0]
	v_pk_add_f32 v[166:167], v[166:167], 1.0 op_sel_hi:[1,0]
	v_pk_add_f32 v[174:175], v[174:175], 1.0 op_sel_hi:[1,0]
	v_pk_add_f32 v[168:169], v[168:169], 1.0 op_sel_hi:[1,0]
	v_pk_add_f32 v[176:177], v[176:177], 1.0 op_sel_hi:[1,0]
	v_rcp_f32_e32 v162, v162
	v_rcp_f32_e32 v170, v170
	v_rcp_f32_e32 v163, v163
	v_rcp_f32_e32 v171, v171
	v_rcp_f32_e32 v164, v164
	v_rcp_f32_e32 v172, v172
	v_rcp_f32_e32 v165, v165
	v_rcp_f32_e32 v173, v173
	v_rcp_f32_e32 v166, v166
	v_rcp_f32_e32 v174, v174
	v_rcp_f32_e32 v167, v167
	v_rcp_f32_e32 v175, v175
	v_rcp_f32_e32 v168, v168
	v_rcp_f32_e32 v176, v176
	v_rcp_f32_e32 v169, v169
	v_rcp_f32_e32 v177, v177
	v_pk_mul_f32 v[162:163], v[92:93], v[162:163]
	v_pk_mul_f32 v[170:171], v[76:77], v[170:171]
	v_pk_mul_f32 v[164:165], v[94:95], v[164:165]
	v_pk_mul_f32 v[172:173], v[78:79], v[172:173]
	v_pk_mul_f32 v[166:167], v[84:85], v[166:167]
	v_pk_mul_f32 v[174:175], v[68:69], v[174:175]
	v_pk_mul_f32 v[168:169], v[86:87], v[168:169]
	v_pk_mul_f32 v[176:177], v[70:71], v[176:177]
	v_pk_mul_f32 v[162:163], v[162:163], v[88:89]
	v_pk_mul_f32 v[170:171], v[170:171], v[72:73]
	v_pk_mul_f32 v[164:165], v[164:165], v[90:91]
	v_pk_mul_f32 v[172:173], v[172:173], v[74:75]
	v_pk_mul_f32 v[166:167], v[166:167], v[80:81]
	v_pk_mul_f32 v[174:175], v[174:175], v[64:65]
	v_pk_mul_f32 v[168:169], v[168:169], v[82:83]
	v_pk_mul_f32 v[176:177], v[176:177], v[66:67]
	v_cvt_pk_bf16_f32 v178, v162, v163
	v_cvt_pk_bf16_f32 v182, v170, v171
	v_cvt_pk_bf16_f32 v179, v164, v165
	v_cvt_pk_bf16_f32 v183, v172, v173
	v_cvt_pk_bf16_f32 v180, v166, v167
	v_cvt_pk_bf16_f32 v184, v174, v175
	v_cvt_pk_bf16_f32 v181, v168, v169
	v_cvt_pk_bf16_f32 v185, v176, v177
	global_store_dwordx4 v[144:145], v[178:181], off sc1
	global_store_dwordx4 v[186:187], v[182:185], off sc1
	v_add_u32_e32 v144, 0x80, v142
	v_add_u32_e32 v186, 0x90, v142
	v_mad_i64_i32 v[144:145], s[2:3], v144, s33, v[134:135]
	v_mad_i64_i32 v[186:187], s[2:3], v186, s33, v[134:135]
	v_pk_mul_f32 v[162:163], v[60:61], v[188:189]
	v_pk_mul_f32 v[170:171], v[44:45], v[188:189]
	v_pk_mul_f32 v[164:165], v[62:63], v[188:189]
	v_pk_mul_f32 v[172:173], v[46:47], v[188:189]
	v_pk_mul_f32 v[166:167], v[52:53], v[188:189]
	v_pk_mul_f32 v[174:175], v[36:37], v[188:189]
	v_pk_mul_f32 v[168:169], v[54:55], v[188:189]
	v_pk_mul_f32 v[176:177], v[38:39], v[188:189]
	v_lshl_add_u64 v[144:145], v[144:145], 0, v[136:137]
	v_lshl_add_u64 v[186:187], v[186:187], 0, v[136:137]
	v_exp_f32_e32 v162, v162
	v_exp_f32_e32 v170, v170
	v_exp_f32_e32 v163, v163
	v_exp_f32_e32 v171, v171
	v_exp_f32_e32 v164, v164
	v_exp_f32_e32 v172, v172
	v_exp_f32_e32 v165, v165
	v_exp_f32_e32 v173, v173
	v_exp_f32_e32 v166, v166
	v_exp_f32_e32 v174, v174
	v_exp_f32_e32 v167, v167
	v_exp_f32_e32 v175, v175
	v_exp_f32_e32 v168, v168
	v_exp_f32_e32 v176, v176
	v_exp_f32_e32 v169, v169
	v_exp_f32_e32 v177, v177
	v_pk_add_f32 v[162:163], v[162:163], 1.0 op_sel_hi:[1,0]
	v_pk_add_f32 v[170:171], v[170:171], 1.0 op_sel_hi:[1,0]
	v_pk_add_f32 v[164:165], v[164:165], 1.0 op_sel_hi:[1,0]
	v_pk_add_f32 v[172:173], v[172:173], 1.0 op_sel_hi:[1,0]
	v_pk_add_f32 v[166:167], v[166:167], 1.0 op_sel_hi:[1,0]
	v_pk_add_f32 v[174:175], v[174:175], 1.0 op_sel_hi:[1,0]
	v_pk_add_f32 v[168:169], v[168:169], 1.0 op_sel_hi:[1,0]
	v_pk_add_f32 v[176:177], v[176:177], 1.0 op_sel_hi:[1,0]
	v_rcp_f32_e32 v162, v162
	v_rcp_f32_e32 v170, v170
	v_rcp_f32_e32 v163, v163
	v_rcp_f32_e32 v171, v171
	v_rcp_f32_e32 v164, v164
	v_rcp_f32_e32 v172, v172
	v_rcp_f32_e32 v165, v165
	v_rcp_f32_e32 v173, v173
	v_rcp_f32_e32 v166, v166
	v_rcp_f32_e32 v174, v174
	v_rcp_f32_e32 v167, v167
	v_rcp_f32_e32 v175, v175
	v_rcp_f32_e32 v168, v168
	v_rcp_f32_e32 v176, v176
	v_rcp_f32_e32 v169, v169
	v_rcp_f32_e32 v177, v177
	v_pk_mul_f32 v[162:163], v[60:61], v[162:163]
	v_pk_mul_f32 v[170:171], v[44:45], v[170:171]
	v_pk_mul_f32 v[164:165], v[62:63], v[164:165]
	v_pk_mul_f32 v[172:173], v[46:47], v[172:173]
	v_pk_mul_f32 v[166:167], v[52:53], v[166:167]
	v_pk_mul_f32 v[174:175], v[36:37], v[174:175]
	v_pk_mul_f32 v[168:169], v[54:55], v[168:169]
	v_pk_mul_f32 v[176:177], v[38:39], v[176:177]
	v_pk_mul_f32 v[162:163], v[162:163], v[56:57]
	v_pk_mul_f32 v[170:171], v[170:171], v[40:41]
	v_pk_mul_f32 v[164:165], v[164:165], v[58:59]
	v_pk_mul_f32 v[172:173], v[172:173], v[42:43]
	v_pk_mul_f32 v[166:167], v[166:167], v[48:49]
	v_pk_mul_f32 v[174:175], v[174:175], v[32:33]
	v_pk_mul_f32 v[168:169], v[168:169], v[50:51]
	v_pk_mul_f32 v[176:177], v[176:177], v[34:35]
	v_cvt_pk_bf16_f32 v178, v162, v163
	v_cvt_pk_bf16_f32 v182, v170, v171
	v_cvt_pk_bf16_f32 v179, v164, v165
	v_cvt_pk_bf16_f32 v183, v172, v173
	v_cvt_pk_bf16_f32 v180, v166, v167
	v_cvt_pk_bf16_f32 v184, v174, v175
	v_cvt_pk_bf16_f32 v181, v168, v169
	v_cvt_pk_bf16_f32 v185, v176, v177
	global_store_dwordx4 v[144:145], v[178:181], off sc1
	global_store_dwordx4 v[186:187], v[182:185], off sc1
	v_add_u32_e32 v144, 0xa0, v142
	v_add_u32_e32 v186, 0xb0, v142
	v_mad_i64_i32 v[144:145], s[2:3], v144, s33, v[134:135]
	v_mad_i64_i32 v[186:187], s[2:3], v186, s33, v[134:135]
	v_pk_mul_f32 v[162:163], v[28:29], v[188:189]
	v_pk_mul_f32 v[170:171], v[12:13], v[188:189]
	v_pk_mul_f32 v[164:165], v[30:31], v[188:189]
	v_pk_mul_f32 v[172:173], v[14:15], v[188:189]
	v_pk_mul_f32 v[166:167], v[20:21], v[188:189]
	v_pk_mul_f32 v[174:175], v[4:5], v[188:189]
	v_pk_mul_f32 v[168:169], v[22:23], v[188:189]
	v_pk_mul_f32 v[176:177], v[6:7], v[188:189]
	v_lshl_add_u64 v[144:145], v[144:145], 0, v[136:137]
	v_lshl_add_u64 v[186:187], v[186:187], 0, v[136:137]
	v_exp_f32_e32 v162, v162
	v_exp_f32_e32 v170, v170
	v_exp_f32_e32 v163, v163
	v_exp_f32_e32 v171, v171
	v_exp_f32_e32 v164, v164
	v_exp_f32_e32 v172, v172
	v_exp_f32_e32 v165, v165
	v_exp_f32_e32 v173, v173
	v_exp_f32_e32 v166, v166
	v_exp_f32_e32 v174, v174
	v_exp_f32_e32 v167, v167
	v_exp_f32_e32 v175, v175
	v_exp_f32_e32 v168, v168
	v_exp_f32_e32 v176, v176
	v_exp_f32_e32 v169, v169
	v_exp_f32_e32 v177, v177
	v_pk_add_f32 v[162:163], v[162:163], 1.0 op_sel_hi:[1,0]
	v_pk_add_f32 v[170:171], v[170:171], 1.0 op_sel_hi:[1,0]
	v_pk_add_f32 v[164:165], v[164:165], 1.0 op_sel_hi:[1,0]
	v_pk_add_f32 v[172:173], v[172:173], 1.0 op_sel_hi:[1,0]
	v_pk_add_f32 v[166:167], v[166:167], 1.0 op_sel_hi:[1,0]
	v_pk_add_f32 v[174:175], v[174:175], 1.0 op_sel_hi:[1,0]
	v_pk_add_f32 v[168:169], v[168:169], 1.0 op_sel_hi:[1,0]
	v_pk_add_f32 v[176:177], v[176:177], 1.0 op_sel_hi:[1,0]
	v_rcp_f32_e32 v162, v162
	v_rcp_f32_e32 v170, v170
	v_rcp_f32_e32 v163, v163
	v_rcp_f32_e32 v171, v171
	v_rcp_f32_e32 v164, v164
	v_rcp_f32_e32 v172, v172
	v_rcp_f32_e32 v165, v165
	v_rcp_f32_e32 v173, v173
	v_rcp_f32_e32 v166, v166
	v_rcp_f32_e32 v174, v174
	v_rcp_f32_e32 v167, v167
	v_rcp_f32_e32 v175, v175
	v_rcp_f32_e32 v168, v168
	v_rcp_f32_e32 v176, v176
	v_rcp_f32_e32 v169, v169
	v_rcp_f32_e32 v177, v177
	v_pk_mul_f32 v[162:163], v[28:29], v[162:163]
	v_pk_mul_f32 v[170:171], v[12:13], v[170:171]
	v_pk_mul_f32 v[164:165], v[30:31], v[164:165]
	v_pk_mul_f32 v[172:173], v[14:15], v[172:173]
	v_pk_mul_f32 v[166:167], v[20:21], v[166:167]
	v_pk_mul_f32 v[174:175], v[4:5], v[174:175]
	v_pk_mul_f32 v[168:169], v[22:23], v[168:169]
	v_pk_mul_f32 v[176:177], v[6:7], v[176:177]
	v_pk_mul_f32 v[162:163], v[162:163], v[24:25]
	v_pk_mul_f32 v[170:171], v[170:171], v[8:9]
	v_pk_mul_f32 v[164:165], v[164:165], v[26:27]
	v_pk_mul_f32 v[172:173], v[172:173], v[10:11]
	v_pk_mul_f32 v[166:167], v[166:167], v[16:17]
	v_pk_mul_f32 v[174:175], v[174:175], v[0:1]
	v_pk_mul_f32 v[168:169], v[168:169], v[18:19]
	v_pk_mul_f32 v[176:177], v[176:177], v[2:3]
	v_cvt_pk_bf16_f32 v178, v162, v163
	v_cvt_pk_bf16_f32 v182, v170, v171
	v_cvt_pk_bf16_f32 v179, v164, v165
	v_cvt_pk_bf16_f32 v183, v172, v173
	v_cvt_pk_bf16_f32 v180, v166, v167
	v_cvt_pk_bf16_f32 v184, v174, v175
	v_cvt_pk_bf16_f32 v181, v168, v169
	v_cvt_pk_bf16_f32 v185, v176, v177
	global_store_dwordx4 v[144:145], v[178:181], off sc1
	global_store_dwordx4 v[186:187], v[182:185], off sc1
	s_cbranch_vccz .LBB0_554
	s_waitcnt vmcnt(0)
	s_cmpk_gt_u32 s21, 0xff
	s_cbranch_scc1 .LBB0_559
	s_barrier

.LBB0_592:
	s_or_b64 exec, exec, s[2:3]
	v_pk_add_f32 v[118:119], v[86:87], v[116:117]
	v_pk_add_f32 v[116:117], v[84:85], v[114:115]
	s_waitcnt vmcnt(20)
	v_pk_add_f32 v[114:115], v[94:95], v[144:145]
	v_pk_add_f32 v[112:113], v[92:93], v[112:113]
	s_waitcnt vmcnt(17)
	v_pk_add_f32 v[94:95], v[98:99], v[152:153]
	v_pk_add_f32 v[92:93], v[96:97], v[150:151]
	s_waitcnt vmcnt(14)
	v_pk_add_f32 v[86:87], v[106:107], v[166:167]
	v_pk_add_f32 v[84:85], v[104:105], v[148:149]
	s_and_saveexec_b64 s[2:3], s[40:41]
	s_cbranch_execz .LBB0_594
	v_lshl_add_u64 v[96:97], v[126:127], 0, v[136:137]
	global_store_dwordx4 v[96:97], v[116:119], off sc1
	global_store_dwordx4 v[96:97], v[112:115], off offset:1024 sc1
	global_store_dwordx4 v[96:97], v[92:95], off offset:2048 sc1
	global_store_dwordx4 v[96:97], v[84:87], off offset:3072 sc1
.LBB0_594:
	s_or_b64 exec, exec, s[2:3]
	v_mul_f32_e32 v96, v117, v117
	v_mul_f32_e32 v97, v113, v113
	v_fmac_f32_e32 v96, v116, v116
	v_fmac_f32_e32 v97, v112, v112
	v_fmac_f32_e32 v96, v118, v118
	v_fmac_f32_e32 v97, v114, v114
	v_fmac_f32_e32 v96, v119, v119
	v_fmac_f32_e32 v97, v115, v115
	v_add_f32_e32 v96, v96, v97
	v_mul_f32_e32 v97, v93, v93
	v_fmac_f32_e32 v97, v92, v92
	v_fmac_f32_e32 v97, v94, v94
	v_fmac_f32_e32 v97, v95, v95
	v_add_f32_e32 v96, v96, v97
	v_mul_f32_e32 v97, v85, v85
	v_fmac_f32_e32 v97, v84, v84
	v_fmac_f32_e32 v97, v86, v86
	v_fmac_f32_e32 v97, v87, v87
	v_add_f32_e32 v96, v96, v97
	v_pk_add_f32 v[32:33], v[32:33], 1.0 op_sel_hi:[1,0]
	v_pk_add_f32 v[34:35], v[34:35], 1.0 op_sel_hi:[1,0]
	s_waitcnt lgkmcnt(0)
	s_nop 1
	v_add_f32_dpp v96, v96, v96 quad_perm:[1,0,3,2] row_mask:0xf bank_mask:0xf
	s_waitcnt lgkmcnt(0)
	s_nop 1
	v_add_f32_dpp v96, v96, v96 quad_perm:[2,3,0,1] row_mask:0xf bank_mask:0xf
	s_waitcnt lgkmcnt(0)
	s_nop 1
	v_add_f32_dpp v96, v96, v96 row_half_mirror row_mask:0xf bank_mask:0xf
	s_waitcnt lgkmcnt(0)
	s_nop 1
	v_add_f32_dpp v96, v96, v96 row_mirror row_mask:0xf bank_mask:0xf
	s_waitcnt lgkmcnt(0)
	v_mov_b32_e32 v97, v96
	s_nop 1
	v_permlane16_swap_b32_e32 v96, v97
	v_add_f32_e32 v96, v96, v97
	s_waitcnt lgkmcnt(0)
	v_mov_b32_e32 v97, v96
	s_nop 1
	v_permlane32_swap_b32_e32 v96, v97
	v_add_f32_e32 v96, v96, v97
	v_fmamk_f32 v96, v96, 0x3a800000, v158
	v_cmp_gt_f32_e32 vcc, s82, v96
	v_mul_f32_e32 v97, 0x4b800000, v96
	s_nop 0
	v_cndmask_b32_e32 v96, v96, v97, vcc
	v_rsq_f32_e32 v96, v96
	s_nop 0
	v_mul_f32_e32 v97, 0x45800000, v96
	v_cndmask_b32_e32 v96, v96, v97, vcc
	v_pk_mul_f32 v[104:105], v[116:117], v[96:97] op_sel_hi:[1,0]
	v_pk_mul_f32 v[98:99], v[118:119], v[96:97] op_sel_hi:[1,0]
	v_pk_mul_f32 v[104:105], v[0:1], v[104:105]
	v_pk_mul_f32 v[98:99], v[2:3], v[98:99]
	v_pk_fma_f32 v[28:29], v[32:33], v[104:105], v[28:29]
	v_pk_fma_f32 v[30:31], v[34:35], v[98:99], v[30:31]
	v_cvt_pk_bf16_f32 v28, v28, v29
	v_pk_add_f32 v[32:33], v[62:63], 1.0 op_sel_hi:[1,0]
	v_cvt_pk_bf16_f32 v29, v30, v31
	global_store_dwordx2 v[132:133], v[28:29], off offset:-1024
	v_pk_mul_f32 v[28:29], v[114:115], v[96:97] op_sel_hi:[1,0]
	v_pk_mul_f32 v[30:31], v[112:113], v[96:97] op_sel_hi:[1,0]
	v_pk_mul_f32 v[28:29], v[6:7], v[28:29]
	v_pk_mul_f32 v[30:31], v[4:5], v[30:31]
	v_pk_add_f32 v[34:35], v[60:61], 1.0 op_sel_hi:[1,0]
	v_pk_fma_f32 v[26:27], v[32:33], v[28:29], v[26:27]
	v_pk_fma_f32 v[24:25], v[34:35], v[30:31], v[24:25]
	v_pk_add_f32 v[30:31], v[56:57], 1.0 op_sel_hi:[1,0]
	v_cvt_pk_bf16_f32 v24, v24, v25
	v_cvt_pk_bf16_f32 v25, v26, v27
	v_pk_mul_f32 v[26:27], v[92:93], v[96:97] op_sel_hi:[1,0]
	global_store_dwordx2 v[132:133], v[24:25], off offset:-512
	v_pk_mul_f32 v[24:25], v[94:95], v[96:97] op_sel_hi:[1,0]
	v_pk_mul_f32 v[26:27], v[8:9], v[26:27]
	v_pk_mul_f32 v[24:25], v[10:11], v[24:25]
	v_pk_add_f32 v[28:29], v[58:59], 1.0 op_sel_hi:[1,0]
	v_pk_fma_f32 v[26:27], v[30:31], v[26:27], v[52:53]
	v_pk_fma_f32 v[24:25], v[28:29], v[24:25], v[54:55]
	v_cvt_pk_bf16_f32 v26, v26, v27
	s_waitcnt vmcnt(15)
	v_pk_add_f32 v[30:31], v[68:69], 1.0 op_sel_hi:[1,0]
	v_cvt_pk_bf16_f32 v27, v24, v25
	global_store_dwordx2 v[132:133], v[26:27], off
	v_pk_mul_f32 v[26:27], v[84:85], v[96:97] op_sel_hi:[1,0]
	v_pk_mul_f32 v[24:25], v[86:87], v[96:97] op_sel_hi:[1,0]
	v_pk_mul_f32 v[26:27], v[12:13], v[26:27]
	v_pk_mul_f32 v[24:25], v[14:15], v[24:25]
	v_pk_add_f32 v[28:29], v[70:71], 1.0 op_sel_hi:[1,0]
	s_waitcnt vmcnt(15)
	v_pk_fma_f32 v[26:27], v[30:31], v[26:27], v[64:65]
	v_pk_fma_f32 v[24:25], v[28:29], v[24:25], v[66:67]
	v_cvt_pk_bf16_f32 v26, v26, v27
	s_nop 0
	v_cvt_pk_bf16_f32 v27, v24, v25
	global_store_dwordx2 v[132:133], v[26:27], off offset:512
	s_and_saveexec_b64 s[6:7], s[38:39]
	s_cbranch_execz .LBB0_567
	s_waitcnt vmcnt(15)
	v_pk_add_f32 v[54:55], v[82:83], v[140:141]
	v_pk_add_f32 v[52:53], v[80:81], v[138:139]
	s_waitcnt vmcnt(12)
	v_pk_add_f32 v[34:35], v[90:91], v[146:147]
	v_pk_add_f32 v[32:33], v[88:89], v[142:143]
	s_waitcnt vmcnt(9)
	v_pk_add_f32 v[30:31], v[102:103], v[164:165]
	v_pk_add_f32 v[28:29], v[100:101], v[162:163]
	s_waitcnt vmcnt(6)
	v_pk_add_f32 v[26:27], v[110:111], v[168:169]
	v_pk_add_f32 v[24:25], v[108:109], v[154:155]
	v_cmp_lt_i32_e32 vcc, s90, v134
	s_and_saveexec_b64 s[2:3], vcc
	s_cbranch_execz .LBB0_566
	v_add_u32_e32 v156, 0xffff8000, v134
	v_lshlrev_b64 v[56:57], 12, v[156:157]
	v_lshl_add_u64 v[56:57], v[126:127], 0, v[56:57]
	global_store_dwordx4 v[56:57], v[52:55], off sc1
	global_store_dwordx4 v[56:57], v[32:35], off offset:1024 sc1
	global_store_dwordx4 v[56:57], v[28:31], off offset:2048 sc1
	global_store_dwordx4 v[56:57], v[24:27], off offset:3072 sc1
	s_branch .LBB0_566

.LBB0_602:
	v_cmp_lt_i32_e32 vcc, s22, v1
	s_and_saveexec_b64 s[6:7], vcc
	s_xor_b64 s[34:35], exec, s[6:7]
	s_cbranch_execz .LBB0_620
	s_movk_i32 s6, 0x15ff
	v_cmp_lt_u32_e32 vcc, s6, v1
	s_and_saveexec_b64 s[6:7], vcc
	s_xor_b64 s[36:37], exec, s[6:7]
	s_cbranch_execz .LBB0_617
	s_movk_i32 s6, 0x1b7f
	v_cmp_lt_u32_e32 vcc, s6, v1
	s_and_saveexec_b64 s[6:7], vcc
	s_xor_b64 s[38:39], exec, s[6:7]
	s_cbranch_execz .LBB0_614
	s_movk_i32 s6, 0x20ff
	v_cmp_lt_u32_e32 vcc, s6, v1
	s_and_saveexec_b64 s[6:7], vcc
	s_xor_b64 s[6:7], exec, s[6:7]
	s_cbranch_execz .LBB0_611
	s_movk_i32 s19, 0x22af
	v_cmp_lt_u32_e32 vcc, s19, v1
	s_and_saveexec_b64 s[24:25], vcc
	s_xor_b64 s[40:41], exec, s[24:25]
	s_cbranch_execz .LBB0_608
	s_load_dwordx2 s[24:25], s[0:1], 0xa8
	v_add_u32_e32 v28, 0xfffbaa00, v26
	v_and_b32_e32 v47, 0x3e0, v28
	v_and_b32_e32 v46, 0x1ffc0, v27
	v_lshlrev_b32_e32 v156, 2, v47
	v_or_b32_e32 v30, v46, v3
	s_waitcnt lgkmcnt(0)
	v_lshl_add_u64 v[28:29], s[24:25], 0, v[156:157]
	v_lshlrev_b32_e32 v156, 2, v4
	v_lshl_add_u64 v[28:29], v[28:29], 0, v[156:157]
	v_lshlrev_b32_e32 v156, 12, v30
	v_lshl_add_u64 v[28:29], v[28:29], 0, v[156:157]
	s_movk_i32 s19, 0x2000
	v_add_co_u32_e32 v30, vcc, s19, v28
	s_movk_i32 s19, 0x4000
	s_nop 0
	v_addc_co_u32_e32 v31, vcc, 0, v29, vcc
	v_add_co_u32_e32 v32, vcc, s19, v28
	s_movk_i32 s19, 0x6000
	s_nop 0
	v_addc_co_u32_e32 v33, vcc, 0, v29, vcc
	v_add_co_u32_e32 v34, vcc, s19, v28
	s_mov_b32 s19, 0xa000
	s_nop 0
	v_addc_co_u32_e32 v35, vcc, 0, v29, vcc
	v_add_co_u32_e32 v36, vcc, s73, v28
	v_lshlrev_b32_e32 v156, 1, v46
	s_nop 0
	v_addc_co_u32_e32 v37, vcc, 0, v29, vcc
	v_add_co_u32_e32 v38, vcc, s19, v28
	s_mov_b32 s19, 0xc000
	s_nop 0
	v_addc_co_u32_e32 v39, vcc, 0, v29, vcc
	v_add_co_u32_e32 v40, vcc, s19, v28
	s_mov_b32 s19, 0xe000
	s_nop 0
	v_addc_co_u32_e32 v41, vcc, 0, v29, vcc
	v_add_co_u32_e32 v42, vcc, s19, v28
	s_mov_b32 s19, 0x10000
	s_nop 0
	v_addc_co_u32_e32 v43, vcc, 0, v29, vcc
	global_load_dword v48, v[28:29], off
	global_load_dword v49, v[30:31], off
	global_load_dword v50, v[32:33], off
	global_load_dword v51, v[34:35], off
	global_load_dword v52, v[36:37], off
	global_load_dword v53, v[38:39], off
	global_load_dword v54, v[40:41], off
	global_load_dword v55, v[42:43], off
	v_add_co_u32_e32 v30, vcc, s19, v28
	s_mov_b32 s19, 0x12000
	s_nop 0
	v_addc_co_u32_e32 v31, vcc, 0, v29, vcc
	v_add_co_u32_e32 v32, vcc, s19, v28
	s_mov_b32 s19, 0x14000
	s_nop 0
	v_addc_co_u32_e32 v33, vcc, 0, v29, vcc
	v_add_co_u32_e32 v34, vcc, s19, v28
	s_mov_b32 s19, 0x16000
	s_nop 0
	v_addc_co_u32_e32 v35, vcc, 0, v29, vcc
	v_add_co_u32_e32 v36, vcc, s19, v28
	s_mov_b32 s19, 0x18000
	s_nop 0
	v_addc_co_u32_e32 v37, vcc, 0, v29, vcc
	v_add_co_u32_e32 v38, vcc, s19, v28
	s_mov_b32 s19, 0x1a000
	s_nop 0
	v_addc_co_u32_e32 v39, vcc, 0, v29, vcc
	v_add_co_u32_e32 v40, vcc, s19, v28
	s_mov_b32 s19, 0x1c000
	s_nop 0
	v_addc_co_u32_e32 v41, vcc, 0, v29, vcc
	v_add_co_u32_e32 v42, vcc, s19, v28
	s_mov_b32 s19, 0x1e000
	s_nop 0
	v_addc_co_u32_e32 v43, vcc, 0, v29, vcc
	v_add_co_u32_e32 v44, vcc, s19, v28
	s_mov_b32 s19, 0x20000
	s_nop 0
	v_addc_co_u32_e32 v45, vcc, 0, v29, vcc
	global_load_dword v56, v[30:31], off
	global_load_dword v57, v[32:33], off
	global_load_dword v58, v[34:35], off
	global_load_dword v59, v[36:37], off
	global_load_dword v60, v[38:39], off
	global_load_dword v61, v[40:41], off
	global_load_dword v62, v[42:43], off
	global_load_dword v63, v[44:45], off
	v_add_co_u32_e32 v30, vcc, s19, v28
	s_mov_b32 s19, 0x22000
	s_nop 0
	v_addc_co_u32_e32 v31, vcc, 0, v29, vcc
	v_add_co_u32_e32 v32, vcc, s19, v28
	s_mov_b32 s19, 0x24000
	s_nop 0
	v_addc_co_u32_e32 v33, vcc, 0, v29, vcc
	v_add_co_u32_e32 v34, vcc, s19, v28
	s_mov_b32 s19, 0x26000
	s_nop 0
	v_addc_co_u32_e32 v35, vcc, 0, v29, vcc
	v_add_co_u32_e32 v36, vcc, s19, v28
	s_mov_b32 s19, 0x28000
	s_nop 0
	v_addc_co_u32_e32 v37, vcc, 0, v29, vcc
	v_add_co_u32_e32 v38, vcc, s19, v28
	s_mov_b32 s19, 0x2a000
	s_nop 0
	v_addc_co_u32_e32 v39, vcc, 0, v29, vcc
	v_add_co_u32_e32 v40, vcc, s19, v28
	s_mov_b32 s19, 0x2c000
	s_nop 0
	v_addc_co_u32_e32 v41, vcc, 0, v29, vcc
	v_add_co_u32_e32 v42, vcc, s19, v28
	s_mov_b32 s19, 0x2e000
	s_nop 0
	v_addc_co_u32_e32 v43, vcc, 0, v29, vcc
	v_add_co_u32_e32 v44, vcc, s19, v28
	s_mov_b32 s19, 0x30000
	s_nop 0
	v_addc_co_u32_e32 v45, vcc, 0, v29, vcc
	global_load_dword v64, v[30:31], off
	global_load_dword v65, v[32:33], off
	global_load_dword v66, v[34:35], off
	global_load_dword v67, v[36:37], off
	global_load_dword v68, v[38:39], off
	global_load_dword v69, v[40:41], off
	global_load_dword v70, v[42:43], off
	s_nop 0
	global_load_dword v44, v[44:45], off
	v_add_co_u32_e32 v30, vcc, s19, v28
	s_mov_b32 s19, 0x32000
	s_nop 0
	v_addc_co_u32_e32 v31, vcc, 0, v29, vcc
	v_add_co_u32_e32 v32, vcc, s19, v28
	s_mov_b32 s19, 0x34000
	s_nop 0
	v_addc_co_u32_e32 v33, vcc, 0, v29, vcc
	v_add_co_u32_e32 v34, vcc, s19, v28
	s_mov_b32 s19, 0x36000
	s_nop 0
	v_addc_co_u32_e32 v35, vcc, 0, v29, vcc
	v_add_co_u32_e32 v36, vcc, s19, v28
	s_mov_b32 s19, 0x38000
	s_nop 0
	v_addc_co_u32_e32 v37, vcc, 0, v29, vcc
	v_add_co_u32_e32 v38, vcc, s19, v28
	s_mov_b32 s19, 0x3a000
	s_nop 0
	v_addc_co_u32_e32 v39, vcc, 0, v29, vcc
	v_add_co_u32_e32 v40, vcc, s19, v28
	s_mov_b32 s19, 0x3c000
	s_nop 0
	v_addc_co_u32_e32 v41, vcc, 0, v29, vcc
	v_add_co_u32_e32 v42, vcc, s19, v28
	s_mov_b32 s19, 0x3e000
	s_nop 0
	v_addc_co_u32_e32 v43, vcc, 0, v29, vcc
	v_add_co_u32_e32 v28, vcc, s19, v28
	s_nop 1
	v_addc_co_u32_e32 v29, vcc, 0, v29, vcc
	global_load_dword v30, v[30:31], off
	s_nop 0
	global_load_dword v31, v[32:33], off
	s_nop 0
	global_load_dword v32, v[34:35], off
	global_load_dword v33, v[36:37], off
	s_nop 0
	global_load_dword v34, v[38:39], off
	global_load_dword v35, v[40:41], off
	global_load_dword v36, v[42:43], off
	s_nop 0
	global_load_dword v28, v[28:29], off
	v_add_u32_e32 v29, 0x400, v5
	s_waitcnt vmcnt(30)
	ds_write2_b32 v5, v48, v49 offset1:66
	s_waitcnt vmcnt(28)
	ds_write2_b32 v5, v50, v51 offset0:132 offset1:198
	s_waitcnt vmcnt(26)
	ds_write2_b32 v29, v52, v53 offset0:8 offset1:74
	s_waitcnt vmcnt(24)
	ds_write2_b32 v29, v54, v55 offset0:140 offset1:206
	v_add_u32_e32 v29, 0x800, v5
	s_waitcnt vmcnt(22)
	ds_write2_b32 v29, v56, v57 offset0:16 offset1:82
	s_waitcnt vmcnt(20)
	ds_write2_b32 v29, v58, v59 offset0:148 offset1:214
	v_add_u32_e32 v29, 0xc00, v5
	s_waitcnt vmcnt(18)
	ds_write2_b32 v29, v60, v61 offset0:24 offset1:90
	s_waitcnt vmcnt(16)
	ds_write2_b32 v29, v62, v63 offset0:156 offset1:222
	v_add_u32_e32 v29, 0x1000, v5
	s_waitcnt vmcnt(14)
	ds_write2_b32 v29, v64, v65 offset0:32 offset1:98
	s_waitcnt vmcnt(12)
	ds_write2_b32 v29, v66, v67 offset0:164 offset1:230
	v_add_u32_e32 v29, 0x1400, v5
	s_waitcnt vmcnt(10)
	ds_write2_b32 v29, v68, v69 offset0:40 offset1:106
	s_waitcnt vmcnt(8)
	ds_write2_b32 v29, v70, v44 offset0:172 offset1:238
	v_add_u32_e32 v29, 0x1800, v5
	s_waitcnt vmcnt(6)
	ds_write2_b32 v29, v30, v31 offset0:48 offset1:114
	s_waitcnt vmcnt(4)
	ds_write2_b32 v29, v32, v33 offset0:180 offset1:246
	v_add_u32_e32 v29, 0x1c00, v5
	s_waitcnt vmcnt(2)
	ds_write2_b32 v29, v34, v35 offset0:56 offset1:122
	s_waitcnt vmcnt(0)
	ds_write2_b32 v29, v36, v28 offset0:188 offset1:254
	s_waitcnt lgkmcnt(0)
	ds_read2_b32 v[28:29], v21 offset1:33
	s_waitcnt lgkmcnt(0)
	v_cvt_pk_bf16_f32 v28, v28, v29
	ds_read2_b32 v[30:31], v21 offset0:66 offset1:99
	v_or_b32_e32 v36, v47, v19
	s_waitcnt lgkmcnt(0)
	v_cvt_pk_bf16_f32 v29, v30, v31
	ds_read2_b32 v[30:31], v21 offset0:132 offset1:165
	v_lshl_add_u64 v[34:35], v[6:7], 0, v[156:157]
	v_lshlrev_b32_e32 v156, 11, v36
	s_waitcnt lgkmcnt(0)
	v_cvt_pk_bf16_f32 v30, v30, v31
	ds_read2_b32 v[32:33], v21 offset0:198 offset1:231
	s_waitcnt lgkmcnt(0)
	v_cvt_pk_bf16_f32 v31, v32, v33
	v_lshl_add_u64 v[36:37], v[34:35], 0, v[156:157]
	ds_read2_b32 v[32:33], v21 offset0:8 offset1:41
	global_store_dwordx4 v[36:37], v[28:31], off sc1
	v_or_b32_e32 v36, v47, v22
	v_lshlrev_b32_e32 v156, 11, v36
	s_waitcnt lgkmcnt(0)
	v_cvt_pk_bf16_f32 v28, v32, v33
	ds_read2_b32 v[30:31], v21 offset0:74 offset1:107
	s_waitcnt lgkmcnt(0)
	v_cvt_pk_bf16_f32 v29, v30, v31
	ds_read2_b32 v[30:31], v21 offset0:140 offset1:173
	s_waitcnt lgkmcnt(0)
	v_cvt_pk_bf16_f32 v30, v30, v31
	ds_read2_b32 v[32:33], v21 offset0:206 offset1:239
	s_waitcnt lgkmcnt(0)
	v_cvt_pk_bf16_f32 v31, v32, v33
	v_lshl_add_u64 v[36:37], v[34:35], 0, v[156:157]
	ds_read2_b32 v[32:33], v21 offset0:16 offset1:49
	global_store_dwordx4 v[36:37], v[28:31], off sc1
	v_or_b32_e32 v36, v47, v23
	v_lshlrev_b32_e32 v156, 11, v36
	s_waitcnt lgkmcnt(0)
	v_cvt_pk_bf16_f32 v28, v32, v33
	ds_read2_b32 v[30:31], v21 offset0:82 offset1:115
	s_waitcnt lgkmcnt(0)
	v_cvt_pk_bf16_f32 v29, v30, v31
	ds_read2_b32 v[30:31], v21 offset0:148 offset1:181
	s_waitcnt lgkmcnt(0)
	v_cvt_pk_bf16_f32 v30, v30, v31
	ds_read2_b32 v[32:33], v21 offset0:214 offset1:247
	s_waitcnt lgkmcnt(0)
	v_cvt_pk_bf16_f32 v31, v32, v33
	v_lshl_add_u64 v[36:37], v[34:35], 0, v[156:157]
	ds_read2_b32 v[32:33], v21 offset0:24 offset1:57
	global_store_dwordx4 v[36:37], v[28:31], off sc1
	s_waitcnt lgkmcnt(0)
	s_nop 0
	v_cvt_pk_bf16_f32 v28, v32, v33
	ds_read2_b32 v[30:31], v21 offset0:90 offset1:123
	s_waitcnt lgkmcnt(0)
	v_cvt_pk_bf16_f32 v29, v30, v31
	ds_read2_b32 v[30:31], v21 offset0:156 offset1:189
	s_waitcnt lgkmcnt(0)
	v_cvt_pk_bf16_f32 v30, v30, v31
	ds_read2_b32 v[32:33], v21 offset0:222 offset1:255
	s_waitcnt lgkmcnt(0)
	v_cvt_pk_bf16_f32 v31, v32, v33
	v_or_b32_e32 v32, v47, v24
	v_lshlrev_b32_e32 v156, 11, v32
	v_lshl_add_u64 v[32:33], v[34:35], 0, v[156:157]
	global_store_dwordx4 v[32:33], v[28:31], off sc1
	s_waitcnt lgkmcnt(0)
.LBB0_608:
	s_andn2_saveexec_b64 s[40:41], s[40:41]
	s_cbranch_execz .LBB0_610
	v_add_u16_e32 v28, 0xdf00, v1
	v_mul_u32_u24_e32 v29, 0x2f69, v28
	v_sub_u16_sdwa v30, v28, v29 dst_sel:DWORD dst_unused:UNUSED_PAD src0_sel:DWORD src1_sel:WORD_1
	v_lshrrev_b16_e32 v30, 1, v30
	v_add_u16_sdwa v29, v30, v29 dst_sel:DWORD dst_unused:UNUSED_PAD src0_sel:DWORD src1_sel:WORD_1
	s_load_dwordx2 s[24:25], s[0:1], 0x50
	v_lshrrev_b16_e32 v46, 4, v29
	v_mul_lo_u16_e32 v29, 27, v46
	v_sub_u16_e32 v28, v28, v29
	v_lshlrev_b16_e32 v47, 5, v28
	v_lshl_or_b32 v30, v46, 6, v3
	v_lshlrev_b32_e32 v156, 2, v47
	s_waitcnt lgkmcnt(0)
	v_lshl_add_u64 v[28:29], s[24:25], 0, v[156:157]
	v_lshlrev_b32_e32 v156, 2, v4
	v_mul_u32_u24_e32 v30, 0x560, v30
	v_lshl_add_u64 v[28:29], v[28:29], 0, v[156:157]
	v_lshlrev_b32_e32 v156, 2, v30
	v_lshl_add_u64 v[28:29], v[28:29], 0, v[156:157]
	s_movk_i32 s19, 0x2000
	v_add_co_u32_e32 v30, vcc, s19, v28
	s_movk_i32 s19, 0x5000
	s_nop 0
	v_addc_co_u32_e32 v31, vcc, 0, v29, vcc
	v_add_co_u32_e32 v32, vcc, s19, v28
	s_mov_b32 s19, 0xb000
	s_nop 0
	v_addc_co_u32_e32 v33, vcc, 0, v29, vcc
	v_add_co_u32_e32 v34, vcc, s73, v28
	v_lshlrev_b32_e32 v156, 7, v46
	s_nop 0
	v_addc_co_u32_e32 v35, vcc, 0, v29, vcc
	v_add_co_u32_e32 v36, vcc, s19, v28
	s_mov_b32 s19, 0xd000
	s_nop 0
	v_addc_co_u32_e32 v37, vcc, 0, v29, vcc
	v_add_co_u32_e32 v38, vcc, s19, v28
	s_mov_b32 s19, 0x10000
	s_nop 0
	v_addc_co_u32_e32 v39, vcc, 0, v29, vcc
	v_add_co_u32_e32 v40, vcc, s19, v28
	s_mov_b32 s19, 0x13000
	s_nop 0
	v_addc_co_u32_e32 v41, vcc, 0, v29, vcc
	v_add_co_u32_e32 v42, vcc, s19, v28
	s_mov_b32 s19, 0x15000
	s_nop 0
	v_addc_co_u32_e32 v43, vcc, 0, v29, vcc
	global_load_dword v48, v[28:29], off offset:1024
	global_load_dword v49, v[30:31], off offset:3840
	global_load_dword v50, v[32:33], off offset:2560
	global_load_dword v51, v[34:35], off offset:1280
	global_load_dword v52, v[36:37], off
	global_load_dword v53, v[38:39], off offset:2816
	global_load_dword v54, v[40:41], off offset:1536
	global_load_dword v55, v[42:43], off offset:256
	v_add_co_u32_e32 v30, vcc, s19, v28
	s_mov_b32 s19, 0x18000
	s_nop 0
	v_addc_co_u32_e32 v31, vcc, 0, v29, vcc
	v_add_co_u32_e32 v32, vcc, s19, v28
	s_mov_b32 s19, 0x1b000
	s_nop 0
	v_addc_co_u32_e32 v33, vcc, 0, v29, vcc
	v_add_co_u32_e32 v34, vcc, s19, v28
	s_mov_b32 s19, 0x1d000
	s_nop 0
	v_addc_co_u32_e32 v35, vcc, 0, v29, vcc
	v_add_co_u32_e32 v36, vcc, s19, v28
	s_mov_b32 s19, 0x20000
	s_nop 0
	v_addc_co_u32_e32 v37, vcc, 0, v29, vcc
	v_add_co_u32_e32 v38, vcc, s19, v28
	s_mov_b32 s19, 0x23000
	s_nop 0
	v_addc_co_u32_e32 v39, vcc, 0, v29, vcc
	v_add_co_u32_e32 v40, vcc, s19, v28
	s_mov_b32 s19, 0x25000
	s_nop 0
	v_addc_co_u32_e32 v41, vcc, 0, v29, vcc
	v_add_co_u32_e32 v42, vcc, s19, v28
	s_mov_b32 s19, 0x28000
	s_nop 0
	v_addc_co_u32_e32 v43, vcc, 0, v29, vcc
	v_add_co_u32_e32 v44, vcc, s19, v28
	s_mov_b32 s19, 0x2b000
	s_nop 0
	v_addc_co_u32_e32 v45, vcc, 0, v29, vcc
	global_load_dword v56, v[30:31], off offset:3072
	global_load_dword v57, v[32:33], off offset:1792
	global_load_dword v58, v[34:35], off offset:512
	global_load_dword v59, v[36:37], off offset:3328
	global_load_dword v60, v[38:39], off offset:2048
	global_load_dword v61, v[40:41], off offset:768
	global_load_dword v62, v[42:43], off offset:3584
	global_load_dword v63, v[44:45], off offset:2304
	v_add_co_u32_e32 v30, vcc, s19, v28
	s_mov_b32 s19, 0x2d000
	s_nop 0
	v_addc_co_u32_e32 v31, vcc, 0, v29, vcc
	v_add_co_u32_e32 v32, vcc, s19, v28
	s_mov_b32 s19, 0x30000
	s_nop 0
	v_addc_co_u32_e32 v33, vcc, 0, v29, vcc
	v_add_co_u32_e32 v34, vcc, s19, v28
	s_mov_b32 s19, 0x33000
	s_nop 0
	v_addc_co_u32_e32 v35, vcc, 0, v29, vcc
	v_add_co_u32_e32 v36, vcc, s19, v28
	s_mov_b32 s19, 0x36000
	s_nop 0
	v_addc_co_u32_e32 v37, vcc, 0, v29, vcc
	v_add_co_u32_e32 v38, vcc, s19, v28
	s_mov_b32 s19, 0x38000
	s_nop 0
	v_addc_co_u32_e32 v39, vcc, 0, v29, vcc
	v_add_co_u32_e32 v40, vcc, s19, v28
	s_mov_b32 s19, 0x3b000
	s_nop 0
	v_addc_co_u32_e32 v41, vcc, 0, v29, vcc
	v_add_co_u32_e32 v42, vcc, s19, v28
	s_mov_b32 s19, 0x3e000
	s_nop 0
	v_addc_co_u32_e32 v43, vcc, 0, v29, vcc
	v_add_co_u32_e32 v44, vcc, s19, v28
	s_mov_b32 s19, 0x40000
	s_nop 0
	v_addc_co_u32_e32 v45, vcc, 0, v29, vcc
	global_load_dword v64, v[30:31], off offset:1024
	global_load_dword v65, v[32:33], off offset:3840
	global_load_dword v66, v[34:35], off offset:2560
	global_load_dword v67, v[36:37], off offset:1280
	global_load_dword v68, v[38:39], off
	global_load_dword v69, v[40:41], off offset:2816
	global_load_dword v70, v[42:43], off offset:1536
	s_nop 0
	global_load_dword v44, v[44:45], off offset:256
	v_add_co_u32_e32 v30, vcc, s19, v28
	s_mov_b32 s19, 0x43000
	s_nop 0
	v_addc_co_u32_e32 v31, vcc, 0, v29, vcc
	v_add_co_u32_e32 v32, vcc, s19, v28
	s_mov_b32 s19, 0x46000
	s_nop 0
	v_addc_co_u32_e32 v33, vcc, 0, v29, vcc
	v_add_co_u32_e32 v34, vcc, s19, v28
	s_mov_b32 s19, 0x48000
	s_nop 0
	v_addc_co_u32_e32 v35, vcc, 0, v29, vcc
	v_add_co_u32_e32 v36, vcc, s19, v28
	s_mov_b32 s19, 0x4b000
	s_nop 0
	v_addc_co_u32_e32 v37, vcc, 0, v29, vcc
	v_add_co_u32_e32 v38, vcc, s19, v28
	s_mov_b32 s19, 0x4e000
	s_nop 0
	v_addc_co_u32_e32 v39, vcc, 0, v29, vcc
	v_add_co_u32_e32 v40, vcc, s19, v28
	s_mov_b32 s19, 0x50000
	s_nop 0
	v_addc_co_u32_e32 v41, vcc, 0, v29, vcc
	v_add_co_u32_e32 v42, vcc, s19, v28
	s_mov_b32 s19, 0x53000
	s_nop 0
	v_addc_co_u32_e32 v43, vcc, 0, v29, vcc
	v_add_co_u32_e32 v28, vcc, s19, v28
	s_nop 1
	v_addc_co_u32_e32 v29, vcc, 0, v29, vcc
	global_load_dword v30, v[30:31], off offset:3072
	s_nop 0
	global_load_dword v31, v[32:33], off offset:1792
	s_nop 0
	global_load_dword v32, v[34:35], off offset:512
	global_load_dword v33, v[36:37], off offset:3328
	s_nop 0
	global_load_dword v34, v[38:39], off offset:2048
	global_load_dword v35, v[40:41], off offset:768
	global_load_dword v36, v[42:43], off offset:3584
	s_nop 0
	global_load_dword v28, v[28:29], off offset:2304
	v_add_u32_e32 v29, 0x400, v5
	s_waitcnt vmcnt(30)
	ds_write2_b32 v5, v48, v49 offset1:66
	s_waitcnt vmcnt(28)
	ds_write2_b32 v5, v50, v51 offset0:132 offset1:198
	s_waitcnt vmcnt(26)
	ds_write2_b32 v29, v52, v53 offset0:8 offset1:74
	s_waitcnt vmcnt(24)
	ds_write2_b32 v29, v54, v55 offset0:140 offset1:206
	v_add_u32_e32 v29, 0x800, v5
	s_waitcnt vmcnt(22)
	ds_write2_b32 v29, v56, v57 offset0:16 offset1:82
	s_waitcnt vmcnt(20)
	ds_write2_b32 v29, v58, v59 offset0:148 offset1:214
	v_add_u32_e32 v29, 0xc00, v5
	s_waitcnt vmcnt(18)
	ds_write2_b32 v29, v60, v61 offset0:24 offset1:90
	s_waitcnt vmcnt(16)
	ds_write2_b32 v29, v62, v63 offset0:156 offset1:222
	v_add_u32_e32 v29, 0x1000, v5
	s_waitcnt vmcnt(14)
	ds_write2_b32 v29, v64, v65 offset0:32 offset1:98
	s_waitcnt vmcnt(12)
	ds_write2_b32 v29, v66, v67 offset0:164 offset1:230
	v_add_u32_e32 v29, 0x1400, v5
	s_waitcnt vmcnt(10)
	ds_write2_b32 v29, v68, v69 offset0:40 offset1:106
	s_waitcnt vmcnt(8)
	ds_write2_b32 v29, v70, v44 offset0:172 offset1:238
	v_add_u32_e32 v29, 0x1800, v5
	s_waitcnt vmcnt(6)
	ds_write2_b32 v29, v30, v31 offset0:48 offset1:114
	s_waitcnt vmcnt(4)
	ds_write2_b32 v29, v32, v33 offset0:180 offset1:246
	v_add_u32_e32 v29, 0x1c00, v5
	s_waitcnt vmcnt(2)
	ds_write2_b32 v29, v34, v35 offset0:56 offset1:122
	s_waitcnt vmcnt(0)
	ds_write2_b32 v29, v36, v28 offset0:188 offset1:254
	s_waitcnt lgkmcnt(0)
	ds_read2_b32 v[28:29], v21 offset1:33
	v_add_u16_e32 v38, 0x200, v47
	s_waitcnt lgkmcnt(0)
	v_cvt_pk_bf16_f32 v28, v28, v29
	ds_read2_b32 v[30:31], v21 offset0:66 offset1:99
	v_or_b32_e32 v36, v19, v38
	s_waitcnt lgkmcnt(0)
	v_cvt_pk_bf16_f32 v29, v30, v31
	ds_read2_b32 v[30:31], v21 offset0:132 offset1:165
	v_lshl_add_u64 v[34:35], v[8:9], 0, v[156:157]
	v_lshlrev_b32_e32 v156, 11, v36
	s_waitcnt lgkmcnt(0)
	v_cvt_pk_bf16_f32 v30, v30, v31
	ds_read2_b32 v[32:33], v21 offset0:198 offset1:231
	s_waitcnt lgkmcnt(0)
	v_cvt_pk_bf16_f32 v31, v32, v33
	v_lshl_add_u64 v[36:37], v[34:35], 0, v[156:157]
	ds_read2_b32 v[32:33], v21 offset0:8 offset1:41
	global_store_dwordx4 v[36:37], v[28:31], off sc1
	v_or_b32_e32 v36, v22, v38
	v_lshlrev_b32_e32 v156, 11, v36
	s_waitcnt lgkmcnt(0)
	v_cvt_pk_bf16_f32 v28, v32, v33
	ds_read2_b32 v[30:31], v21 offset0:74 offset1:107
	s_waitcnt lgkmcnt(0)
	v_cvt_pk_bf16_f32 v29, v30, v31
	ds_read2_b32 v[30:31], v21 offset0:140 offset1:173
	s_waitcnt lgkmcnt(0)
	v_cvt_pk_bf16_f32 v30, v30, v31
	ds_read2_b32 v[32:33], v21 offset0:206 offset1:239
	s_waitcnt lgkmcnt(0)
	v_cvt_pk_bf16_f32 v31, v32, v33
	v_lshl_add_u64 v[36:37], v[34:35], 0, v[156:157]
	ds_read2_b32 v[32:33], v21 offset0:16 offset1:49
	global_store_dwordx4 v[36:37], v[28:31], off sc1
	v_or_b32_e32 v36, v23, v38
	v_lshlrev_b32_e32 v156, 11, v36
	s_waitcnt lgkmcnt(0)
	v_cvt_pk_bf16_f32 v28, v32, v33
	ds_read2_b32 v[30:31], v21 offset0:82 offset1:115
	s_waitcnt lgkmcnt(0)
	v_cvt_pk_bf16_f32 v29, v30, v31
	ds_read2_b32 v[30:31], v21 offset0:148 offset1:181
	s_waitcnt lgkmcnt(0)
	v_cvt_pk_bf16_f32 v30, v30, v31
	ds_read2_b32 v[32:33], v21 offset0:214 offset1:247
	s_waitcnt lgkmcnt(0)
	v_cvt_pk_bf16_f32 v31, v32, v33
	v_lshl_add_u64 v[36:37], v[34:35], 0, v[156:157]
	ds_read2_b32 v[32:33], v21 offset0:24 offset1:57
	global_store_dwordx4 v[36:37], v[28:31], off sc1
	s_waitcnt lgkmcnt(0)
	s_nop 0
	v_cvt_pk_bf16_f32 v28, v32, v33
	ds_read2_b32 v[30:31], v21 offset0:90 offset1:123
	s_waitcnt lgkmcnt(0)
	v_cvt_pk_bf16_f32 v29, v30, v31
	ds_read2_b32 v[30:31], v21 offset0:156 offset1:189
	s_waitcnt lgkmcnt(0)
	v_cvt_pk_bf16_f32 v30, v30, v31
	ds_read2_b32 v[32:33], v21 offset0:222 offset1:255
	s_waitcnt lgkmcnt(0)
	v_cvt_pk_bf16_f32 v31, v32, v33
	v_or_b32_e32 v32, v24, v38
	v_lshlrev_b32_e32 v156, 11, v32
	v_lshl_add_u64 v[32:33], v[34:35], 0, v[156:157]
	global_store_dwordx4 v[32:33], v[28:31], off sc1
	s_waitcnt lgkmcnt(0)

.LBB0_611:
	s_andn2_saveexec_b64 s[6:7], s[6:7]
	s_cbranch_execz .LBB0_613
	s_load_dwordx2 s[24:25], s[0:1], 0xc0
	v_add_u32_e32 v28, 0x20e60, v27
	v_and_b32_e32 v47, 0x3e0, v26
	v_and_b32_e32 v46, 0x1ffc0, v28
	v_lshlrev_b32_e32 v156, 2, v47
	v_or_b32_e32 v30, v46, v3
	s_waitcnt lgkmcnt(0)
	v_lshl_add_u64 v[28:29], s[24:25], 0, v[156:157]
	v_lshlrev_b32_e32 v156, 2, v4
	v_lshl_add_u64 v[28:29], v[28:29], 0, v[156:157]
	v_lshlrev_b32_e32 v156, 12, v30
	v_lshl_add_u64 v[28:29], v[28:29], 0, v[156:157]
	s_movk_i32 s19, 0x2000
	v_add_co_u32_e32 v30, vcc, s19, v28
	s_movk_i32 s19, 0x4000
	s_nop 0
	v_addc_co_u32_e32 v31, vcc, 0, v29, vcc
	v_add_co_u32_e32 v32, vcc, s19, v28
	s_movk_i32 s19, 0x6000
	s_nop 0
	v_addc_co_u32_e32 v33, vcc, 0, v29, vcc
	v_add_co_u32_e32 v34, vcc, s19, v28
	s_mov_b32 s19, 0xa000
	s_nop 0
	v_addc_co_u32_e32 v35, vcc, 0, v29, vcc
	v_add_co_u32_e32 v36, vcc, s73, v28
	v_lshlrev_b32_e32 v156, 1, v46
	s_nop 0
	v_addc_co_u32_e32 v37, vcc, 0, v29, vcc
	v_add_co_u32_e32 v38, vcc, s19, v28
	s_mov_b32 s19, 0xc000
	s_nop 0
	v_addc_co_u32_e32 v39, vcc, 0, v29, vcc
	v_add_co_u32_e32 v40, vcc, s19, v28
	s_mov_b32 s19, 0xe000
	s_nop 0
	v_addc_co_u32_e32 v41, vcc, 0, v29, vcc
	v_add_co_u32_e32 v42, vcc, s19, v28
	s_mov_b32 s19, 0x10000
	s_nop 0
	v_addc_co_u32_e32 v43, vcc, 0, v29, vcc
	global_load_dword v48, v[28:29], off
	global_load_dword v49, v[30:31], off
	global_load_dword v50, v[32:33], off
	global_load_dword v51, v[34:35], off
	global_load_dword v52, v[36:37], off
	global_load_dword v53, v[38:39], off
	global_load_dword v54, v[40:41], off
	global_load_dword v55, v[42:43], off
	v_add_co_u32_e32 v30, vcc, s19, v28
	s_mov_b32 s19, 0x12000
	s_nop 0
	v_addc_co_u32_e32 v31, vcc, 0, v29, vcc
	v_add_co_u32_e32 v32, vcc, s19, v28
	s_mov_b32 s19, 0x14000
	s_nop 0
	v_addc_co_u32_e32 v33, vcc, 0, v29, vcc
	v_add_co_u32_e32 v34, vcc, s19, v28
	s_mov_b32 s19, 0x16000
	s_nop 0
	v_addc_co_u32_e32 v35, vcc, 0, v29, vcc
	v_add_co_u32_e32 v36, vcc, s19, v28
	s_mov_b32 s19, 0x18000
	s_nop 0
	v_addc_co_u32_e32 v37, vcc, 0, v29, vcc
	v_add_co_u32_e32 v38, vcc, s19, v28
	s_mov_b32 s19, 0x1a000
	s_nop 0
	v_addc_co_u32_e32 v39, vcc, 0, v29, vcc
	v_add_co_u32_e32 v40, vcc, s19, v28
	s_mov_b32 s19, 0x1c000
	s_nop 0
	v_addc_co_u32_e32 v41, vcc, 0, v29, vcc
	v_add_co_u32_e32 v42, vcc, s19, v28
	s_mov_b32 s19, 0x1e000
	s_nop 0
	v_addc_co_u32_e32 v43, vcc, 0, v29, vcc
	v_add_co_u32_e32 v44, vcc, s19, v28
	s_mov_b32 s19, 0x20000
	s_nop 0
	v_addc_co_u32_e32 v45, vcc, 0, v29, vcc
	global_load_dword v56, v[30:31], off
	global_load_dword v57, v[32:33], off
	global_load_dword v58, v[34:35], off
	global_load_dword v59, v[36:37], off
	global_load_dword v60, v[38:39], off
	global_load_dword v61, v[40:41], off
	global_load_dword v62, v[42:43], off
	global_load_dword v63, v[44:45], off
	v_add_co_u32_e32 v30, vcc, s19, v28
	s_mov_b32 s19, 0x22000
	s_nop 0
	v_addc_co_u32_e32 v31, vcc, 0, v29, vcc
	v_add_co_u32_e32 v32, vcc, s19, v28
	s_mov_b32 s19, 0x24000
	s_nop 0
	v_addc_co_u32_e32 v33, vcc, 0, v29, vcc
	v_add_co_u32_e32 v34, vcc, s19, v28
	s_mov_b32 s19, 0x26000
	s_nop 0
	v_addc_co_u32_e32 v35, vcc, 0, v29, vcc
	v_add_co_u32_e32 v36, vcc, s19, v28
	s_mov_b32 s19, 0x28000
	s_nop 0
	v_addc_co_u32_e32 v37, vcc, 0, v29, vcc
	v_add_co_u32_e32 v38, vcc, s19, v28
	s_mov_b32 s19, 0x2a000
	s_nop 0
	v_addc_co_u32_e32 v39, vcc, 0, v29, vcc
	v_add_co_u32_e32 v40, vcc, s19, v28
	s_mov_b32 s19, 0x2c000
	s_nop 0
	v_addc_co_u32_e32 v41, vcc, 0, v29, vcc
	v_add_co_u32_e32 v42, vcc, s19, v28
	s_mov_b32 s19, 0x2e000
	s_nop 0
	v_addc_co_u32_e32 v43, vcc, 0, v29, vcc
	v_add_co_u32_e32 v44, vcc, s19, v28
	s_mov_b32 s19, 0x30000
	s_nop 0
	v_addc_co_u32_e32 v45, vcc, 0, v29, vcc
	global_load_dword v64, v[30:31], off
	global_load_dword v65, v[32:33], off
	global_load_dword v66, v[34:35], off
	global_load_dword v67, v[36:37], off
	global_load_dword v68, v[38:39], off
	global_load_dword v69, v[40:41], off
	global_load_dword v70, v[42:43], off
	s_nop 0
	global_load_dword v44, v[44:45], off
	v_add_co_u32_e32 v30, vcc, s19, v28
	s_mov_b32 s19, 0x32000
	s_nop 0
	v_addc_co_u32_e32 v31, vcc, 0, v29, vcc
	v_add_co_u32_e32 v32, vcc, s19, v28
	s_mov_b32 s19, 0x34000
	s_nop 0
	v_addc_co_u32_e32 v33, vcc, 0, v29, vcc
	v_add_co_u32_e32 v34, vcc, s19, v28
	s_mov_b32 s19, 0x36000
	s_nop 0
	v_addc_co_u32_e32 v35, vcc, 0, v29, vcc
	v_add_co_u32_e32 v36, vcc, s19, v28
	s_mov_b32 s19, 0x38000
	s_nop 0
	v_addc_co_u32_e32 v37, vcc, 0, v29, vcc
	v_add_co_u32_e32 v38, vcc, s19, v28
	s_mov_b32 s19, 0x3a000
	s_nop 0
	v_addc_co_u32_e32 v39, vcc, 0, v29, vcc
	v_add_co_u32_e32 v40, vcc, s19, v28
	s_mov_b32 s19, 0x3c000
	s_nop 0
	v_addc_co_u32_e32 v41, vcc, 0, v29, vcc
	v_add_co_u32_e32 v42, vcc, s19, v28
	s_mov_b32 s19, 0x3e000
	s_nop 0
	v_addc_co_u32_e32 v43, vcc, 0, v29, vcc
	v_add_co_u32_e32 v28, vcc, s19, v28
	s_nop 1
	v_addc_co_u32_e32 v29, vcc, 0, v29, vcc
	global_load_dword v30, v[30:31], off
	s_nop 0
	global_load_dword v31, v[32:33], off
	s_nop 0
	global_load_dword v32, v[34:35], off
	global_load_dword v33, v[36:37], off
	s_nop 0
	global_load_dword v34, v[38:39], off
	global_load_dword v35, v[40:41], off
	global_load_dword v36, v[42:43], off
	s_nop 0
	global_load_dword v28, v[28:29], off
	v_add_u32_e32 v29, 0x400, v5
	s_waitcnt vmcnt(30)
	ds_write2_b32 v5, v48, v49 offset1:66
	s_waitcnt vmcnt(28)
	ds_write2_b32 v5, v50, v51 offset0:132 offset1:198
	s_waitcnt vmcnt(26)
	ds_write2_b32 v29, v52, v53 offset0:8 offset1:74
	s_waitcnt vmcnt(24)
	ds_write2_b32 v29, v54, v55 offset0:140 offset1:206
	v_add_u32_e32 v29, 0x800, v5
	s_waitcnt vmcnt(22)
	ds_write2_b32 v29, v56, v57 offset0:16 offset1:82
	s_waitcnt vmcnt(20)
	ds_write2_b32 v29, v58, v59 offset0:148 offset1:214
	v_add_u32_e32 v29, 0xc00, v5
	s_waitcnt vmcnt(18)
	ds_write2_b32 v29, v60, v61 offset0:24 offset1:90
	s_waitcnt vmcnt(16)
	ds_write2_b32 v29, v62, v63 offset0:156 offset1:222
	v_add_u32_e32 v29, 0x1000, v5
	s_waitcnt vmcnt(14)
	ds_write2_b32 v29, v64, v65 offset0:32 offset1:98
	s_waitcnt vmcnt(12)
	ds_write2_b32 v29, v66, v67 offset0:164 offset1:230
	v_add_u32_e32 v29, 0x1400, v5
	s_waitcnt vmcnt(10)
	ds_write2_b32 v29, v68, v69 offset0:40 offset1:106
	s_waitcnt vmcnt(8)
	ds_write2_b32 v29, v70, v44 offset0:172 offset1:238
	v_add_u32_e32 v29, 0x1800, v5
	s_waitcnt vmcnt(6)
	ds_write2_b32 v29, v30, v31 offset0:48 offset1:114
	s_waitcnt vmcnt(4)
	ds_write2_b32 v29, v32, v33 offset0:180 offset1:246
	v_add_u32_e32 v29, 0x1c00, v5
	s_waitcnt vmcnt(2)
	ds_write2_b32 v29, v34, v35 offset0:56 offset1:122
	s_waitcnt vmcnt(0)
	ds_write2_b32 v29, v36, v28 offset0:188 offset1:254
	s_waitcnt lgkmcnt(0)
	v_or_b32_e32 v36, v47, v19
	ds_read2_b32 v[28:29], v21 offset1:33
	v_mul_u32_u24_e32 v36, 0xb00, v36
	s_waitcnt lgkmcnt(0)
	v_cvt_pk_bf16_f32 v28, v28, v29
	ds_read2_b32 v[30:31], v21 offset0:66 offset1:99
	v_lshl_add_u64 v[34:35], v[10:11], 0, v[156:157]
	v_lshlrev_b32_e32 v156, 1, v36
	s_waitcnt lgkmcnt(0)
	v_cvt_pk_bf16_f32 v29, v30, v31
	ds_read2_b32 v[30:31], v21 offset0:132 offset1:165
	v_lshl_add_u64 v[36:37], v[34:35], 0, v[156:157]
	s_waitcnt lgkmcnt(0)
	v_cvt_pk_bf16_f32 v30, v30, v31
	ds_read2_b32 v[32:33], v21 offset0:198 offset1:231
	s_waitcnt lgkmcnt(0)
	v_cvt_pk_bf16_f32 v31, v32, v33
	global_store_dwordx4 v[36:37], v[28:31], off sc1
	v_or_b32_e32 v36, v47, v22
	v_mul_u32_u24_e32 v36, 0xb00, v36
	ds_read2_b32 v[32:33], v21 offset0:8 offset1:41
	s_waitcnt lgkmcnt(0)
	v_cvt_pk_bf16_f32 v28, v32, v33
	ds_read2_b32 v[30:31], v21 offset0:74 offset1:107
	v_lshlrev_b32_e32 v156, 1, v36
	s_waitcnt lgkmcnt(0)
	v_cvt_pk_bf16_f32 v29, v30, v31
	ds_read2_b32 v[30:31], v21 offset0:140 offset1:173
	v_lshl_add_u64 v[36:37], v[34:35], 0, v[156:157]
	s_waitcnt lgkmcnt(0)
	v_cvt_pk_bf16_f32 v30, v30, v31
	ds_read2_b32 v[32:33], v21 offset0:206 offset1:239
	s_waitcnt lgkmcnt(0)
	v_cvt_pk_bf16_f32 v31, v32, v33
	global_store_dwordx4 v[36:37], v[28:31], off sc1
	v_or_b32_e32 v36, v47, v23
	ds_read2_b32 v[32:33], v21 offset0:16 offset1:49
	s_waitcnt lgkmcnt(0)
	v_cvt_pk_bf16_f32 v28, v32, v33
	ds_read2_b32 v[30:31], v21 offset0:82 offset1:115
	v_mul_u32_u24_e32 v36, 0xb00, v36
	s_waitcnt lgkmcnt(0)
	v_cvt_pk_bf16_f32 v29, v30, v31
	ds_read2_b32 v[30:31], v21 offset0:148 offset1:181
	v_lshlrev_b32_e32 v156, 1, v36
	s_waitcnt lgkmcnt(0)
	v_cvt_pk_bf16_f32 v30, v30, v31
	ds_read2_b32 v[32:33], v21 offset0:214 offset1:247
	s_waitcnt lgkmcnt(0)
	v_cvt_pk_bf16_f32 v31, v32, v33
	v_lshl_add_u64 v[36:37], v[34:35], 0, v[156:157]
	ds_read2_b32 v[32:33], v21 offset0:24 offset1:57
	global_store_dwordx4 v[36:37], v[28:31], off sc1
	s_waitcnt lgkmcnt(0)
	s_nop 0
	v_cvt_pk_bf16_f32 v28, v32, v33
	ds_read2_b32 v[30:31], v21 offset0:90 offset1:123
	s_waitcnt lgkmcnt(0)
	v_cvt_pk_bf16_f32 v29, v30, v31
	ds_read2_b32 v[30:31], v21 offset0:156 offset1:189
	s_waitcnt lgkmcnt(0)
	v_cvt_pk_bf16_f32 v30, v30, v31
	ds_read2_b32 v[32:33], v21 offset0:222 offset1:255
	s_waitcnt lgkmcnt(0)
	v_cvt_pk_bf16_f32 v31, v32, v33
	v_or_b32_e32 v32, v47, v24
	v_mul_u32_u24_e32 v32, 0xb00, v32
	v_lshlrev_b32_e32 v156, 1, v32
	v_lshl_add_u64 v[32:33], v[34:35], 0, v[156:157]
	global_store_dwordx4 v[32:33], v[28:31], off sc1
	s_waitcnt lgkmcnt(0)

.LBB0_614:
	s_andn2_saveexec_b64 s[6:7], s[38:39]
	s_cbranch_execz .LBB0_616
	s_load_dwordx2 s[24:25], s[0:1], 0x40
	v_add_u32_e32 v28, 0x21960, v27
	v_and_b32_e32 v47, 0x3e0, v26
	v_and_b32_e32 v46, 0x1ffc0, v28
	v_lshlrev_b32_e32 v156, 2, v47
	v_or_b32_e32 v30, v46, v3
	s_waitcnt lgkmcnt(0)
	v_lshl_add_u64 v[28:29], s[24:25], 0, v[156:157]
	v_lshlrev_b32_e32 v156, 2, v4
	v_lshl_add_u64 v[28:29], v[28:29], 0, v[156:157]
	v_lshlrev_b32_e32 v156, 12, v30
	v_lshl_add_u64 v[28:29], v[28:29], 0, v[156:157]
	s_movk_i32 s19, 0x2000
	v_add_co_u32_e32 v30, vcc, s19, v28
	s_movk_i32 s19, 0x4000
	s_nop 0
	v_addc_co_u32_e32 v31, vcc, 0, v29, vcc
	v_add_co_u32_e32 v32, vcc, s19, v28
	s_movk_i32 s19, 0x6000
	s_nop 0
	v_addc_co_u32_e32 v33, vcc, 0, v29, vcc
	v_add_co_u32_e32 v34, vcc, s19, v28
	s_mov_b32 s19, 0xa000
	s_nop 0
	v_addc_co_u32_e32 v35, vcc, 0, v29, vcc
	v_add_co_u32_e32 v36, vcc, s73, v28
	v_lshlrev_b32_e32 v156, 1, v46
	s_nop 0
	v_addc_co_u32_e32 v37, vcc, 0, v29, vcc
	v_add_co_u32_e32 v38, vcc, s19, v28
	s_mov_b32 s19, 0xc000
	s_nop 0
	v_addc_co_u32_e32 v39, vcc, 0, v29, vcc
	v_add_co_u32_e32 v40, vcc, s19, v28
	s_mov_b32 s19, 0xe000
	s_nop 0
	v_addc_co_u32_e32 v41, vcc, 0, v29, vcc
	v_add_co_u32_e32 v42, vcc, s19, v28
	s_mov_b32 s19, 0x10000
	s_nop 0
	v_addc_co_u32_e32 v43, vcc, 0, v29, vcc
	global_load_dword v48, v[28:29], off
	global_load_dword v49, v[30:31], off
	global_load_dword v50, v[32:33], off
	global_load_dword v51, v[34:35], off
	global_load_dword v52, v[36:37], off
	global_load_dword v53, v[38:39], off
	global_load_dword v54, v[40:41], off
	global_load_dword v55, v[42:43], off
	v_add_co_u32_e32 v30, vcc, s19, v28
	s_mov_b32 s19, 0x12000
	s_nop 0
	v_addc_co_u32_e32 v31, vcc, 0, v29, vcc
	v_add_co_u32_e32 v32, vcc, s19, v28
	s_mov_b32 s19, 0x14000
	s_nop 0
	v_addc_co_u32_e32 v33, vcc, 0, v29, vcc
	v_add_co_u32_e32 v34, vcc, s19, v28
	s_mov_b32 s19, 0x16000
	s_nop 0
	v_addc_co_u32_e32 v35, vcc, 0, v29, vcc
	v_add_co_u32_e32 v36, vcc, s19, v28
	s_mov_b32 s19, 0x18000
	s_nop 0
	v_addc_co_u32_e32 v37, vcc, 0, v29, vcc
	v_add_co_u32_e32 v38, vcc, s19, v28
	s_mov_b32 s19, 0x1a000
	s_nop 0
	v_addc_co_u32_e32 v39, vcc, 0, v29, vcc
	v_add_co_u32_e32 v40, vcc, s19, v28
	s_mov_b32 s19, 0x1c000
	s_nop 0
	v_addc_co_u32_e32 v41, vcc, 0, v29, vcc
	v_add_co_u32_e32 v42, vcc, s19, v28
	s_mov_b32 s19, 0x1e000
	s_nop 0
	v_addc_co_u32_e32 v43, vcc, 0, v29, vcc
	v_add_co_u32_e32 v44, vcc, s19, v28
	s_mov_b32 s19, 0x20000
	s_nop 0
	v_addc_co_u32_e32 v45, vcc, 0, v29, vcc
	global_load_dword v56, v[30:31], off
	global_load_dword v57, v[32:33], off
	global_load_dword v58, v[34:35], off
	global_load_dword v59, v[36:37], off
	global_load_dword v60, v[38:39], off
	global_load_dword v61, v[40:41], off
	global_load_dword v62, v[42:43], off
	global_load_dword v63, v[44:45], off
	v_add_co_u32_e32 v30, vcc, s19, v28
	s_mov_b32 s19, 0x22000
	s_nop 0
	v_addc_co_u32_e32 v31, vcc, 0, v29, vcc
	v_add_co_u32_e32 v32, vcc, s19, v28
	s_mov_b32 s19, 0x24000
	s_nop 0
	v_addc_co_u32_e32 v33, vcc, 0, v29, vcc
	v_add_co_u32_e32 v34, vcc, s19, v28
	s_mov_b32 s19, 0x26000
	s_nop 0
	v_addc_co_u32_e32 v35, vcc, 0, v29, vcc
	v_add_co_u32_e32 v36, vcc, s19, v28
	s_mov_b32 s19, 0x28000
	s_nop 0
	v_addc_co_u32_e32 v37, vcc, 0, v29, vcc
	v_add_co_u32_e32 v38, vcc, s19, v28
	s_mov_b32 s19, 0x2a000
	s_nop 0
	v_addc_co_u32_e32 v39, vcc, 0, v29, vcc
	v_add_co_u32_e32 v40, vcc, s19, v28
	s_mov_b32 s19, 0x2c000
	s_nop 0
	v_addc_co_u32_e32 v41, vcc, 0, v29, vcc
	v_add_co_u32_e32 v42, vcc, s19, v28
	s_mov_b32 s19, 0x2e000
	s_nop 0
	v_addc_co_u32_e32 v43, vcc, 0, v29, vcc
	v_add_co_u32_e32 v44, vcc, s19, v28
	s_mov_b32 s19, 0x30000
	s_nop 0
	v_addc_co_u32_e32 v45, vcc, 0, v29, vcc
	global_load_dword v64, v[30:31], off
	global_load_dword v65, v[32:33], off
	global_load_dword v66, v[34:35], off
	global_load_dword v67, v[36:37], off
	global_load_dword v68, v[38:39], off
	global_load_dword v69, v[40:41], off
	global_load_dword v70, v[42:43], off
	s_nop 0
	global_load_dword v44, v[44:45], off
	v_add_co_u32_e32 v30, vcc, s19, v28
	s_mov_b32 s19, 0x32000
	s_nop 0
	v_addc_co_u32_e32 v31, vcc, 0, v29, vcc
	v_add_co_u32_e32 v32, vcc, s19, v28
	s_mov_b32 s19, 0x34000
	s_nop 0
	v_addc_co_u32_e32 v33, vcc, 0, v29, vcc
	v_add_co_u32_e32 v34, vcc, s19, v28
	s_mov_b32 s19, 0x36000
	s_nop 0
	v_addc_co_u32_e32 v35, vcc, 0, v29, vcc
	v_add_co_u32_e32 v36, vcc, s19, v28
	s_mov_b32 s19, 0x38000
	s_nop 0
	v_addc_co_u32_e32 v37, vcc, 0, v29, vcc
	v_add_co_u32_e32 v38, vcc, s19, v28
	s_mov_b32 s19, 0x3a000
	s_nop 0
	v_addc_co_u32_e32 v39, vcc, 0, v29, vcc
	v_add_co_u32_e32 v40, vcc, s19, v28
	s_mov_b32 s19, 0x3c000
	s_nop 0
	v_addc_co_u32_e32 v41, vcc, 0, v29, vcc
	v_add_co_u32_e32 v42, vcc, s19, v28
	s_mov_b32 s19, 0x3e000
	s_nop 0
	v_addc_co_u32_e32 v43, vcc, 0, v29, vcc
	v_add_co_u32_e32 v28, vcc, s19, v28
	s_nop 1
	v_addc_co_u32_e32 v29, vcc, 0, v29, vcc
	global_load_dword v30, v[30:31], off
	s_nop 0
	global_load_dword v31, v[32:33], off
	s_nop 0
	global_load_dword v32, v[34:35], off
	global_load_dword v33, v[36:37], off
	s_nop 0
	global_load_dword v34, v[38:39], off
	global_load_dword v35, v[40:41], off
	global_load_dword v36, v[42:43], off
	s_nop 0
	global_load_dword v28, v[28:29], off
	v_add_u32_e32 v29, 0x400, v5
	s_waitcnt vmcnt(30)
	ds_write2_b32 v5, v48, v49 offset1:66
	s_waitcnt vmcnt(28)
	ds_write2_b32 v5, v50, v51 offset0:132 offset1:198
	s_waitcnt vmcnt(26)
	ds_write2_b32 v29, v52, v53 offset0:8 offset1:74
	s_waitcnt vmcnt(24)
	ds_write2_b32 v29, v54, v55 offset0:140 offset1:206
	v_add_u32_e32 v29, 0x800, v5
	s_waitcnt vmcnt(22)
	ds_write2_b32 v29, v56, v57 offset0:16 offset1:82
	s_waitcnt vmcnt(20)
	ds_write2_b32 v29, v58, v59 offset0:148 offset1:214
	v_add_u32_e32 v29, 0xc00, v5
	s_waitcnt vmcnt(18)
	ds_write2_b32 v29, v60, v61 offset0:24 offset1:90
	s_waitcnt vmcnt(16)
	ds_write2_b32 v29, v62, v63 offset0:156 offset1:222
	v_add_u32_e32 v29, 0x1000, v5
	s_waitcnt vmcnt(14)
	ds_write2_b32 v29, v64, v65 offset0:32 offset1:98
	s_waitcnt vmcnt(12)
	ds_write2_b32 v29, v66, v67 offset0:164 offset1:230
	v_add_u32_e32 v29, 0x1400, v5
	s_waitcnt vmcnt(10)
	ds_write2_b32 v29, v68, v69 offset0:40 offset1:106
	s_waitcnt vmcnt(8)
	ds_write2_b32 v29, v70, v44 offset0:172 offset1:238
	v_add_u32_e32 v29, 0x1800, v5
	s_waitcnt vmcnt(6)
	ds_write2_b32 v29, v30, v31 offset0:48 offset1:114
	s_waitcnt vmcnt(4)
	ds_write2_b32 v29, v32, v33 offset0:180 offset1:246
	v_add_u32_e32 v29, 0x1c00, v5
	s_waitcnt vmcnt(2)
	ds_write2_b32 v29, v34, v35 offset0:56 offset1:122
	s_waitcnt vmcnt(0)
	ds_write2_b32 v29, v36, v28 offset0:188 offset1:254
	s_waitcnt lgkmcnt(0)
	v_or_b32_e32 v36, v47, v19
	ds_read2_b32 v[28:29], v21 offset1:33
	v_mul_u32_u24_e32 v36, 0xb00, v36
	s_waitcnt lgkmcnt(0)
	v_cvt_pk_bf16_f32 v28, v28, v29
	ds_read2_b32 v[30:31], v21 offset0:66 offset1:99
	v_lshl_add_u64 v[34:35], v[12:13], 0, v[156:157]
	v_lshlrev_b32_e32 v156, 1, v36
	s_waitcnt lgkmcnt(0)
	v_cvt_pk_bf16_f32 v29, v30, v31
	ds_read2_b32 v[30:31], v21 offset0:132 offset1:165
	v_lshl_add_u64 v[36:37], v[34:35], 0, v[156:157]
	s_waitcnt lgkmcnt(0)
	v_cvt_pk_bf16_f32 v30, v30, v31
	ds_read2_b32 v[32:33], v21 offset0:198 offset1:231
	s_waitcnt lgkmcnt(0)
	v_cvt_pk_bf16_f32 v31, v32, v33
	global_store_dwordx4 v[36:37], v[28:31], off sc1
	v_or_b32_e32 v36, v47, v22
	v_mul_u32_u24_e32 v36, 0xb00, v36
	ds_read2_b32 v[32:33], v21 offset0:8 offset1:41
	s_waitcnt lgkmcnt(0)
	v_cvt_pk_bf16_f32 v28, v32, v33
	ds_read2_b32 v[30:31], v21 offset0:74 offset1:107
	v_lshlrev_b32_e32 v156, 1, v36
	s_waitcnt lgkmcnt(0)
	v_cvt_pk_bf16_f32 v29, v30, v31
	ds_read2_b32 v[30:31], v21 offset0:140 offset1:173
	v_lshl_add_u64 v[36:37], v[34:35], 0, v[156:157]
	s_waitcnt lgkmcnt(0)
	v_cvt_pk_bf16_f32 v30, v30, v31
	ds_read2_b32 v[32:33], v21 offset0:206 offset1:239
	s_waitcnt lgkmcnt(0)
	v_cvt_pk_bf16_f32 v31, v32, v33
	global_store_dwordx4 v[36:37], v[28:31], off sc1
	v_or_b32_e32 v36, v47, v23
	ds_read2_b32 v[32:33], v21 offset0:16 offset1:49
	s_waitcnt lgkmcnt(0)
	v_cvt_pk_bf16_f32 v28, v32, v33
	ds_read2_b32 v[30:31], v21 offset0:82 offset1:115
	v_mul_u32_u24_e32 v36, 0xb00, v36
	s_waitcnt lgkmcnt(0)
	v_cvt_pk_bf16_f32 v29, v30, v31
	ds_read2_b32 v[30:31], v21 offset0:148 offset1:181
	v_lshlrev_b32_e32 v156, 1, v36
	s_waitcnt lgkmcnt(0)
	v_cvt_pk_bf16_f32 v30, v30, v31
	ds_read2_b32 v[32:33], v21 offset0:214 offset1:247
	s_waitcnt lgkmcnt(0)
	v_cvt_pk_bf16_f32 v31, v32, v33
	v_lshl_add_u64 v[36:37], v[34:35], 0, v[156:157]
	ds_read2_b32 v[32:33], v21 offset0:24 offset1:57
	global_store_dwordx4 v[36:37], v[28:31], off sc1
	s_waitcnt lgkmcnt(0)
	s_nop 0
	v_cvt_pk_bf16_f32 v28, v32, v33
	ds_read2_b32 v[30:31], v21 offset0:90 offset1:123
	s_waitcnt lgkmcnt(0)
	v_cvt_pk_bf16_f32 v29, v30, v31
	ds_read2_b32 v[30:31], v21 offset0:156 offset1:189
	s_waitcnt lgkmcnt(0)
	v_cvt_pk_bf16_f32 v30, v30, v31
	ds_read2_b32 v[32:33], v21 offset0:222 offset1:255
	s_waitcnt lgkmcnt(0)
	v_cvt_pk_bf16_f32 v31, v32, v33
	v_or_b32_e32 v32, v47, v24
	v_mul_u32_u24_e32 v32, 0xb00, v32
	v_lshlrev_b32_e32 v156, 1, v32
	v_lshl_add_u64 v[32:33], v[34:35], 0, v[156:157]
	global_store_dwordx4 v[32:33], v[28:31], off sc1
	s_waitcnt lgkmcnt(0)

.LBB0_617:
	s_andn2_saveexec_b64 s[6:7], s[36:37]
	s_cbranch_execz .LBB0_619
	v_add_u16_e32 v28, 0xf500, v1
	v_mul_u32_u24_e32 v29, 0xba2f, v28
	s_load_dwordx2 s[24:25], s[0:1], 0xb8
	v_lshrrev_b32_e32 v29, 23, v29
	v_mul_lo_u16_e32 v30, 0xb0, v29
	v_sub_u16_e32 v46, v28, v30
	v_lshlrev_b16_e32 v47, 6, v29
	v_lshlrev_b16_e32 v48, 5, v46
	v_or_b32_e32 v30, v3, v47
	v_lshlrev_b32_e32 v156, 2, v48
	s_waitcnt lgkmcnt(0)
	v_lshl_add_u64 v[28:29], s[24:25], 0, v[156:157]
	v_lshlrev_b32_e32 v156, 2, v4
	v_mul_u32_u24_e32 v30, 0x1600, v30
	v_lshl_add_u64 v[28:29], v[28:29], 0, v[156:157]
	v_lshlrev_b32_e32 v156, 2, v30
	v_lshl_add_u64 v[28:29], v[28:29], 0, v[156:157]
	s_mov_b32 s19, 0xb000
	v_add_co_u32_e32 v30, vcc, s19, v28
	s_mov_b32 s19, 0x16000
	s_nop 0
	v_addc_co_u32_e32 v31, vcc, 0, v29, vcc
	v_add_co_u32_e32 v32, vcc, s19, v28
	s_mov_b32 s19, 0x21000
	s_nop 0
	v_addc_co_u32_e32 v33, vcc, 0, v29, vcc
	v_add_co_u32_e32 v34, vcc, s19, v28
	s_mov_b32 s19, 0x2c000
	s_nop 0
	v_addc_co_u32_e32 v35, vcc, 0, v29, vcc
	v_add_co_u32_e32 v36, vcc, s19, v28
	s_mov_b32 s19, 0x37000
	s_nop 0
	v_addc_co_u32_e32 v37, vcc, 0, v29, vcc
	v_add_co_u32_e32 v38, vcc, s19, v28
	s_mov_b32 s19, 0x42000
	s_nop 0
	v_addc_co_u32_e32 v39, vcc, 0, v29, vcc
	v_add_co_u32_e32 v40, vcc, s19, v28
	s_mov_b32 s19, 0x4d000
	s_nop 0
	v_addc_co_u32_e32 v41, vcc, 0, v29, vcc
	v_add_co_u32_e32 v42, vcc, s19, v28
	s_mov_b32 s19, 0x58000
	s_nop 0
	v_addc_co_u32_e32 v43, vcc, 0, v29, vcc
	global_load_dword v49, v[28:29], off
	global_load_dword v50, v[30:31], off
	global_load_dword v51, v[32:33], off
	global_load_dword v52, v[34:35], off
	global_load_dword v53, v[36:37], off
	global_load_dword v54, v[38:39], off
	global_load_dword v55, v[40:41], off
	global_load_dword v56, v[42:43], off
	v_add_co_u32_e32 v30, vcc, s19, v28
	s_mov_b32 s19, 0x63000
	s_nop 0
	v_addc_co_u32_e32 v31, vcc, 0, v29, vcc
	v_add_co_u32_e32 v32, vcc, s19, v28
	s_mov_b32 s19, 0x6e000
	s_nop 0
	v_addc_co_u32_e32 v33, vcc, 0, v29, vcc
	v_add_co_u32_e32 v34, vcc, s19, v28
	s_mov_b32 s19, 0x79000
	s_nop 0
	v_addc_co_u32_e32 v35, vcc, 0, v29, vcc
	v_add_co_u32_e32 v36, vcc, s19, v28
	s_mov_b32 s19, 0x84000
	s_nop 0
	v_addc_co_u32_e32 v37, vcc, 0, v29, vcc
	v_add_co_u32_e32 v38, vcc, s19, v28
	s_mov_b32 s19, 0x8f000
	s_nop 0
	v_addc_co_u32_e32 v39, vcc, 0, v29, vcc
	v_add_co_u32_e32 v40, vcc, s19, v28
	s_mov_b32 s19, 0x9a000
	s_nop 0
	v_addc_co_u32_e32 v41, vcc, 0, v29, vcc
	v_add_co_u32_e32 v42, vcc, s19, v28
	s_mov_b32 s19, 0xa5000
	s_nop 0
	v_addc_co_u32_e32 v43, vcc, 0, v29, vcc
	v_add_co_u32_e32 v44, vcc, s19, v28
	s_mov_b32 s19, 0xb0000
	s_nop 0
	v_addc_co_u32_e32 v45, vcc, 0, v29, vcc
	global_load_dword v57, v[30:31], off
	global_load_dword v58, v[32:33], off
	global_load_dword v59, v[34:35], off
	global_load_dword v60, v[36:37], off
	global_load_dword v61, v[38:39], off
	global_load_dword v62, v[40:41], off
	global_load_dword v63, v[42:43], off
	global_load_dword v64, v[44:45], off
	v_add_co_u32_e32 v30, vcc, s19, v28
	s_mov_b32 s19, 0xbb000
	s_nop 0
	v_addc_co_u32_e32 v31, vcc, 0, v29, vcc
	v_add_co_u32_e32 v32, vcc, s19, v28
	s_mov_b32 s19, 0xc6000
	s_nop 0
	v_addc_co_u32_e32 v33, vcc, 0, v29, vcc
	v_add_co_u32_e32 v34, vcc, s19, v28
	s_mov_b32 s19, 0xd1000
	s_nop 0
	v_addc_co_u32_e32 v35, vcc, 0, v29, vcc
	v_add_co_u32_e32 v36, vcc, s19, v28
	s_mov_b32 s19, 0xdc000
	s_nop 0
	v_addc_co_u32_e32 v37, vcc, 0, v29, vcc
	v_add_co_u32_e32 v38, vcc, s19, v28
	s_mov_b32 s19, 0xe7000
	s_nop 0
	v_addc_co_u32_e32 v39, vcc, 0, v29, vcc
	v_add_co_u32_e32 v40, vcc, s19, v28
	s_mov_b32 s19, 0xf2000
	s_nop 0
	v_addc_co_u32_e32 v41, vcc, 0, v29, vcc
	v_add_co_u32_e32 v42, vcc, s19, v28
	s_mov_b32 s19, 0xfd000
	s_nop 0
	v_addc_co_u32_e32 v43, vcc, 0, v29, vcc
	v_add_co_u32_e32 v44, vcc, s19, v28
	s_mov_b32 s19, 0x108000
	s_nop 0
	v_addc_co_u32_e32 v45, vcc, 0, v29, vcc
	global_load_dword v65, v[30:31], off
	global_load_dword v66, v[32:33], off
	global_load_dword v67, v[34:35], off
	global_load_dword v68, v[36:37], off
	global_load_dword v69, v[38:39], off
	global_load_dword v70, v[40:41], off
	global_load_dword v71, v[42:43], off
	s_nop 0
	global_load_dword v44, v[44:45], off
	v_add_co_u32_e32 v30, vcc, s19, v28
	s_mov_b32 s19, 0x113000
	s_nop 0
	v_addc_co_u32_e32 v31, vcc, 0, v29, vcc
	v_add_co_u32_e32 v32, vcc, s19, v28
	s_mov_b32 s19, 0x11e000
	s_nop 0
	v_addc_co_u32_e32 v33, vcc, 0, v29, vcc
	v_add_co_u32_e32 v34, vcc, s19, v28
	s_mov_b32 s19, 0x129000
	s_nop 0
	v_addc_co_u32_e32 v35, vcc, 0, v29, vcc
	v_add_co_u32_e32 v36, vcc, s19, v28
	s_mov_b32 s19, 0x134000
	s_nop 0
	v_addc_co_u32_e32 v37, vcc, 0, v29, vcc
	v_add_co_u32_e32 v38, vcc, s19, v28
	s_mov_b32 s19, 0x13f000
	s_nop 0
	v_addc_co_u32_e32 v39, vcc, 0, v29, vcc
	v_add_co_u32_e32 v40, vcc, s19, v28
	s_mov_b32 s19, 0x14a000
	s_nop 0
	v_addc_co_u32_e32 v41, vcc, 0, v29, vcc
	v_add_co_u32_e32 v42, vcc, s19, v28
	s_mov_b32 s19, 0x155000
	s_nop 0
	v_addc_co_u32_e32 v43, vcc, 0, v29, vcc
	v_add_co_u32_e32 v28, vcc, s19, v28
	s_movk_i32 s19, 0x57
	s_nop 0
	v_addc_co_u32_e32 v29, vcc, 0, v29, vcc
	global_load_dword v30, v[30:31], off
	s_nop 0
	global_load_dword v31, v[32:33], off
	s_nop 0
	global_load_dword v32, v[34:35], off
	global_load_dword v33, v[36:37], off
	s_nop 0
	global_load_dword v34, v[38:39], off
	global_load_dword v35, v[40:41], off
	global_load_dword v36, v[42:43], off
	s_nop 0
	global_load_dword v28, v[28:29], off
	v_add_u32_e32 v29, 0x400, v5
	s_waitcnt vmcnt(30)
	ds_write2_b32 v5, v49, v50 offset1:66
	s_waitcnt vmcnt(28)
	ds_write2_b32 v5, v51, v52 offset0:132 offset1:198
	s_waitcnt vmcnt(26)
	ds_write2_b32 v29, v53, v54 offset0:8 offset1:74
	s_waitcnt vmcnt(24)
	ds_write2_b32 v29, v55, v56 offset0:140 offset1:206
	v_add_u32_e32 v29, 0x800, v5
	s_waitcnt vmcnt(22)
	ds_write2_b32 v29, v57, v58 offset0:16 offset1:82
	s_waitcnt vmcnt(20)
	ds_write2_b32 v29, v59, v60 offset0:148 offset1:214
	v_add_u32_e32 v29, 0xc00, v5
	s_waitcnt vmcnt(18)
	ds_write2_b32 v29, v61, v62 offset0:24 offset1:90
	s_waitcnt vmcnt(16)
	ds_write2_b32 v29, v63, v64 offset0:156 offset1:222
	v_add_u32_e32 v29, 0x1000, v5
	s_waitcnt vmcnt(14)
	ds_write2_b32 v29, v65, v66 offset0:32 offset1:98
	s_waitcnt vmcnt(12)
	ds_write2_b32 v29, v67, v68 offset0:164 offset1:230
	v_add_u32_e32 v29, 0x1400, v5
	s_waitcnt vmcnt(10)
	ds_write2_b32 v29, v69, v70 offset0:40 offset1:106
	s_waitcnt vmcnt(8)
	ds_write2_b32 v29, v71, v44 offset0:172 offset1:238
	v_add_u32_e32 v29, 0x1800, v5
	s_waitcnt vmcnt(6)
	ds_write2_b32 v29, v30, v31 offset0:48 offset1:114
	s_waitcnt vmcnt(4)
	ds_write2_b32 v29, v32, v33 offset0:180 offset1:246
	v_add_u32_e32 v29, 0x1c00, v5
	s_waitcnt vmcnt(2)
	ds_write2_b32 v29, v34, v35 offset0:56 offset1:122
	s_waitcnt vmcnt(0)
	ds_write2_b32 v29, v36, v28 offset0:188 offset1:254
	s_waitcnt lgkmcnt(0)
	ds_read2_b32 v[28:29], v21 offset1:33
	s_waitcnt lgkmcnt(0)
	v_cvt_pk_bf16_f32 v28, v28, v29
	ds_read2_b32 v[30:31], v21 offset0:66 offset1:99
	s_waitcnt lgkmcnt(0)
	v_cvt_pk_bf16_f32 v29, v30, v31
	ds_read2_b32 v[30:31], v21 offset0:132 offset1:165
	s_waitcnt lgkmcnt(0)
	v_cvt_pk_bf16_f32 v30, v30, v31
	ds_read2_b32 v[32:33], v21 offset0:198 offset1:231
	v_cmp_lt_u16_e32 vcc, s19, v46
	s_waitcnt lgkmcnt(0)
	v_cvt_pk_bf16_f32 v31, v32, v33
	v_bitop3_b32 v42, v19, s59, v48 bitop3:0xc8
	v_lshlrev_b32_e32 v156, 1, v47
	v_cndmask_b32_e32 v32, 0, v210, vcc
	v_add_lshl_u32 v32, v32, v48, 1
	v_cndmask_b32_e32 v41, 0, v211, vcc
	v_and_b32_e32 v40, 0xffffff00, v32
	v_or_b32_e32 v32, v41, v25
	v_or3_b32 v32, v32, v42, v40
	v_ashrrev_i32_e32 v33, 31, v32
	v_lshl_add_u64 v[34:35], v[14:15], 0, v[156:157]
	v_lshlrev_b64 v[38:39], 11, v[32:33]
	v_lshl_add_u64 v[38:39], v[34:35], 0, v[38:39]
	ds_read2_b32 v[36:37], v21 offset0:8 offset1:41
	global_store_dwordx4 v[38:39], v[28:31], off sc1
	s_waitcnt lgkmcnt(0)
	s_nop 0
	v_cvt_pk_bf16_f32 v28, v36, v37
	ds_read2_b32 v[30:31], v21 offset0:74 offset1:107
	s_waitcnt lgkmcnt(0)
	v_cvt_pk_bf16_f32 v29, v30, v31
	ds_read2_b32 v[30:31], v21 offset0:140 offset1:173
	s_waitcnt lgkmcnt(0)
	v_cvt_pk_bf16_f32 v30, v30, v31
	ds_read2_b32 v[36:37], v21 offset0:206 offset1:239
	s_waitcnt lgkmcnt(0)
	v_cvt_pk_bf16_f32 v31, v36, v37
	v_or_b32_e32 v36, 4, v32
	v_ashrrev_i32_e32 v37, 31, v36
	v_lshlrev_b64 v[36:37], 11, v[36:37]
	v_lshl_add_u64 v[36:37], v[34:35], 0, v[36:37]
	v_or_b32_e32 v32, 8, v32
	ds_read2_b32 v[38:39], v21 offset0:16 offset1:49
	global_store_dwordx4 v[36:37], v[28:31], off sc1
	v_ashrrev_i32_e32 v33, 31, v32
	v_lshlrev_b64 v[32:33], 11, v[32:33]
	s_waitcnt lgkmcnt(0)
	v_cvt_pk_bf16_f32 v28, v38, v39
	ds_read2_b32 v[30:31], v21 offset0:82 offset1:115
	s_waitcnt lgkmcnt(0)
	v_cvt_pk_bf16_f32 v29, v30, v31
	ds_read2_b32 v[30:31], v21 offset0:148 offset1:181
	s_waitcnt lgkmcnt(0)
	v_cvt_pk_bf16_f32 v30, v30, v31
	ds_read2_b32 v[36:37], v21 offset0:214 offset1:247
	s_waitcnt lgkmcnt(0)
	v_cvt_pk_bf16_f32 v31, v36, v37
	v_lshl_add_u64 v[32:33], v[34:35], 0, v[32:33]
	ds_read2_b32 v[36:37], v21 offset0:24 offset1:57
	global_store_dwordx4 v[32:33], v[28:31], off sc1
	s_waitcnt lgkmcnt(0)
	s_nop 0
	v_cvt_pk_bf16_f32 v28, v36, v37
	ds_read2_b32 v[30:31], v21 offset0:90 offset1:123
	s_waitcnt lgkmcnt(0)
	v_cvt_pk_bf16_f32 v29, v30, v31
	ds_read2_b32 v[30:31], v21 offset0:156 offset1:189
	s_waitcnt lgkmcnt(0)
	v_cvt_pk_bf16_f32 v30, v30, v31
	ds_read2_b32 v[32:33], v21 offset0:222 offset1:255
	s_waitcnt lgkmcnt(0)
	v_cvt_pk_bf16_f32 v31, v32, v33
	v_or3_b32 v32, v20, v41, v42
	v_or3_b32 v32, v32, v40, 12
	v_ashrrev_i32_e32 v33, 31, v32
	v_lshlrev_b64 v[32:33], 11, v[32:33]
	v_lshl_add_u64 v[32:33], v[34:35], 0, v[32:33]
	global_store_dwordx4 v[32:33], v[28:31], off sc1
	s_waitcnt lgkmcnt(0)

.LBB0_620:
	s_andn2_saveexec_b64 s[6:7], s[34:35]
	s_cbranch_execz .LBB0_601
	s_mov_b32 s19, 0x2e8ba2e9
	v_mul_hi_i32 v28, v1, s19
	s_load_dwordx2 s[24:25], s[0:1], 0x38
	v_lshrrev_b32_e32 v29, 31, v28
	v_ashrrev_i32_e32 v28, 5, v28
	v_add_u32_e32 v48, v28, v29
	s_movk_i32 s19, 0xea00
	v_mul_lo_u32 v49, v48, s19
	v_add_u32_e32 v28, v26, v49
	v_lshlrev_b32_e32 v32, 6, v48
	v_ashrrev_i32_e32 v29, 31, v28
	v_or_b32_e32 v33, v32, v3
	s_waitcnt lgkmcnt(0)
	v_lshl_add_u64 v[28:29], v[28:29], 2, s[24:25]
	v_lshlrev_b32_e32 v156, 2, v4
	v_lshl_add_u64 v[28:29], v[28:29], 0, v[156:157]
	v_or_b32_e32 v34, 2, v33
	v_or_b32_e32 v36, 4, v33
	v_or_b32_e32 v38, 6, v33
	v_or_b32_e32 v40, 8, v33
	v_or_b32_e32 v42, 10, v33
	v_or_b32_e32 v44, 12, v33
	v_or_b32_e32 v46, 14, v33
	v_mad_i64_i32 v[30:31], s[24:25], v33, s75, v[28:29]
	v_mad_i64_i32 v[34:35], s[24:25], v34, s75, v[28:29]
	v_mad_i64_i32 v[36:37], s[24:25], v36, s75, v[28:29]
	v_mad_i64_i32 v[38:39], s[24:25], v38, s75, v[28:29]
	v_mad_i64_i32 v[40:41], s[24:25], v40, s75, v[28:29]
	v_mad_i64_i32 v[42:43], s[24:25], v42, s75, v[28:29]
	v_mad_i64_i32 v[44:45], s[24:25], v44, s75, v[28:29]
	v_mad_i64_i32 v[46:47], s[24:25], v46, s75, v[28:29]
	global_load_dword v50, v[30:31], off
	global_load_dword v51, v[34:35], off
	global_load_dword v52, v[36:37], off
	global_load_dword v53, v[38:39], off
	global_load_dword v54, v[40:41], off
	global_load_dword v55, v[42:43], off
	global_load_dword v56, v[44:45], off
	global_load_dword v57, v[46:47], off
	v_or_b32_e32 v30, 16, v33
	v_or_b32_e32 v34, 18, v33
	v_or_b32_e32 v36, 20, v33
	v_or_b32_e32 v38, 22, v33
	v_or_b32_e32 v40, 24, v33
	v_or_b32_e32 v42, 26, v33
	v_or_b32_e32 v44, 28, v33
	v_or_b32_e32 v46, 30, v33
	v_mad_i64_i32 v[30:31], s[24:25], v30, s75, v[28:29]
	v_mad_i64_i32 v[34:35], s[24:25], v34, s75, v[28:29]
	v_mad_i64_i32 v[36:37], s[24:25], v36, s75, v[28:29]
	v_mad_i64_i32 v[38:39], s[24:25], v38, s75, v[28:29]
	v_mad_i64_i32 v[40:41], s[24:25], v40, s75, v[28:29]
	v_mad_i64_i32 v[42:43], s[24:25], v42, s75, v[28:29]
	v_mad_i64_i32 v[44:45], s[24:25], v44, s75, v[28:29]
	v_mad_i64_i32 v[46:47], s[24:25], v46, s75, v[28:29]
	global_load_dword v58, v[30:31], off
	global_load_dword v59, v[34:35], off
	global_load_dword v60, v[36:37], off
	global_load_dword v61, v[38:39], off
	global_load_dword v62, v[40:41], off
	global_load_dword v63, v[42:43], off
	global_load_dword v64, v[44:45], off
	global_load_dword v65, v[46:47], off
	v_or_b32_e32 v30, 32, v33
	v_or_b32_e32 v34, 34, v33
	v_or_b32_e32 v36, 36, v33
	v_or_b32_e32 v38, 38, v33
	v_or_b32_e32 v40, 40, v33
	v_or_b32_e32 v42, 42, v33
	v_or_b32_e32 v44, 44, v33
	v_or_b32_e32 v46, 46, v33
	v_mad_i64_i32 v[30:31], s[24:25], v30, s75, v[28:29]
	v_mad_i64_i32 v[34:35], s[24:25], v34, s75, v[28:29]
	v_mad_i64_i32 v[36:37], s[24:25], v36, s75, v[28:29]
	v_mad_i64_i32 v[38:39], s[24:25], v38, s75, v[28:29]
	v_mad_i64_i32 v[40:41], s[24:25], v40, s75, v[28:29]
	v_mad_i64_i32 v[42:43], s[24:25], v42, s75, v[28:29]
	v_mad_i64_i32 v[44:45], s[24:25], v44, s75, v[28:29]
	v_mad_i64_i32 v[46:47], s[24:25], v46, s75, v[28:29]
	global_load_dword v66, v[30:31], off
	global_load_dword v67, v[34:35], off
	global_load_dword v68, v[36:37], off
	global_load_dword v69, v[38:39], off
	global_load_dword v70, v[40:41], off
	global_load_dword v71, v[42:43], off
	global_load_dword v72, v[44:45], off
	s_nop 0
	global_load_dword v46, v[46:47], off
	v_or_b32_e32 v30, 48, v33
	v_or_b32_e32 v34, 50, v33
	v_or_b32_e32 v36, 52, v33
	v_or_b32_e32 v38, 54, v33
	v_or_b32_e32 v40, 56, v33
	v_or_b32_e32 v42, 58, v33
	v_or_b32_e32 v44, 60, v33
	v_or_b32_e32 v33, 62, v33
	v_mad_i64_i32 v[30:31], s[24:25], v30, s75, v[28:29]
	v_mad_i64_i32 v[34:35], s[24:25], v34, s75, v[28:29]
	v_mad_i64_i32 v[36:37], s[24:25], v36, s75, v[28:29]
	v_mad_i64_i32 v[38:39], s[24:25], v38, s75, v[28:29]
	v_mad_i64_i32 v[40:41], s[24:25], v40, s75, v[28:29]
	v_mad_i64_i32 v[42:43], s[24:25], v42, s75, v[28:29]
	v_mad_i64_i32 v[44:45], s[24:25], v44, s75, v[28:29]
	v_mad_i64_i32 v[28:29], s[24:25], v33, s75, v[28:29]
	global_load_dword v30, v[30:31], off
	s_nop 0
	global_load_dword v31, v[34:35], off
	global_load_dword v33, v[36:37], off
	s_nop 0
	global_load_dword v34, v[38:39], off
	global_load_dword v35, v[40:41], off
	global_load_dword v36, v[42:43], off
	global_load_dword v37, v[44:45], off
	s_nop 0
	global_load_dword v28, v[28:29], off
	v_add_u32_e32 v29, 0x400, v5
	s_waitcnt vmcnt(30)
	ds_write2_b32 v5, v50, v51 offset1:66
	s_waitcnt vmcnt(28)
	ds_write2_b32 v5, v52, v53 offset0:132 offset1:198
	s_waitcnt vmcnt(26)
	ds_write2_b32 v29, v54, v55 offset0:8 offset1:74
	s_waitcnt vmcnt(24)
	ds_write2_b32 v29, v56, v57 offset0:140 offset1:206
	v_add_u32_e32 v29, 0x800, v5
	s_waitcnt vmcnt(22)
	ds_write2_b32 v29, v58, v59 offset0:16 offset1:82
	s_waitcnt vmcnt(20)
	ds_write2_b32 v29, v60, v61 offset0:148 offset1:214
	v_add_u32_e32 v29, 0xc00, v5
	s_waitcnt vmcnt(18)
	ds_write2_b32 v29, v62, v63 offset0:24 offset1:90
	s_waitcnt vmcnt(16)
	ds_write2_b32 v29, v64, v65 offset0:156 offset1:222
	v_add_u32_e32 v29, 0x1000, v5
	s_waitcnt vmcnt(14)
	ds_write2_b32 v29, v66, v67 offset0:32 offset1:98
	s_waitcnt vmcnt(12)
	ds_write2_b32 v29, v68, v69 offset0:164 offset1:230
	v_add_u32_e32 v29, 0x1400, v5
	s_waitcnt vmcnt(10)
	ds_write2_b32 v29, v70, v71 offset0:40 offset1:106
	s_waitcnt vmcnt(8)
	ds_write2_b32 v29, v72, v46 offset0:172 offset1:238
	v_add_u32_e32 v29, 0x1800, v5
	s_waitcnt vmcnt(6)
	ds_write2_b32 v29, v30, v31 offset0:48 offset1:114
	s_waitcnt vmcnt(4)
	ds_write2_b32 v29, v33, v34 offset0:180 offset1:246
	v_add_u32_e32 v29, 0x1c00, v5
	s_waitcnt vmcnt(2)
	ds_write2_b32 v29, v35, v36 offset0:56 offset1:122
	s_waitcnt vmcnt(0)
	ds_write2_b32 v29, v37, v28 offset0:188 offset1:254
	s_waitcnt lgkmcnt(0)
	ds_read2_b32 v[28:29], v21 offset1:33
	s_waitcnt lgkmcnt(0)
	v_cvt_pk_bf16_f32 v28, v28, v29
	ds_read2_b32 v[30:31], v21 offset0:66 offset1:99
	v_add_u32_e32 v40, v19, v26
	s_waitcnt lgkmcnt(0)
	v_cvt_pk_bf16_f32 v29, v30, v31
	ds_read2_b32 v[30:31], v21 offset0:132 offset1:165
	v_add_u32_e32 v41, v40, v49
	s_waitcnt lgkmcnt(0)
	v_cvt_pk_bf16_f32 v30, v30, v31
	ds_read2_b32 v[34:35], v21 offset0:198 offset1:231
	v_cmp_lt_i32_e32 vcc, s22, v41
	s_waitcnt lgkmcnt(0)
	v_cvt_pk_bf16_f32 v31, v34, v35
	v_mul_lo_u32 v42, v48, s33
	s_movk_i32 s19, 0xa800
	v_cndmask_b32_e32 v34, 0, v210, vcc
	v_sub_u32_e32 v34, v34, v42
	v_add_lshl_u32 v34, v40, v34, 1
	v_and_b32_e32 v36, 0xffffff00, v34
	v_cndmask_b32_e32 v37, 0, v211, vcc
	v_mad_u64_u32 v[34:35], s[24:25], v48, s19, v[18:19]
	v_and_b32_e32 v35, 16, v34
	v_and_or_b32 v37, v41, s59, v37
	v_or3_b32 v36, v37, v35, v36
	v_ashrrev_i32_e32 v33, 31, v32
	v_ashrrev_i32_e32 v37, 31, v36
	v_lshl_add_u64 v[32:33], v[32:33], 1, v[16:17]
	v_lshlrev_b64 v[36:37], 11, v[36:37]
	v_lshl_add_u64 v[36:37], v[32:33], 0, v[36:37]
	ds_read2_b32 v[38:39], v21 offset0:8 offset1:41
	global_store_dwordx4 v[36:37], v[28:31], off sc1
	v_add_u32_e32 v35, 8, v41
	v_cmp_lt_i32_e32 vcc, s22, v35
	s_waitcnt lgkmcnt(0)
	v_cvt_pk_bf16_f32 v28, v38, v39
	ds_read2_b32 v[30:31], v21 offset0:74 offset1:107
	s_waitcnt lgkmcnt(0)
	v_cvt_pk_bf16_f32 v29, v30, v31
	ds_read2_b32 v[30:31], v21 offset0:140 offset1:173
	s_waitcnt lgkmcnt(0)
	v_cvt_pk_bf16_f32 v30, v30, v31
	ds_read2_b32 v[36:37], v21 offset0:206 offset1:239
	s_waitcnt lgkmcnt(0)
	v_cvt_pk_bf16_f32 v31, v36, v37
	v_cndmask_b32_e32 v36, 0, v210, vcc
	v_sub_u32_e32 v36, v36, v42
	v_add_u32_e32 v36, v40, v36
	v_add_u32_e32 v38, 32, v34
	v_lshl_add_u32 v36, v36, 1, 16
	v_cndmask_b32_e32 v37, 0, v211, vcc
	v_and_b32_e32 v38, 16, v38
	v_and_b32_e32 v35, 0x63, v35
	v_and_b32_e32 v36, 0xffffff00, v36
	v_or3_b32 v35, v35, v37, v38
	v_or3_b32 v36, v35, v36, 4
	v_ashrrev_i32_e32 v37, 31, v36
	v_lshlrev_b64 v[36:37], 11, v[36:37]
	v_lshl_add_u64 v[36:37], v[32:33], 0, v[36:37]
	ds_read2_b32 v[38:39], v21 offset0:16 offset1:49
	global_store_dwordx4 v[36:37], v[28:31], off sc1
	v_add_u32_e32 v35, 16, v41
	v_cmp_lt_i32_e32 vcc, s22, v35
	s_waitcnt lgkmcnt(0)
	v_cvt_pk_bf16_f32 v28, v38, v39
	ds_read2_b32 v[30:31], v21 offset0:82 offset1:115
	s_waitcnt lgkmcnt(0)
	v_cvt_pk_bf16_f32 v29, v30, v31
	ds_read2_b32 v[30:31], v21 offset0:148 offset1:181
	s_waitcnt lgkmcnt(0)
	v_cvt_pk_bf16_f32 v30, v30, v31
	ds_read2_b32 v[36:37], v21 offset0:214 offset1:247
	s_waitcnt lgkmcnt(0)
	v_cvt_pk_bf16_f32 v31, v36, v37
	v_cndmask_b32_e32 v36, 0, v210, vcc
	v_sub_u32_e32 v36, v36, v42
	v_add_u32_e32 v36, v40, v36
	v_add_u32_e32 v38, 64, v34
	v_lshl_add_u32 v36, v36, 1, 32
	v_cndmask_b32_e32 v37, 0, v211, vcc
	v_and_b32_e32 v38, 16, v38
	v_and_b32_e32 v35, 0x63, v35
	v_and_b32_e32 v36, 0xffffff00, v36
	v_or3_b32 v35, v35, v37, v38
	v_or3_b32 v36, v35, v36, 8
	v_ashrrev_i32_e32 v37, 31, v36
	v_lshlrev_b64 v[36:37], 11, v[36:37]
	v_lshl_add_u64 v[36:37], v[32:33], 0, v[36:37]
	ds_read2_b32 v[38:39], v21 offset0:24 offset1:57
	global_store_dwordx4 v[36:37], v[28:31], off sc1
	v_add_u32_e32 v35, 24, v41
	v_cmp_lt_i32_e32 vcc, s22, v35
	s_waitcnt lgkmcnt(0)
	v_cvt_pk_bf16_f32 v28, v38, v39
	ds_read2_b32 v[30:31], v21 offset0:90 offset1:123
	s_waitcnt lgkmcnt(0)
	v_cvt_pk_bf16_f32 v29, v30, v31
	ds_read2_b32 v[30:31], v21 offset0:156 offset1:189
	s_waitcnt lgkmcnt(0)
	v_cvt_pk_bf16_f32 v30, v30, v31
	ds_read2_b32 v[36:37], v21 offset0:222 offset1:255
	s_waitcnt lgkmcnt(0)
	v_cvt_pk_bf16_f32 v31, v36, v37
	v_cndmask_b32_e32 v36, 0, v210, vcc
	v_sub_u32_e32 v36, v36, v42
	v_add_u32_e32 v36, v40, v36
	v_add_u32_e32 v34, 0x60, v34
	v_lshl_add_u32 v36, v36, 1, 48
	v_cndmask_b32_e32 v37, 0, v211, vcc
	v_and_b32_e32 v34, 16, v34
	v_and_b32_e32 v35, 0x63, v35
	v_and_b32_e32 v36, 0xffffff00, v36
	v_or3_b32 v34, v35, v37, v34
	v_or3_b32 v34, v34, v36, 12
	v_ashrrev_i32_e32 v35, 31, v34
	v_lshlrev_b64 v[34:35], 11, v[34:35]
	v_lshl_add_u64 v[32:33], v[32:33], 0, v[34:35]
	global_store_dwordx4 v[32:33], v[28:31], off sc1
	s_waitcnt lgkmcnt(0)
	s_branch .LBB0_601

.LBB0_624:
	v_bfe_u32 v3, v8, 8, 11
	v_and_b32_e32 v10, 0x7f8, v1
	v_mul_u32_u24_e32 v11, v10, v3
	v_mad_u32_u24 v10, v10, v3, v3
	v_and_b32_e32 v12, 0xfff, v10
	v_add_u32_e32 v10, v10, v3
	v_and_b32_e32 v11, 0xff8, v11
	v_and_b32_e32 v13, 0xffe, v10
	v_add_u32_e32 v10, v10, v3
	v_cvt_f32_u32_e32 v11, v11
	v_cvt_f32_u32_e32 v12, v12
	v_and_b32_e32 v14, 0xfff, v10
	v_add_u32_e32 v10, v10, v3
	v_cvt_f32_u32_e32 v13, v13
	v_and_b32_e32 v15, 0xffc, v10
	v_add_u32_e32 v10, v10, v3
	v_cvt_f32_u32_e32 v14, v14
	v_and_b32_e32 v16, 0xfff, v10
	v_add_u32_e32 v10, v10, v3
	v_and_b32_e32 v17, 0xffe, v10
	v_add_u32_e32 v3, v10, v3
	v_mul_f32_e32 v11, 0x39800000, v11
	v_mul_f32_e32 v12, 0x39800000, v12
	v_cvt_f32_u32_e32 v16, v16
	v_cvt_f32_u32_e32 v17, v17
	v_and_b32_e32 v3, 0xfff, v3
	v_cvt_f32_u32_e32 v15, v15
	v_sin_f32_e32 v10, v11
	v_cos_f32_e32 v11, v11
	v_sin_f32_e32 v18, v12
	v_cos_f32_e32 v12, v12
	v_mul_f32_e32 v13, 0x39800000, v13
	v_cvt_f32_u32_e32 v3, v3
	v_sin_f32_e32 v19, v13
	v_cos_f32_e32 v13, v13
	v_mul_f32_e32 v14, 0x39800000, v14
	s_mov_b64 s[24:25], 0x80000
	v_sin_f32_e32 v20, v14
	v_cos_f32_e32 v14, v14
	v_cmp_gt_u64_e32 vcc, s[24:25], v[8:9]
	v_mul_f32_e32 v16, 0x39800000, v16
	v_mul_f32_e32 v17, 0x39800000, v17
	v_mul_f32_e32 v15, 0x39800000, v15
	v_cndmask_b32_e32 v10, v10, v11, vcc
	v_cndmask_b32_e32 v11, v18, v12, vcc
	v_sin_f32_e32 v12, v16
	v_cos_f32_e32 v16, v16
	v_sin_f32_e32 v18, v17
	v_cos_f32_e32 v17, v17
	v_mul_f32_e32 v3, 0x39800000, v3
	v_sin_f32_e32 v21, v15
	v_cos_f32_e32 v15, v15
	v_cndmask_b32_e32 v13, v19, v13, vcc
	v_sin_f32_e32 v19, v3
	v_cos_f32_e32 v3, v3
	v_mul_f32_e32 v10, 0x3b000000, v10
	v_mul_f32_e32 v11, 0x3b000000, v11
	v_cndmask_b32_e32 v14, v20, v14, vcc
	v_mul_f32_e32 v13, 0x3b000000, v13
	v_cvt_pk_bf16_f32 v10, v10, v11
	v_mul_f32_e32 v11, 0x3b000000, v14
	v_lshl_add_u64 v[8:9], v[8:9], 0, s[6:7]
	s_mov_b64 s[24:25], 0xfffff
	v_cndmask_b32_e32 v12, v12, v16, vcc
	v_cvt_pk_bf16_f32 v11, v13, v11
	v_cndmask_b32_e32 v13, v18, v17, vcc
	v_cmp_lt_u64_e64 s[38:39], s[24:25], v[8:9]
	v_cndmask_b32_e32 v14, v21, v15, vcc
	v_mul_f32_e32 v12, 0x3b000000, v12
	v_mul_f32_e32 v13, 0x3b000000, v13
	v_cndmask_b32_e32 v3, v19, v3, vcc
	v_add_u32_e32 v1, s2, v1
	s_or_b64 s[34:35], s[38:39], s[34:35]
	v_mul_f32_e32 v14, 0x3b000000, v14
	v_cvt_pk_bf16_f32 v12, v14, v12
	v_mul_f32_e32 v3, 0x3b000000, v3
	v_cvt_pk_bf16_f32 v13, v13, v3
	global_store_dwordx4 v[6:7], v[10:13], off sc1
	v_lshl_add_u64 v[6:7], v[6:7], 0, s[30:31]
	s_andn2_b64 exec, exec, s[34:35]
	s_cbranch_execnz .LBB0_624
